# T5: no VALU left in K-loop load segments (LDS read base in one VGPR + immediate offsets, last 64-bit adds to SALU) on top of v16
# baseline (speedup 1.0000x reference)
.LBB0_267:
	s_mov_b32 s49, s35
	s_add_i32 s35, s35, 1
	s_cmp_lt_u32 s35, s15
	s_mov_b64 s[30:31], s[28:29]
	s_mov_b32 s28, s48
	s_cselect_b64 s[54:55], -1, 0
	s_add_i32 s48, s35, s4
	s_mov_b64 s[52:53], s[6:7]
	s_and_b64 s[6:7], s[54:55], exec
	s_cselect_b32 s6, s48, s28
	s_cselect_b32 s28, s58, s58
	s_ashr_i32 s29, s28, 31
	s_lshl_b64 s[28:29], s[28:29], 19
	s_add_u32 s28, s60, s28
	s_addc_u32 s29, s33, s29
	s_and_b64 s[50:51], s[54:55], exec
	s_cselect_b32 s50, s29, s31
	s_cselect_b32 s51, s28, s30
	s_ashr_i32 s7, s6, 31
	s_lshl_b64 s[6:7], s[6:7], 19
	s_add_u32 s6, s86, s6
	s_addc_u32 s7, s87, s7
	s_and_b64 s[54:55], s[54:55], exec
	s_cselect_b32 s54, s7, s53
	s_cselect_b32 s55, s6, s52
	s_add_u32 s61, s52, 0x10000
	s_addc_u32 s66, s53, 0
	s_mov_b32 s67, -2
	v_add_u32_e32 v255, 0x10000, v1
	ds_read_b128 v[156:159], v255 offset:256
	ds_read_b128 v[162:165], v255 offset:1280
	ds_read_b128 v[166:169], v255 offset:2304
	ds_read_b128 v[170:173], v255 offset:3328
	ds_read_b128 v[174:177], v255 offset:16640
	ds_read_b128 v[178:181], v255 offset:17664
	ds_read_b128 v[182:185], v255 offset:18688
	ds_read_b128 v[192:195], v255 offset:19712
	s_add_u32 s52, s30, 0x10000
	s_addc_u32 s53, s31, 0
	s_cmp_eq_u32 s67, 12
	s_cselect_b32 s64, s51, s52
	s_cselect_b32 s65, s50, s53
	s_cselect_b32 s62, s55, s61
	s_cselect_b32 s63, s54, s66
	s_add_u32 s56, s64, 0x8000
	s_addc_u32 s57, s65, 0
	s_add_i32 m0, s36, 0xc000
	ds_read_b128 v[200:203], v155
	ds_read_b128 v[204:207], v155 offset:1024
	ds_read_b128 v[208:211], v155 offset:2048
	ds_read_b128 v[212:215], v155 offset:3072
	ds_read_b128 v[216:219], v155 offset:4096
	ds_read_b128 v[220:223], v155 offset:5120
	ds_read_b128 v[224:227], v155 offset:6144
	ds_read_b128 v[228:231], v155 offset:7168
	global_load_lds_dwordx4 v146, s[30:31] sc1
	s_add_i32 m0, s36, 0xe000
	s_nop 0
	global_load_lds_dwordx4 v148, s[30:31] sc1
	s_waitcnt vmcnt(8)
	s_waitcnt lgkmcnt(0)
	s_setprio 1
	s_barrier
	v_mfma_f32_16x16x32_bf16 v[118:121], v[156:159], v[200:203], 0
	v_mfma_f32_16x16x32_bf16 v[110:113], v[166:169], v[200:203], 0
	v_mfma_f32_16x16x32_bf16 v[102:105], v[156:159], v[208:211], 0
	v_mfma_f32_16x16x32_bf16 v[94:97], v[166:169], v[208:211], 0
	v_mfma_f32_16x16x32_bf16 v[86:89], v[156:159], v[216:219], 0
	v_mfma_f32_16x16x32_bf16 v[78:81], v[166:169], v[216:219], 0
	v_mfma_f32_16x16x32_bf16 v[62:65], v[156:159], v[224:227], 0
	v_mfma_f32_16x16x32_bf16 v[54:57], v[166:169], v[224:227], 0
	v_mfma_f32_16x16x32_bf16 v[118:121], v[162:165], v[204:207], v[118:121]
	v_mfma_f32_16x16x32_bf16 v[110:113], v[170:173], v[204:207], v[110:113]
	v_mfma_f32_16x16x32_bf16 v[102:105], v[162:165], v[212:215], v[102:105]
	v_mfma_f32_16x16x32_bf16 v[94:97], v[170:173], v[212:215], v[94:97]
	v_mfma_f32_16x16x32_bf16 v[86:89], v[162:165], v[220:223], v[86:89]
	v_mfma_f32_16x16x32_bf16 v[78:81], v[170:173], v[220:223], v[78:81]
	v_mfma_f32_16x16x32_bf16 v[62:65], v[162:165], v[228:231], v[62:65]
	v_mfma_f32_16x16x32_bf16 v[54:57], v[170:173], v[228:231], v[54:57]
	v_mfma_f32_16x16x32_bf16 v[126:129], v[174:177], v[200:203], 0
	v_mfma_f32_16x16x32_bf16 v[122:125], v[182:185], v[200:203], 0
	v_mfma_f32_16x16x32_bf16 v[114:117], v[174:177], v[208:211], 0
	v_mfma_f32_16x16x32_bf16 v[106:109], v[182:185], v[208:211], 0
	v_mfma_f32_16x16x32_bf16 v[98:101], v[174:177], v[216:219], 0
	v_mfma_f32_16x16x32_bf16 v[90:93], v[182:185], v[216:219], 0
	v_mfma_f32_16x16x32_bf16 v[82:85], v[174:177], v[224:227], 0
	v_mfma_f32_16x16x32_bf16 v[70:73], v[182:185], v[224:227], 0
	v_mfma_f32_16x16x32_bf16 v[126:129], v[178:181], v[204:207], v[126:129]
	v_mfma_f32_16x16x32_bf16 v[122:125], v[192:195], v[204:207], v[122:125]
	v_mfma_f32_16x16x32_bf16 v[114:117], v[178:181], v[212:215], v[114:117]
	v_mfma_f32_16x16x32_bf16 v[106:109], v[192:195], v[212:215], v[106:109]
	v_mfma_f32_16x16x32_bf16 v[98:101], v[178:181], v[220:223], v[98:101]
	v_mfma_f32_16x16x32_bf16 v[90:93], v[192:195], v[220:223], v[90:93]
	s_setprio 2
	s_barrier
	v_mfma_f32_16x16x32_bf16 v[82:85], v[178:181], v[228:231], v[82:85]
	v_mfma_f32_16x16x32_bf16 v[70:73], v[192:195], v[228:231], v[70:73]
	s_setprio 0
	s_add_i32 s30, s43, s5
	s_mov_b32 m0, s30
	ds_read_b128 v[200:203], v155 offset:16384
	ds_read_b128 v[204:207], v155 offset:17408
	ds_read_b128 v[208:211], v155 offset:18432
	ds_read_b128 v[212:215], v155 offset:19456
	ds_read_b128 v[216:219], v155 offset:20480
	ds_read_b128 v[220:223], v155 offset:21504
	ds_read_b128 v[224:227], v155 offset:22528
	ds_read_b128 v[228:231], v155 offset:23552
	global_load_lds_dwordx4 v134, s[62:63] sc1
	s_add_i32 m0, s30, 0x2000
	s_add_u32 s30, s62, 0x4000
	s_addc_u32 s31, s63, 0
	s_add_i32 s69, s44, s5
	global_load_lds_dwordx4 v136, s[62:63] sc1
	s_mov_b32 m0, s69
	s_nop 0
	global_load_lds_dwordx4 v134, s[30:31] sc1
	s_add_i32 m0, s69, 0x2000
	s_nop 0
	global_load_lds_dwordx4 v136, s[30:31] sc1
	s_mov_b32 m0, s36
	s_nop 0
	global_load_lds_dwordx4 v132, s[64:65] sc1
	s_mov_b32 m0, s37
	s_nop 0
	global_load_lds_dwordx4 v130, s[64:65] sc1
	s_waitcnt vmcnt(8)
	s_waitcnt lgkmcnt(0)
	s_setprio 1
	s_barrier
	v_mfma_f32_16x16x32_bf16 v[58:61], v[156:159], v[200:203], 0
	v_mfma_f32_16x16x32_bf16 v[46:49], v[166:169], v[200:203], 0
	v_mfma_f32_16x16x32_bf16 v[38:41], v[156:159], v[208:211], 0
	v_mfma_f32_16x16x32_bf16 v[30:33], v[166:169], v[208:211], 0
	v_mfma_f32_16x16x32_bf16 v[22:25], v[156:159], v[216:219], 0
	v_mfma_f32_16x16x32_bf16 v[14:17], v[166:169], v[216:219], 0
	v_mfma_f32_16x16x32_bf16 v[6:9], v[156:159], v[224:227], 0
	v_mfma_f32_16x16x32_bf16 v[2:5], v[166:169], v[224:227], 0
	v_mfma_f32_16x16x32_bf16 v[58:61], v[162:165], v[204:207], v[58:61]
	v_mfma_f32_16x16x32_bf16 v[46:49], v[170:173], v[204:207], v[46:49]
	v_mfma_f32_16x16x32_bf16 v[38:41], v[162:165], v[212:215], v[38:41]
	v_mfma_f32_16x16x32_bf16 v[30:33], v[170:173], v[212:215], v[30:33]
	v_mfma_f32_16x16x32_bf16 v[22:25], v[162:165], v[220:223], v[22:25]
	v_mfma_f32_16x16x32_bf16 v[14:17], v[170:173], v[220:223], v[14:17]
	v_mfma_f32_16x16x32_bf16 v[6:9], v[162:165], v[228:231], v[6:9]
	v_mfma_f32_16x16x32_bf16 v[2:5], v[170:173], v[228:231], v[2:5]
	v_mfma_f32_16x16x32_bf16 v[74:77], v[174:177], v[200:203], 0
	v_mfma_f32_16x16x32_bf16 v[66:69], v[182:185], v[200:203], 0
	v_mfma_f32_16x16x32_bf16 v[50:53], v[174:177], v[208:211], 0
	v_mfma_f32_16x16x32_bf16 v[42:45], v[182:185], v[208:211], 0
	v_mfma_f32_16x16x32_bf16 v[34:37], v[174:177], v[216:219], 0
	v_mfma_f32_16x16x32_bf16 v[26:29], v[182:185], v[216:219], 0
	v_mfma_f32_16x16x32_bf16 v[18:21], v[174:177], v[224:227], 0
	v_mfma_f32_16x16x32_bf16 v[10:13], v[182:185], v[224:227], 0
	v_mfma_f32_16x16x32_bf16 v[74:77], v[178:181], v[204:207], v[74:77]
	v_mfma_f32_16x16x32_bf16 v[66:69], v[192:195], v[204:207], v[66:69]
	v_mfma_f32_16x16x32_bf16 v[50:53], v[178:181], v[212:215], v[50:53]
	v_mfma_f32_16x16x32_bf16 v[42:45], v[192:195], v[212:215], v[42:45]
	v_mfma_f32_16x16x32_bf16 v[34:37], v[178:181], v[220:223], v[34:37]
	v_mfma_f32_16x16x32_bf16 v[26:29], v[192:195], v[220:223], v[26:29]
	s_setprio 2
	s_barrier
	v_mfma_f32_16x16x32_bf16 v[18:21], v[178:181], v[228:231], v[18:21]
	v_mfma_f32_16x16x32_bf16 v[10:13], v[192:195], v[228:231], v[10:13]
	s_setprio 0
	ds_read_b128 v[156:159], v255 offset:33024
	ds_read_b128 v[162:165], v255 offset:34048
	ds_read_b128 v[166:169], v255 offset:35072
	ds_read_b128 v[170:173], v255 offset:36096
	ds_read_b128 v[174:177], v255 offset:49408
	ds_read_b128 v[178:181], v255 offset:50432
	ds_read_b128 v[182:185], v255 offset:51456
	ds_read_b128 v[192:195], v255 offset:52480
	s_add_u32 s30, s64, 0x4000
	s_addc_u32 s31, s65, 0
	s_mov_b32 m0, s38
	ds_read_b128 v[200:203], v155 offset:32768
	ds_read_b128 v[204:207], v155 offset:33792
	ds_read_b128 v[208:211], v155 offset:34816
	ds_read_b128 v[212:215], v155 offset:35840
	ds_read_b128 v[216:219], v155 offset:36864
	ds_read_b128 v[220:223], v155 offset:37888
	ds_read_b128 v[224:227], v155 offset:38912
	ds_read_b128 v[228:231], v155 offset:39936
	global_load_lds_dwordx4 v132, s[30:31] sc1
	s_mov_b32 m0, s39
	s_nop 0
	global_load_lds_dwordx4 v130, s[30:31] sc1
	s_waitcnt vmcnt(8)
	s_waitcnt lgkmcnt(0)
	s_setprio 1
	s_barrier
	v_mfma_f32_16x16x32_bf16 v[118:121], v[156:159], v[200:203], v[118:121]
	v_mfma_f32_16x16x32_bf16 v[110:113], v[166:169], v[200:203], v[110:113]
	v_mfma_f32_16x16x32_bf16 v[102:105], v[156:159], v[208:211], v[102:105]
	v_mfma_f32_16x16x32_bf16 v[94:97], v[166:169], v[208:211], v[94:97]
	v_mfma_f32_16x16x32_bf16 v[86:89], v[156:159], v[216:219], v[86:89]
	v_mfma_f32_16x16x32_bf16 v[78:81], v[166:169], v[216:219], v[78:81]
	v_mfma_f32_16x16x32_bf16 v[62:65], v[156:159], v[224:227], v[62:65]
	v_mfma_f32_16x16x32_bf16 v[54:57], v[166:169], v[224:227], v[54:57]
	v_mfma_f32_16x16x32_bf16 v[118:121], v[162:165], v[204:207], v[118:121]
	v_mfma_f32_16x16x32_bf16 v[110:113], v[170:173], v[204:207], v[110:113]
	v_mfma_f32_16x16x32_bf16 v[102:105], v[162:165], v[212:215], v[102:105]
	v_mfma_f32_16x16x32_bf16 v[94:97], v[170:173], v[212:215], v[94:97]
	v_mfma_f32_16x16x32_bf16 v[86:89], v[162:165], v[220:223], v[86:89]
	v_mfma_f32_16x16x32_bf16 v[78:81], v[170:173], v[220:223], v[78:81]
	v_mfma_f32_16x16x32_bf16 v[62:65], v[162:165], v[228:231], v[62:65]
	v_mfma_f32_16x16x32_bf16 v[54:57], v[170:173], v[228:231], v[54:57]
	v_mfma_f32_16x16x32_bf16 v[126:129], v[174:177], v[200:203], v[126:129]
	v_mfma_f32_16x16x32_bf16 v[122:125], v[182:185], v[200:203], v[122:125]
	v_mfma_f32_16x16x32_bf16 v[114:117], v[174:177], v[208:211], v[114:117]
	v_mfma_f32_16x16x32_bf16 v[106:109], v[182:185], v[208:211], v[106:109]
	v_mfma_f32_16x16x32_bf16 v[98:101], v[174:177], v[216:219], v[98:101]
	v_mfma_f32_16x16x32_bf16 v[90:93], v[182:185], v[216:219], v[90:93]
	v_mfma_f32_16x16x32_bf16 v[82:85], v[174:177], v[224:227], v[82:85]
	v_mfma_f32_16x16x32_bf16 v[70:73], v[182:185], v[224:227], v[70:73]
	v_mfma_f32_16x16x32_bf16 v[126:129], v[178:181], v[204:207], v[126:129]
	v_mfma_f32_16x16x32_bf16 v[122:125], v[192:195], v[204:207], v[122:125]
	v_mfma_f32_16x16x32_bf16 v[114:117], v[178:181], v[212:215], v[114:117]
	v_mfma_f32_16x16x32_bf16 v[106:109], v[192:195], v[212:215], v[106:109]
	v_mfma_f32_16x16x32_bf16 v[98:101], v[178:181], v[220:223], v[98:101]
	v_mfma_f32_16x16x32_bf16 v[90:93], v[192:195], v[220:223], v[90:93]
	s_setprio 2
	s_barrier
	v_mfma_f32_16x16x32_bf16 v[82:85], v[178:181], v[228:231], v[82:85]
	v_mfma_f32_16x16x32_bf16 v[70:73], v[192:195], v[228:231], v[70:73]
	s_setprio 0
	s_add_u32 s30, s62, 0x8000
	s_addc_u32 s31, s63, 0
	s_add_i32 s64, s45, s5
	s_mov_b32 m0, s64
	ds_read_b128 v[200:203], v155 offset:49152
	ds_read_b128 v[204:207], v155 offset:50176
	ds_read_b128 v[208:211], v155 offset:51200
	ds_read_b128 v[212:215], v155 offset:52224
	ds_read_b128 v[216:219], v155 offset:53248
	ds_read_b128 v[220:223], v155 offset:54272
	ds_read_b128 v[224:227], v155 offset:55296
	ds_read_b128 v[228:231], v155 offset:56320
	global_load_lds_dwordx4 v134, s[30:31] sc1
	s_add_i32 m0, s64, 0x2000
	s_nop 0
	global_load_lds_dwordx4 v136, s[30:31] sc1
	s_add_u32 s30, s62, 0xc000
	s_addc_u32 s31, s63, 0
	s_add_i32 s62, s46, s5
	s_mov_b32 m0, s62
	s_nop 0
	global_load_lds_dwordx4 v134, s[30:31] sc1
	s_add_i32 m0, s62, 0x2000
	s_nop 0
	global_load_lds_dwordx4 v136, s[30:31] sc1
	s_mov_b32 m0, s40
	s_nop 0
	global_load_lds_dwordx4 v132, s[56:57] sc1
	s_mov_b32 m0, s41
	s_nop 0
	global_load_lds_dwordx4 v130, s[56:57] sc1
	s_waitcnt vmcnt(8)
	s_waitcnt lgkmcnt(0)
	s_setprio 1
	s_barrier
	v_mfma_f32_16x16x32_bf16 v[58:61], v[156:159], v[200:203], v[58:61]
	v_mfma_f32_16x16x32_bf16 v[46:49], v[166:169], v[200:203], v[46:49]
	v_mfma_f32_16x16x32_bf16 v[38:41], v[156:159], v[208:211], v[38:41]
	v_mfma_f32_16x16x32_bf16 v[30:33], v[166:169], v[208:211], v[30:33]
	v_mfma_f32_16x16x32_bf16 v[22:25], v[156:159], v[216:219], v[22:25]
	v_mfma_f32_16x16x32_bf16 v[14:17], v[166:169], v[216:219], v[14:17]
	v_mfma_f32_16x16x32_bf16 v[6:9], v[156:159], v[224:227], v[6:9]
	v_mfma_f32_16x16x32_bf16 v[2:5], v[166:169], v[224:227], v[2:5]
	v_mfma_f32_16x16x32_bf16 v[58:61], v[162:165], v[204:207], v[58:61]
	v_mfma_f32_16x16x32_bf16 v[46:49], v[170:173], v[204:207], v[46:49]
	v_mfma_f32_16x16x32_bf16 v[38:41], v[162:165], v[212:215], v[38:41]
	v_mfma_f32_16x16x32_bf16 v[30:33], v[170:173], v[212:215], v[30:33]
	v_mfma_f32_16x16x32_bf16 v[22:25], v[162:165], v[220:223], v[22:25]
	v_mfma_f32_16x16x32_bf16 v[14:17], v[170:173], v[220:223], v[14:17]
	v_mfma_f32_16x16x32_bf16 v[6:9], v[162:165], v[228:231], v[6:9]
	v_mfma_f32_16x16x32_bf16 v[2:5], v[170:173], v[228:231], v[2:5]
	v_mfma_f32_16x16x32_bf16 v[74:77], v[174:177], v[200:203], v[74:77]
	v_mfma_f32_16x16x32_bf16 v[66:69], v[182:185], v[200:203], v[66:69]
	v_mfma_f32_16x16x32_bf16 v[50:53], v[174:177], v[208:211], v[50:53]
	v_mfma_f32_16x16x32_bf16 v[42:45], v[182:185], v[208:211], v[42:45]
	v_mfma_f32_16x16x32_bf16 v[34:37], v[174:177], v[216:219], v[34:37]
	v_mfma_f32_16x16x32_bf16 v[26:29], v[182:185], v[216:219], v[26:29]
	v_mfma_f32_16x16x32_bf16 v[18:21], v[174:177], v[224:227], v[18:21]
	v_mfma_f32_16x16x32_bf16 v[10:13], v[182:185], v[224:227], v[10:13]
	v_mfma_f32_16x16x32_bf16 v[74:77], v[178:181], v[204:207], v[74:77]
	v_mfma_f32_16x16x32_bf16 v[66:69], v[192:195], v[204:207], v[66:69]
	v_mfma_f32_16x16x32_bf16 v[50:53], v[178:181], v[212:215], v[50:53]
	v_mfma_f32_16x16x32_bf16 v[42:45], v[192:195], v[212:215], v[42:45]
	v_mfma_f32_16x16x32_bf16 v[34:37], v[178:181], v[220:223], v[34:37]
	v_mfma_f32_16x16x32_bf16 v[26:29], v[192:195], v[220:223], v[26:29]
	s_setprio 2
	s_barrier
	v_mfma_f32_16x16x32_bf16 v[18:21], v[178:181], v[228:231], v[18:21]
	v_mfma_f32_16x16x32_bf16 v[10:13], v[192:195], v[228:231], v[10:13]
	s_setprio 0
	s_add_i32 s67, s67, 2
	s_add_u32 s61, s61, 0x10000
	s_addc_u32 s66, s66, 0
	s_cmp_gt_u32 s67, 13
	s_mov_b64 s[30:31], s[52:53]
.LBB0_268:
	ds_read_b128 v[156:159], v255 offset:256
	ds_read_b128 v[162:165], v255 offset:1280
	ds_read_b128 v[166:169], v255 offset:2304
	ds_read_b128 v[170:173], v255 offset:3328
	ds_read_b128 v[174:177], v255 offset:16640
	ds_read_b128 v[178:181], v255 offset:17664
	ds_read_b128 v[182:185], v255 offset:18688
	ds_read_b128 v[192:195], v255 offset:19712
	s_add_u32 s52, s30, 0x10000
	s_addc_u32 s53, s31, 0
	s_cmp_eq_u32 s67, 12
	s_cselect_b32 s64, s51, s52
	s_cselect_b32 s65, s50, s53
	s_cselect_b32 s62, s55, s61
	s_cselect_b32 s63, s54, s66
	s_add_u32 s56, s64, 0x8000
	s_addc_u32 s57, s65, 0
	s_add_i32 m0, s36, 0xc000
	ds_read_b128 v[200:203], v155
	ds_read_b128 v[204:207], v155 offset:1024
	ds_read_b128 v[208:211], v155 offset:2048
	ds_read_b128 v[212:215], v155 offset:3072
	ds_read_b128 v[216:219], v155 offset:4096
	ds_read_b128 v[220:223], v155 offset:5120
	ds_read_b128 v[224:227], v155 offset:6144
	ds_read_b128 v[228:231], v155 offset:7168
	global_load_lds_dwordx4 v146, s[30:31] sc1
	s_add_i32 m0, s36, 0xe000
	s_nop 0
	global_load_lds_dwordx4 v148, s[30:31] sc1
	s_waitcnt vmcnt(8)
	s_waitcnt lgkmcnt(0)
	s_setprio 1
	s_barrier
	v_mfma_f32_16x16x32_bf16 v[118:121], v[156:159], v[200:203], v[118:121]
	v_mfma_f32_16x16x32_bf16 v[110:113], v[166:169], v[200:203], v[110:113]
	v_mfma_f32_16x16x32_bf16 v[102:105], v[156:159], v[208:211], v[102:105]
	v_mfma_f32_16x16x32_bf16 v[94:97], v[166:169], v[208:211], v[94:97]
	v_mfma_f32_16x16x32_bf16 v[86:89], v[156:159], v[216:219], v[86:89]
	v_mfma_f32_16x16x32_bf16 v[78:81], v[166:169], v[216:219], v[78:81]
	v_mfma_f32_16x16x32_bf16 v[62:65], v[156:159], v[224:227], v[62:65]
	v_mfma_f32_16x16x32_bf16 v[54:57], v[166:169], v[224:227], v[54:57]
	v_mfma_f32_16x16x32_bf16 v[118:121], v[162:165], v[204:207], v[118:121]
	v_mfma_f32_16x16x32_bf16 v[110:113], v[170:173], v[204:207], v[110:113]
	v_mfma_f32_16x16x32_bf16 v[102:105], v[162:165], v[212:215], v[102:105]
	v_mfma_f32_16x16x32_bf16 v[94:97], v[170:173], v[212:215], v[94:97]
	v_mfma_f32_16x16x32_bf16 v[86:89], v[162:165], v[220:223], v[86:89]
	v_mfma_f32_16x16x32_bf16 v[78:81], v[170:173], v[220:223], v[78:81]
	v_mfma_f32_16x16x32_bf16 v[62:65], v[162:165], v[228:231], v[62:65]
	v_mfma_f32_16x16x32_bf16 v[54:57], v[170:173], v[228:231], v[54:57]
	v_mfma_f32_16x16x32_bf16 v[126:129], v[174:177], v[200:203], v[126:129]
	v_mfma_f32_16x16x32_bf16 v[122:125], v[182:185], v[200:203], v[122:125]
	v_mfma_f32_16x16x32_bf16 v[114:117], v[174:177], v[208:211], v[114:117]
	v_mfma_f32_16x16x32_bf16 v[106:109], v[182:185], v[208:211], v[106:109]
	v_mfma_f32_16x16x32_bf16 v[98:101], v[174:177], v[216:219], v[98:101]
	v_mfma_f32_16x16x32_bf16 v[90:93], v[182:185], v[216:219], v[90:93]
	v_mfma_f32_16x16x32_bf16 v[82:85], v[174:177], v[224:227], v[82:85]
	v_mfma_f32_16x16x32_bf16 v[70:73], v[182:185], v[224:227], v[70:73]
	v_mfma_f32_16x16x32_bf16 v[126:129], v[178:181], v[204:207], v[126:129]
	v_mfma_f32_16x16x32_bf16 v[122:125], v[192:195], v[204:207], v[122:125]
	v_mfma_f32_16x16x32_bf16 v[114:117], v[178:181], v[212:215], v[114:117]
	v_mfma_f32_16x16x32_bf16 v[106:109], v[192:195], v[212:215], v[106:109]
	v_mfma_f32_16x16x32_bf16 v[98:101], v[178:181], v[220:223], v[98:101]
	v_mfma_f32_16x16x32_bf16 v[90:93], v[192:195], v[220:223], v[90:93]
	s_setprio 2
	s_barrier
	v_mfma_f32_16x16x32_bf16 v[82:85], v[178:181], v[228:231], v[82:85]
	v_mfma_f32_16x16x32_bf16 v[70:73], v[192:195], v[228:231], v[70:73]
	s_setprio 0
	s_add_i32 s30, s43, s5
	s_mov_b32 m0, s30
	ds_read_b128 v[200:203], v155 offset:16384
	ds_read_b128 v[204:207], v155 offset:17408
	ds_read_b128 v[208:211], v155 offset:18432
	ds_read_b128 v[212:215], v155 offset:19456
	ds_read_b128 v[216:219], v155 offset:20480
	ds_read_b128 v[220:223], v155 offset:21504
	ds_read_b128 v[224:227], v155 offset:22528
	ds_read_b128 v[228:231], v155 offset:23552
	global_load_lds_dwordx4 v134, s[62:63] sc1
	s_add_i32 m0, s30, 0x2000
	s_add_u32 s30, s62, 0x4000
	s_addc_u32 s31, s63, 0
	s_add_i32 s69, s44, s5
	global_load_lds_dwordx4 v136, s[62:63] sc1
	s_mov_b32 m0, s69
	s_nop 0
	global_load_lds_dwordx4 v134, s[30:31] sc1
	s_add_i32 m0, s69, 0x2000
	s_nop 0
	global_load_lds_dwordx4 v136, s[30:31] sc1
	s_mov_b32 m0, s36
	s_nop 0
	global_load_lds_dwordx4 v132, s[64:65] sc1
	s_mov_b32 m0, s37
	s_nop 0
	global_load_lds_dwordx4 v130, s[64:65] sc1
	s_waitcnt vmcnt(8)
	s_waitcnt lgkmcnt(0)
	s_setprio 1
	s_barrier
	v_mfma_f32_16x16x32_bf16 v[58:61], v[156:159], v[200:203], v[58:61]
	v_mfma_f32_16x16x32_bf16 v[46:49], v[166:169], v[200:203], v[46:49]
	v_mfma_f32_16x16x32_bf16 v[38:41], v[156:159], v[208:211], v[38:41]
	v_mfma_f32_16x16x32_bf16 v[30:33], v[166:169], v[208:211], v[30:33]
	v_mfma_f32_16x16x32_bf16 v[22:25], v[156:159], v[216:219], v[22:25]
	v_mfma_f32_16x16x32_bf16 v[14:17], v[166:169], v[216:219], v[14:17]
	v_mfma_f32_16x16x32_bf16 v[6:9], v[156:159], v[224:227], v[6:9]
	v_mfma_f32_16x16x32_bf16 v[2:5], v[166:169], v[224:227], v[2:5]
	v_mfma_f32_16x16x32_bf16 v[58:61], v[162:165], v[204:207], v[58:61]
	v_mfma_f32_16x16x32_bf16 v[46:49], v[170:173], v[204:207], v[46:49]
	v_mfma_f32_16x16x32_bf16 v[38:41], v[162:165], v[212:215], v[38:41]
	v_mfma_f32_16x16x32_bf16 v[30:33], v[170:173], v[212:215], v[30:33]
	v_mfma_f32_16x16x32_bf16 v[22:25], v[162:165], v[220:223], v[22:25]
	v_mfma_f32_16x16x32_bf16 v[14:17], v[170:173], v[220:223], v[14:17]
	v_mfma_f32_16x16x32_bf16 v[6:9], v[162:165], v[228:231], v[6:9]
	v_mfma_f32_16x16x32_bf16 v[2:5], v[170:173], v[228:231], v[2:5]
	v_mfma_f32_16x16x32_bf16 v[74:77], v[174:177], v[200:203], v[74:77]
	v_mfma_f32_16x16x32_bf16 v[66:69], v[182:185], v[200:203], v[66:69]
	v_mfma_f32_16x16x32_bf16 v[50:53], v[174:177], v[208:211], v[50:53]
	v_mfma_f32_16x16x32_bf16 v[42:45], v[182:185], v[208:211], v[42:45]
	v_mfma_f32_16x16x32_bf16 v[34:37], v[174:177], v[216:219], v[34:37]
	v_mfma_f32_16x16x32_bf16 v[26:29], v[182:185], v[216:219], v[26:29]
	v_mfma_f32_16x16x32_bf16 v[18:21], v[174:177], v[224:227], v[18:21]
	v_mfma_f32_16x16x32_bf16 v[10:13], v[182:185], v[224:227], v[10:13]
	v_mfma_f32_16x16x32_bf16 v[74:77], v[178:181], v[204:207], v[74:77]
	v_mfma_f32_16x16x32_bf16 v[66:69], v[192:195], v[204:207], v[66:69]
	v_mfma_f32_16x16x32_bf16 v[50:53], v[178:181], v[212:215], v[50:53]
	v_mfma_f32_16x16x32_bf16 v[42:45], v[192:195], v[212:215], v[42:45]
	v_mfma_f32_16x16x32_bf16 v[34:37], v[178:181], v[220:223], v[34:37]
	v_mfma_f32_16x16x32_bf16 v[26:29], v[192:195], v[220:223], v[26:29]
	s_setprio 2
	s_barrier
	v_mfma_f32_16x16x32_bf16 v[18:21], v[178:181], v[228:231], v[18:21]
	v_mfma_f32_16x16x32_bf16 v[10:13], v[192:195], v[228:231], v[10:13]
	s_setprio 0
	ds_read_b128 v[156:159], v255 offset:33024
	ds_read_b128 v[162:165], v255 offset:34048
	ds_read_b128 v[166:169], v255 offset:35072
	ds_read_b128 v[170:173], v255 offset:36096
	ds_read_b128 v[174:177], v255 offset:49408
	ds_read_b128 v[178:181], v255 offset:50432
	ds_read_b128 v[182:185], v255 offset:51456
	ds_read_b128 v[192:195], v255 offset:52480
	s_add_u32 s30, s64, 0x4000
	s_addc_u32 s31, s65, 0
	s_mov_b32 m0, s38
	ds_read_b128 v[200:203], v155 offset:32768
	ds_read_b128 v[204:207], v155 offset:33792
	ds_read_b128 v[208:211], v155 offset:34816
	ds_read_b128 v[212:215], v155 offset:35840
	ds_read_b128 v[216:219], v155 offset:36864
	ds_read_b128 v[220:223], v155 offset:37888
	ds_read_b128 v[224:227], v155 offset:38912
	ds_read_b128 v[228:231], v155 offset:39936
	global_load_lds_dwordx4 v132, s[30:31] sc1
	s_mov_b32 m0, s39
	s_nop 0
	global_load_lds_dwordx4 v130, s[30:31] sc1
	s_waitcnt vmcnt(8)
	s_waitcnt lgkmcnt(0)
	s_setprio 1
	s_barrier
	v_mfma_f32_16x16x32_bf16 v[118:121], v[156:159], v[200:203], v[118:121]
	v_mfma_f32_16x16x32_bf16 v[110:113], v[166:169], v[200:203], v[110:113]
	v_mfma_f32_16x16x32_bf16 v[102:105], v[156:159], v[208:211], v[102:105]
	v_mfma_f32_16x16x32_bf16 v[94:97], v[166:169], v[208:211], v[94:97]
	v_mfma_f32_16x16x32_bf16 v[86:89], v[156:159], v[216:219], v[86:89]
	v_mfma_f32_16x16x32_bf16 v[78:81], v[166:169], v[216:219], v[78:81]
	v_mfma_f32_16x16x32_bf16 v[62:65], v[156:159], v[224:227], v[62:65]
	v_mfma_f32_16x16x32_bf16 v[54:57], v[166:169], v[224:227], v[54:57]
	v_mfma_f32_16x16x32_bf16 v[118:121], v[162:165], v[204:207], v[118:121]
	v_mfma_f32_16x16x32_bf16 v[110:113], v[170:173], v[204:207], v[110:113]
	v_mfma_f32_16x16x32_bf16 v[102:105], v[162:165], v[212:215], v[102:105]
	v_mfma_f32_16x16x32_bf16 v[94:97], v[170:173], v[212:215], v[94:97]
	v_mfma_f32_16x16x32_bf16 v[86:89], v[162:165], v[220:223], v[86:89]
	v_mfma_f32_16x16x32_bf16 v[78:81], v[170:173], v[220:223], v[78:81]
	v_mfma_f32_16x16x32_bf16 v[62:65], v[162:165], v[228:231], v[62:65]
	v_mfma_f32_16x16x32_bf16 v[54:57], v[170:173], v[228:231], v[54:57]
	v_mfma_f32_16x16x32_bf16 v[126:129], v[174:177], v[200:203], v[126:129]
	v_mfma_f32_16x16x32_bf16 v[122:125], v[182:185], v[200:203], v[122:125]
	v_mfma_f32_16x16x32_bf16 v[114:117], v[174:177], v[208:211], v[114:117]
	v_mfma_f32_16x16x32_bf16 v[106:109], v[182:185], v[208:211], v[106:109]
	v_mfma_f32_16x16x32_bf16 v[98:101], v[174:177], v[216:219], v[98:101]
	v_mfma_f32_16x16x32_bf16 v[90:93], v[182:185], v[216:219], v[90:93]
	v_mfma_f32_16x16x32_bf16 v[82:85], v[174:177], v[224:227], v[82:85]
	v_mfma_f32_16x16x32_bf16 v[70:73], v[182:185], v[224:227], v[70:73]
	v_mfma_f32_16x16x32_bf16 v[126:129], v[178:181], v[204:207], v[126:129]
	v_mfma_f32_16x16x32_bf16 v[122:125], v[192:195], v[204:207], v[122:125]
	v_mfma_f32_16x16x32_bf16 v[114:117], v[178:181], v[212:215], v[114:117]
	v_mfma_f32_16x16x32_bf16 v[106:109], v[192:195], v[212:215], v[106:109]
	v_mfma_f32_16x16x32_bf16 v[98:101], v[178:181], v[220:223], v[98:101]
	v_mfma_f32_16x16x32_bf16 v[90:93], v[192:195], v[220:223], v[90:93]
	s_setprio 2
	s_barrier
	v_mfma_f32_16x16x32_bf16 v[82:85], v[178:181], v[228:231], v[82:85]
	v_mfma_f32_16x16x32_bf16 v[70:73], v[192:195], v[228:231], v[70:73]
	s_setprio 0
	s_add_u32 s30, s62, 0x8000
	s_addc_u32 s31, s63, 0
	s_add_i32 s64, s45, s5
	s_mov_b32 m0, s64
	ds_read_b128 v[200:203], v155 offset:49152
	ds_read_b128 v[204:207], v155 offset:50176
	ds_read_b128 v[208:211], v155 offset:51200
	ds_read_b128 v[212:215], v155 offset:52224
	ds_read_b128 v[216:219], v155 offset:53248
	ds_read_b128 v[220:223], v155 offset:54272
	ds_read_b128 v[224:227], v155 offset:55296
	ds_read_b128 v[228:231], v155 offset:56320
	global_load_lds_dwordx4 v134, s[30:31] sc1
	s_add_i32 m0, s64, 0x2000
	s_nop 0
	global_load_lds_dwordx4 v136, s[30:31] sc1
	s_add_u32 s30, s62, 0xc000
	s_addc_u32 s31, s63, 0
	s_add_i32 s62, s46, s5
	s_mov_b32 m0, s62
	s_nop 0
	global_load_lds_dwordx4 v134, s[30:31] sc1
	s_add_i32 m0, s62, 0x2000
	s_nop 0
	global_load_lds_dwordx4 v136, s[30:31] sc1
	s_mov_b32 m0, s40
	s_nop 0
	global_load_lds_dwordx4 v132, s[56:57] sc1
	s_mov_b32 m0, s41
	s_nop 0
	global_load_lds_dwordx4 v130, s[56:57] sc1
	s_waitcnt vmcnt(8)
	s_waitcnt lgkmcnt(0)
	s_setprio 1
	s_barrier
	v_mfma_f32_16x16x32_bf16 v[58:61], v[156:159], v[200:203], v[58:61]
	v_mfma_f32_16x16x32_bf16 v[46:49], v[166:169], v[200:203], v[46:49]
	v_mfma_f32_16x16x32_bf16 v[38:41], v[156:159], v[208:211], v[38:41]
	v_mfma_f32_16x16x32_bf16 v[30:33], v[166:169], v[208:211], v[30:33]
	v_mfma_f32_16x16x32_bf16 v[22:25], v[156:159], v[216:219], v[22:25]
	v_mfma_f32_16x16x32_bf16 v[14:17], v[166:169], v[216:219], v[14:17]
	v_mfma_f32_16x16x32_bf16 v[6:9], v[156:159], v[224:227], v[6:9]
	v_mfma_f32_16x16x32_bf16 v[2:5], v[166:169], v[224:227], v[2:5]
	v_mfma_f32_16x16x32_bf16 v[58:61], v[162:165], v[204:207], v[58:61]
	v_mfma_f32_16x16x32_bf16 v[46:49], v[170:173], v[204:207], v[46:49]
	v_mfma_f32_16x16x32_bf16 v[38:41], v[162:165], v[212:215], v[38:41]
	v_mfma_f32_16x16x32_bf16 v[30:33], v[170:173], v[212:215], v[30:33]
	v_mfma_f32_16x16x32_bf16 v[22:25], v[162:165], v[220:223], v[22:25]
	v_mfma_f32_16x16x32_bf16 v[14:17], v[170:173], v[220:223], v[14:17]
	v_mfma_f32_16x16x32_bf16 v[6:9], v[162:165], v[228:231], v[6:9]
	v_mfma_f32_16x16x32_bf16 v[2:5], v[170:173], v[228:231], v[2:5]
	v_mfma_f32_16x16x32_bf16 v[74:77], v[174:177], v[200:203], v[74:77]
	v_mfma_f32_16x16x32_bf16 v[66:69], v[182:185], v[200:203], v[66:69]
	v_mfma_f32_16x16x32_bf16 v[50:53], v[174:177], v[208:211], v[50:53]
	v_mfma_f32_16x16x32_bf16 v[42:45], v[182:185], v[208:211], v[42:45]
	v_mfma_f32_16x16x32_bf16 v[34:37], v[174:177], v[216:219], v[34:37]
	v_mfma_f32_16x16x32_bf16 v[26:29], v[182:185], v[216:219], v[26:29]
	v_mfma_f32_16x16x32_bf16 v[18:21], v[174:177], v[224:227], v[18:21]
	v_mfma_f32_16x16x32_bf16 v[10:13], v[182:185], v[224:227], v[10:13]
	v_mfma_f32_16x16x32_bf16 v[74:77], v[178:181], v[204:207], v[74:77]
	v_mfma_f32_16x16x32_bf16 v[66:69], v[192:195], v[204:207], v[66:69]
	v_mfma_f32_16x16x32_bf16 v[50:53], v[178:181], v[212:215], v[50:53]
	v_mfma_f32_16x16x32_bf16 v[42:45], v[192:195], v[212:215], v[42:45]
	v_mfma_f32_16x16x32_bf16 v[34:37], v[178:181], v[220:223], v[34:37]
	v_mfma_f32_16x16x32_bf16 v[26:29], v[192:195], v[220:223], v[26:29]
	s_setprio 2
	s_barrier
	v_mfma_f32_16x16x32_bf16 v[18:21], v[178:181], v[228:231], v[18:21]
	v_mfma_f32_16x16x32_bf16 v[10:13], v[192:195], v[228:231], v[10:13]
	s_setprio 0
	s_add_i32 s67, s67, 2
	s_add_u32 s61, s61, 0x10000
	s_addc_u32 s66, s66, 0
	s_cmp_gt_u32 s67, 13
	s_mov_b64 s[30:31], s[52:53]
	s_cbranch_scc0 .LBB0_268
	s_and_b64 vcc, exec, s[10:11]
	s_cbranch_vccz .LBB0_271
	s_barrier

.LBB0_403:
	s_add_u32 s61, s62, 0x10000
	s_addc_u32 s69, s63, 0
	s_lshl_b32 s62, s10, 2
	s_ashr_i32 s29, s28, 31
	s_ashr_i32 s63, s62, 31
	s_lshl_b64 s[64:65], s[28:29], 19
	s_lshl_b64 s[62:63], s[62:63], 15
	s_add_u32 s29, s60, s62
	s_addc_u32 s55, s33, s63
	s_add_u32 s29, s29, s64
	s_addc_u32 s55, s55, s65
	s_add_u32 s62, s29, 0x10000
	s_addc_u32 s63, s55, 0
	s_and_b64 s[8:9], s[8:9], exec
	s_cselect_b32 s70, s57, s63
	s_cselect_b32 s71, s56, s62
	s_cselect_b32 s78, s53, s55
	s_cselect_b32 s79, s52, s29
	v_lshl_add_u64 v[146:147], s[30:31], 0, v[138:139]
	v_lshl_add_u64 v[148:149], s[30:31], 0, v[140:141]
	s_mov_b32 s80, -2
	s_mov_b64 s[8:9], 0
	v_add_u32_e32 v255, 0x10000, v153
	s_add_u32 s29, s30, s8
	s_addc_u32 s55, s31, s9
	ds_read_b128 v[162:165], v255 offset:256
	ds_read_b128 v[166:169], v255 offset:1280
	ds_read_b128 v[170:173], v255 offset:2304
	ds_read_b128 v[174:177], v255 offset:3328
	s_add_u32 s29, s29, 0x10000
	ds_read_b128 v[178:181], v255 offset:16640
	ds_read_b128 v[182:185], v255 offset:17664
	ds_read_b128 v[192:195], v255 offset:18688
	ds_read_b128 v[200:203], v255 offset:19712
	s_addc_u32 s55, s55, 0
	s_add_u32 s62, s61, s8
	s_addc_u32 s63, s69, s9
	s_cmp_eq_u32 s8, 0x150000
	s_cselect_b32 s66, s71, s29
	s_cselect_b32 s67, s70, s55
	s_cselect_b32 s64, s79, s62
	s_cselect_b32 s65, s78, s63
	s_add_u32 s62, s66, 0x8000
	s_addc_u32 s63, s67, 0
	s_add_i32 s29, s37, 0xc000
	s_add_u32 s98, s30, s8
	s_addc_u32 s99, s31, s9
	s_mov_b32 m0, s29
	s_add_i32 s55, s37, 0xe000
	ds_read_b128 v[204:207], v155
	ds_read_b128 v[208:211], v155 offset:1024
	ds_read_b128 v[212:215], v155 offset:2048
	ds_read_b128 v[216:219], v155 offset:3072
	ds_read_b128 v[220:223], v155 offset:4096
	ds_read_b128 v[224:227], v155 offset:5120
	ds_read_b128 v[228:231], v155 offset:6144
	ds_read_b128 v[232:235], v155 offset:7168
	global_load_lds_dwordx4 v138, s[98:99] sc1
	s_mov_b32 m0, s55
	s_nop 0
	global_load_lds_dwordx4 v140, s[98:99] sc1
	s_waitcnt vmcnt(8)
	s_waitcnt lgkmcnt(0)
	s_setprio 1
	s_barrier
	v_mfma_f32_16x16x32_bf16 v[114:117], v[162:165], v[204:207], 0
	v_mfma_f32_16x16x32_bf16 v[118:121], v[170:173], v[204:207], 0
	v_mfma_f32_16x16x32_bf16 v[98:101], v[162:165], v[212:215], 0
	v_mfma_f32_16x16x32_bf16 v[102:105], v[170:173], v[212:215], 0
	v_mfma_f32_16x16x32_bf16 v[82:85], v[162:165], v[220:223], 0
	v_mfma_f32_16x16x32_bf16 v[86:89], v[170:173], v[220:223], 0
	v_mfma_f32_16x16x32_bf16 v[66:69], v[162:165], v[228:231], 0
	v_mfma_f32_16x16x32_bf16 v[70:73], v[170:173], v[228:231], 0
	v_mfma_f32_16x16x32_bf16 v[114:117], v[166:169], v[208:211], v[114:117]
	v_mfma_f32_16x16x32_bf16 v[118:121], v[174:177], v[208:211], v[118:121]
	v_mfma_f32_16x16x32_bf16 v[98:101], v[166:169], v[216:219], v[98:101]
	v_mfma_f32_16x16x32_bf16 v[102:105], v[174:177], v[216:219], v[102:105]
	v_mfma_f32_16x16x32_bf16 v[82:85], v[166:169], v[224:227], v[82:85]
	v_mfma_f32_16x16x32_bf16 v[86:89], v[174:177], v[224:227], v[86:89]
	v_mfma_f32_16x16x32_bf16 v[66:69], v[166:169], v[232:235], v[66:69]
	v_mfma_f32_16x16x32_bf16 v[70:73], v[174:177], v[232:235], v[70:73]
	v_mfma_f32_16x16x32_bf16 v[122:125], v[178:181], v[204:207], 0
	v_mfma_f32_16x16x32_bf16 v[126:129], v[192:195], v[204:207], 0
	v_mfma_f32_16x16x32_bf16 v[106:109], v[178:181], v[212:215], 0
	v_mfma_f32_16x16x32_bf16 v[110:113], v[192:195], v[212:215], 0
	v_mfma_f32_16x16x32_bf16 v[90:93], v[178:181], v[220:223], 0
	v_mfma_f32_16x16x32_bf16 v[94:97], v[192:195], v[220:223], 0
	v_mfma_f32_16x16x32_bf16 v[74:77], v[178:181], v[228:231], 0
	v_mfma_f32_16x16x32_bf16 v[78:81], v[192:195], v[228:231], 0
	v_mfma_f32_16x16x32_bf16 v[122:125], v[182:185], v[208:211], v[122:125]
	v_mfma_f32_16x16x32_bf16 v[126:129], v[200:203], v[208:211], v[126:129]
	v_mfma_f32_16x16x32_bf16 v[106:109], v[182:185], v[216:219], v[106:109]
	v_mfma_f32_16x16x32_bf16 v[110:113], v[200:203], v[216:219], v[110:113]
	v_mfma_f32_16x16x32_bf16 v[90:93], v[182:185], v[224:227], v[90:93]
	v_mfma_f32_16x16x32_bf16 v[94:97], v[200:203], v[224:227], v[94:97]
	s_setprio 2
	s_barrier
	v_mfma_f32_16x16x32_bf16 v[74:77], v[182:185], v[232:235], v[74:77]
	v_mfma_f32_16x16x32_bf16 v[78:81], v[200:203], v[232:235], v[78:81]
	s_setprio 0
	s_add_i32 s81, s45, s35
	s_mov_b32 m0, s81
	ds_read_b128 v[204:207], v155 offset:16384
	ds_read_b128 v[208:211], v155 offset:17408
	ds_read_b128 v[212:215], v155 offset:18432
	ds_read_b128 v[216:219], v155 offset:19456
	ds_read_b128 v[220:223], v155 offset:20480
	ds_read_b128 v[224:227], v155 offset:21504
	ds_read_b128 v[228:231], v155 offset:22528
	ds_read_b128 v[232:235], v155 offset:23552
	global_load_lds_dwordx4 v132, s[64:65] sc1
	s_add_i32 m0, s81, 0x2000
	s_add_u32 s82, s64, 0x4000
	s_addc_u32 s83, s65, 0
	s_add_i32 s81, s47, s35
	global_load_lds_dwordx4 v136, s[64:65] sc1
	s_mov_b32 m0, s81
	s_nop 0
	global_load_lds_dwordx4 v132, s[82:83] sc1
	s_add_i32 m0, s81, 0x2000
	s_nop 0
	global_load_lds_dwordx4 v136, s[82:83] sc1
	s_mov_b32 m0, s37
	s_nop 0
	global_load_lds_dwordx4 v130, s[66:67] sc1
	s_mov_b32 m0, s39
	s_nop 0
	global_load_lds_dwordx4 v134, s[66:67] sc1
	s_waitcnt vmcnt(8)
	s_waitcnt lgkmcnt(0)
	s_setprio 1
	s_barrier
	v_mfma_f32_16x16x32_bf16 v[50:53], v[162:165], v[204:207], 0
	v_mfma_f32_16x16x32_bf16 v[54:57], v[170:173], v[204:207], 0
	v_mfma_f32_16x16x32_bf16 v[34:37], v[162:165], v[212:215], 0
	v_mfma_f32_16x16x32_bf16 v[38:41], v[170:173], v[212:215], 0
	v_mfma_f32_16x16x32_bf16 v[18:21], v[162:165], v[220:223], 0
	v_mfma_f32_16x16x32_bf16 v[22:25], v[170:173], v[220:223], 0
	v_mfma_f32_16x16x32_bf16 v[2:5], v[162:165], v[228:231], 0
	v_mfma_f32_16x16x32_bf16 v[6:9], v[170:173], v[228:231], 0
	v_mfma_f32_16x16x32_bf16 v[50:53], v[166:169], v[208:211], v[50:53]
	v_mfma_f32_16x16x32_bf16 v[54:57], v[174:177], v[208:211], v[54:57]
	v_mfma_f32_16x16x32_bf16 v[34:37], v[166:169], v[216:219], v[34:37]
	v_mfma_f32_16x16x32_bf16 v[38:41], v[174:177], v[216:219], v[38:41]
	v_mfma_f32_16x16x32_bf16 v[18:21], v[166:169], v[224:227], v[18:21]
	v_mfma_f32_16x16x32_bf16 v[22:25], v[174:177], v[224:227], v[22:25]
	v_mfma_f32_16x16x32_bf16 v[2:5], v[166:169], v[232:235], v[2:5]
	v_mfma_f32_16x16x32_bf16 v[6:9], v[174:177], v[232:235], v[6:9]
	v_mfma_f32_16x16x32_bf16 v[58:61], v[178:181], v[204:207], 0
	v_mfma_f32_16x16x32_bf16 v[62:65], v[192:195], v[204:207], 0
	v_mfma_f32_16x16x32_bf16 v[42:45], v[178:181], v[212:215], 0
	v_mfma_f32_16x16x32_bf16 v[46:49], v[192:195], v[212:215], 0
	v_mfma_f32_16x16x32_bf16 v[26:29], v[178:181], v[220:223], 0
	v_mfma_f32_16x16x32_bf16 v[30:33], v[192:195], v[220:223], 0
	v_mfma_f32_16x16x32_bf16 v[10:13], v[178:181], v[228:231], 0
	v_mfma_f32_16x16x32_bf16 v[14:17], v[192:195], v[228:231], 0
	v_mfma_f32_16x16x32_bf16 v[58:61], v[182:185], v[208:211], v[58:61]
	v_mfma_f32_16x16x32_bf16 v[62:65], v[200:203], v[208:211], v[62:65]
	v_mfma_f32_16x16x32_bf16 v[42:45], v[182:185], v[216:219], v[42:45]
	v_mfma_f32_16x16x32_bf16 v[46:49], v[200:203], v[216:219], v[46:49]
	v_mfma_f32_16x16x32_bf16 v[26:29], v[182:185], v[224:227], v[26:29]
	v_mfma_f32_16x16x32_bf16 v[30:33], v[200:203], v[224:227], v[30:33]
	s_setprio 2
	s_barrier
	v_mfma_f32_16x16x32_bf16 v[10:13], v[182:185], v[232:235], v[10:13]
	v_mfma_f32_16x16x32_bf16 v[14:17], v[200:203], v[232:235], v[14:17]
	s_setprio 0
	ds_read_b128 v[162:165], v255 offset:33024
	ds_read_b128 v[166:169], v255 offset:34048
	ds_read_b128 v[170:173], v255 offset:35072
	ds_read_b128 v[174:177], v255 offset:36096
	ds_read_b128 v[178:181], v255 offset:49408
	ds_read_b128 v[182:185], v255 offset:50432
	ds_read_b128 v[192:195], v255 offset:51456
	ds_read_b128 v[200:203], v255 offset:52480
	s_add_u32 s66, s66, 0x4000
	s_addc_u32 s67, s67, 0
	s_mov_b32 m0, s40
	ds_read_b128 v[204:207], v155 offset:32768
	ds_read_b128 v[208:211], v155 offset:33792
	ds_read_b128 v[212:215], v155 offset:34816
	ds_read_b128 v[216:219], v155 offset:35840
	ds_read_b128 v[220:223], v155 offset:36864
	ds_read_b128 v[224:227], v155 offset:37888
	ds_read_b128 v[228:231], v155 offset:38912
	ds_read_b128 v[232:235], v155 offset:39936
	global_load_lds_dwordx4 v130, s[66:67] sc1
	s_mov_b32 m0, s41
	s_nop 0
	global_load_lds_dwordx4 v134, s[66:67] sc1
	s_waitcnt vmcnt(8)
	s_waitcnt lgkmcnt(0)
	s_setprio 1
	s_barrier
	v_mfma_f32_16x16x32_bf16 v[114:117], v[162:165], v[204:207], v[114:117]
	v_mfma_f32_16x16x32_bf16 v[118:121], v[170:173], v[204:207], v[118:121]
	v_mfma_f32_16x16x32_bf16 v[98:101], v[162:165], v[212:215], v[98:101]
	v_mfma_f32_16x16x32_bf16 v[102:105], v[170:173], v[212:215], v[102:105]
	v_mfma_f32_16x16x32_bf16 v[82:85], v[162:165], v[220:223], v[82:85]
	v_mfma_f32_16x16x32_bf16 v[86:89], v[170:173], v[220:223], v[86:89]
	v_mfma_f32_16x16x32_bf16 v[66:69], v[162:165], v[228:231], v[66:69]
	v_mfma_f32_16x16x32_bf16 v[70:73], v[170:173], v[228:231], v[70:73]
	v_mfma_f32_16x16x32_bf16 v[114:117], v[166:169], v[208:211], v[114:117]
	v_mfma_f32_16x16x32_bf16 v[118:121], v[174:177], v[208:211], v[118:121]
	v_mfma_f32_16x16x32_bf16 v[98:101], v[166:169], v[216:219], v[98:101]
	v_mfma_f32_16x16x32_bf16 v[102:105], v[174:177], v[216:219], v[102:105]
	v_mfma_f32_16x16x32_bf16 v[82:85], v[166:169], v[224:227], v[82:85]
	v_mfma_f32_16x16x32_bf16 v[86:89], v[174:177], v[224:227], v[86:89]
	v_mfma_f32_16x16x32_bf16 v[66:69], v[166:169], v[232:235], v[66:69]
	v_mfma_f32_16x16x32_bf16 v[70:73], v[174:177], v[232:235], v[70:73]
	v_mfma_f32_16x16x32_bf16 v[122:125], v[178:181], v[204:207], v[122:125]
	v_mfma_f32_16x16x32_bf16 v[126:129], v[192:195], v[204:207], v[126:129]
	v_mfma_f32_16x16x32_bf16 v[106:109], v[178:181], v[212:215], v[106:109]
	v_mfma_f32_16x16x32_bf16 v[110:113], v[192:195], v[212:215], v[110:113]
	v_mfma_f32_16x16x32_bf16 v[90:93], v[178:181], v[220:223], v[90:93]
	v_mfma_f32_16x16x32_bf16 v[94:97], v[192:195], v[220:223], v[94:97]
	v_mfma_f32_16x16x32_bf16 v[74:77], v[178:181], v[228:231], v[74:77]
	v_mfma_f32_16x16x32_bf16 v[78:81], v[192:195], v[228:231], v[78:81]
	v_mfma_f32_16x16x32_bf16 v[122:125], v[182:185], v[208:211], v[122:125]
	v_mfma_f32_16x16x32_bf16 v[126:129], v[200:203], v[208:211], v[126:129]
	v_mfma_f32_16x16x32_bf16 v[106:109], v[182:185], v[216:219], v[106:109]
	v_mfma_f32_16x16x32_bf16 v[110:113], v[200:203], v[216:219], v[110:113]
	v_mfma_f32_16x16x32_bf16 v[90:93], v[182:185], v[224:227], v[90:93]
	v_mfma_f32_16x16x32_bf16 v[94:97], v[200:203], v[224:227], v[94:97]
	s_setprio 2
	s_barrier
	v_mfma_f32_16x16x32_bf16 v[74:77], v[182:185], v[232:235], v[74:77]
	v_mfma_f32_16x16x32_bf16 v[78:81], v[200:203], v[232:235], v[78:81]
	s_setprio 0
	s_add_u32 s66, s64, 0x8000
	s_addc_u32 s67, s65, 0
	s_add_i32 s81, s48, s35
	s_mov_b32 m0, s81
	ds_read_b128 v[204:207], v155 offset:49152
	ds_read_b128 v[208:211], v155 offset:50176
	ds_read_b128 v[212:215], v155 offset:51200
	ds_read_b128 v[216:219], v155 offset:52224
	ds_read_b128 v[220:223], v155 offset:53248
	ds_read_b128 v[224:227], v155 offset:54272
	ds_read_b128 v[228:231], v155 offset:55296
	ds_read_b128 v[232:235], v155 offset:56320
	global_load_lds_dwordx4 v132, s[66:67] sc1
	s_add_i32 m0, s81, 0x2000
	s_add_u32 s64, s64, 0xc000
	global_load_lds_dwordx4 v136, s[66:67] sc1
	s_addc_u32 s65, s65, 0
	s_add_i32 s66, s49, s35
	s_mov_b32 m0, s66
	s_nop 0
	global_load_lds_dwordx4 v132, s[64:65] sc1
	s_add_i32 m0, s66, 0x2000
	s_nop 0
	global_load_lds_dwordx4 v136, s[64:65] sc1
	s_mov_b32 m0, s43
	s_nop 0
	global_load_lds_dwordx4 v130, s[62:63] sc1
	s_mov_b32 m0, s44
	s_nop 0
	global_load_lds_dwordx4 v134, s[62:63] sc1
	s_waitcnt vmcnt(8)
	s_waitcnt lgkmcnt(0)
	s_setprio 1
	s_barrier
	v_mfma_f32_16x16x32_bf16 v[50:53], v[162:165], v[204:207], v[50:53]
	v_mfma_f32_16x16x32_bf16 v[54:57], v[170:173], v[204:207], v[54:57]
	v_mfma_f32_16x16x32_bf16 v[34:37], v[162:165], v[212:215], v[34:37]
	v_mfma_f32_16x16x32_bf16 v[38:41], v[170:173], v[212:215], v[38:41]
	v_mfma_f32_16x16x32_bf16 v[18:21], v[162:165], v[220:223], v[18:21]
	v_mfma_f32_16x16x32_bf16 v[22:25], v[170:173], v[220:223], v[22:25]
	v_mfma_f32_16x16x32_bf16 v[2:5], v[162:165], v[228:231], v[2:5]
	v_mfma_f32_16x16x32_bf16 v[6:9], v[170:173], v[228:231], v[6:9]
	v_mfma_f32_16x16x32_bf16 v[50:53], v[166:169], v[208:211], v[50:53]
	v_mfma_f32_16x16x32_bf16 v[54:57], v[174:177], v[208:211], v[54:57]
	v_mfma_f32_16x16x32_bf16 v[34:37], v[166:169], v[216:219], v[34:37]
	v_mfma_f32_16x16x32_bf16 v[38:41], v[174:177], v[216:219], v[38:41]
	v_mfma_f32_16x16x32_bf16 v[18:21], v[166:169], v[224:227], v[18:21]
	v_mfma_f32_16x16x32_bf16 v[22:25], v[174:177], v[224:227], v[22:25]
	v_mfma_f32_16x16x32_bf16 v[2:5], v[166:169], v[232:235], v[2:5]
	v_mfma_f32_16x16x32_bf16 v[6:9], v[174:177], v[232:235], v[6:9]
	v_mfma_f32_16x16x32_bf16 v[58:61], v[178:181], v[204:207], v[58:61]
	v_mfma_f32_16x16x32_bf16 v[62:65], v[192:195], v[204:207], v[62:65]
	v_mfma_f32_16x16x32_bf16 v[42:45], v[178:181], v[212:215], v[42:45]
	v_mfma_f32_16x16x32_bf16 v[46:49], v[192:195], v[212:215], v[46:49]
	v_mfma_f32_16x16x32_bf16 v[26:29], v[178:181], v[220:223], v[26:29]
	v_mfma_f32_16x16x32_bf16 v[30:33], v[192:195], v[220:223], v[30:33]
	v_mfma_f32_16x16x32_bf16 v[10:13], v[178:181], v[228:231], v[10:13]
	v_mfma_f32_16x16x32_bf16 v[14:17], v[192:195], v[228:231], v[14:17]
	v_mfma_f32_16x16x32_bf16 v[58:61], v[182:185], v[208:211], v[58:61]
	v_mfma_f32_16x16x32_bf16 v[62:65], v[200:203], v[208:211], v[62:65]
	v_mfma_f32_16x16x32_bf16 v[42:45], v[182:185], v[216:219], v[42:45]
	v_mfma_f32_16x16x32_bf16 v[46:49], v[200:203], v[216:219], v[46:49]
	v_mfma_f32_16x16x32_bf16 v[26:29], v[182:185], v[224:227], v[26:29]
	v_mfma_f32_16x16x32_bf16 v[30:33], v[200:203], v[224:227], v[30:33]
	s_setprio 2
	s_barrier
	v_mfma_f32_16x16x32_bf16 v[10:13], v[182:185], v[232:235], v[10:13]
	v_mfma_f32_16x16x32_bf16 v[14:17], v[200:203], v[232:235], v[14:17]
	s_setprio 0
	s_add_i32 s80, s80, 2
	s_add_u32 s8, s8, 0x10000
	s_addc_u32 s9, s9, 0
	s_cmp_gt_u32 s80, 41
.LBB0_404:
	s_add_u32 s29, s30, s8
	s_addc_u32 s55, s31, s9
	ds_read_b128 v[162:165], v255 offset:256
	ds_read_b128 v[166:169], v255 offset:1280
	ds_read_b128 v[170:173], v255 offset:2304
	ds_read_b128 v[174:177], v255 offset:3328
	s_add_u32 s29, s29, 0x10000
	ds_read_b128 v[178:181], v255 offset:16640
	ds_read_b128 v[182:185], v255 offset:17664
	ds_read_b128 v[192:195], v255 offset:18688
	ds_read_b128 v[200:203], v255 offset:19712
	s_addc_u32 s55, s55, 0
	s_add_u32 s62, s61, s8
	s_addc_u32 s63, s69, s9
	s_cmp_eq_u32 s8, 0x150000
	s_cselect_b32 s66, s71, s29
	s_cselect_b32 s67, s70, s55
	s_cselect_b32 s64, s79, s62
	s_cselect_b32 s65, s78, s63
	s_add_u32 s62, s66, 0x8000
	s_addc_u32 s63, s67, 0
	s_add_i32 s29, s37, 0xc000
	s_add_u32 s98, s30, s8
	s_addc_u32 s99, s31, s9
	s_mov_b32 m0, s29
	s_add_i32 s55, s37, 0xe000
	ds_read_b128 v[204:207], v155
	ds_read_b128 v[208:211], v155 offset:1024
	ds_read_b128 v[212:215], v155 offset:2048
	ds_read_b128 v[216:219], v155 offset:3072
	ds_read_b128 v[220:223], v155 offset:4096
	ds_read_b128 v[224:227], v155 offset:5120
	ds_read_b128 v[228:231], v155 offset:6144
	ds_read_b128 v[232:235], v155 offset:7168
	global_load_lds_dwordx4 v138, s[98:99] sc1
	s_mov_b32 m0, s55
	s_nop 0
	global_load_lds_dwordx4 v140, s[98:99] sc1
	s_waitcnt vmcnt(8)
	s_waitcnt lgkmcnt(0)
	s_setprio 1
	s_barrier
	v_mfma_f32_16x16x32_bf16 v[114:117], v[162:165], v[204:207], v[114:117]
	v_mfma_f32_16x16x32_bf16 v[118:121], v[170:173], v[204:207], v[118:121]
	v_mfma_f32_16x16x32_bf16 v[98:101], v[162:165], v[212:215], v[98:101]
	v_mfma_f32_16x16x32_bf16 v[102:105], v[170:173], v[212:215], v[102:105]
	v_mfma_f32_16x16x32_bf16 v[82:85], v[162:165], v[220:223], v[82:85]
	v_mfma_f32_16x16x32_bf16 v[86:89], v[170:173], v[220:223], v[86:89]
	v_mfma_f32_16x16x32_bf16 v[66:69], v[162:165], v[228:231], v[66:69]
	v_mfma_f32_16x16x32_bf16 v[70:73], v[170:173], v[228:231], v[70:73]
	v_mfma_f32_16x16x32_bf16 v[114:117], v[166:169], v[208:211], v[114:117]
	v_mfma_f32_16x16x32_bf16 v[118:121], v[174:177], v[208:211], v[118:121]
	v_mfma_f32_16x16x32_bf16 v[98:101], v[166:169], v[216:219], v[98:101]
	v_mfma_f32_16x16x32_bf16 v[102:105], v[174:177], v[216:219], v[102:105]
	v_mfma_f32_16x16x32_bf16 v[82:85], v[166:169], v[224:227], v[82:85]
	v_mfma_f32_16x16x32_bf16 v[86:89], v[174:177], v[224:227], v[86:89]
	v_mfma_f32_16x16x32_bf16 v[66:69], v[166:169], v[232:235], v[66:69]
	v_mfma_f32_16x16x32_bf16 v[70:73], v[174:177], v[232:235], v[70:73]
	v_mfma_f32_16x16x32_bf16 v[122:125], v[178:181], v[204:207], v[122:125]
	v_mfma_f32_16x16x32_bf16 v[126:129], v[192:195], v[204:207], v[126:129]
	v_mfma_f32_16x16x32_bf16 v[106:109], v[178:181], v[212:215], v[106:109]
	v_mfma_f32_16x16x32_bf16 v[110:113], v[192:195], v[212:215], v[110:113]
	v_mfma_f32_16x16x32_bf16 v[90:93], v[178:181], v[220:223], v[90:93]
	v_mfma_f32_16x16x32_bf16 v[94:97], v[192:195], v[220:223], v[94:97]
	v_mfma_f32_16x16x32_bf16 v[74:77], v[178:181], v[228:231], v[74:77]
	v_mfma_f32_16x16x32_bf16 v[78:81], v[192:195], v[228:231], v[78:81]
	v_mfma_f32_16x16x32_bf16 v[122:125], v[182:185], v[208:211], v[122:125]
	v_mfma_f32_16x16x32_bf16 v[126:129], v[200:203], v[208:211], v[126:129]
	v_mfma_f32_16x16x32_bf16 v[106:109], v[182:185], v[216:219], v[106:109]
	v_mfma_f32_16x16x32_bf16 v[110:113], v[200:203], v[216:219], v[110:113]
	v_mfma_f32_16x16x32_bf16 v[90:93], v[182:185], v[224:227], v[90:93]
	v_mfma_f32_16x16x32_bf16 v[94:97], v[200:203], v[224:227], v[94:97]
	s_setprio 2
	s_barrier
	v_mfma_f32_16x16x32_bf16 v[74:77], v[182:185], v[232:235], v[74:77]
	v_mfma_f32_16x16x32_bf16 v[78:81], v[200:203], v[232:235], v[78:81]
	s_setprio 0
	s_add_i32 s81, s45, s35
	s_mov_b32 m0, s81
	ds_read_b128 v[204:207], v155 offset:16384
	ds_read_b128 v[208:211], v155 offset:17408
	ds_read_b128 v[212:215], v155 offset:18432
	ds_read_b128 v[216:219], v155 offset:19456
	ds_read_b128 v[220:223], v155 offset:20480
	ds_read_b128 v[224:227], v155 offset:21504
	ds_read_b128 v[228:231], v155 offset:22528
	ds_read_b128 v[232:235], v155 offset:23552
	global_load_lds_dwordx4 v132, s[64:65] sc1
	s_add_i32 m0, s81, 0x2000
	s_add_u32 s82, s64, 0x4000
	s_addc_u32 s83, s65, 0
	s_add_i32 s81, s47, s35
	global_load_lds_dwordx4 v136, s[64:65] sc1
	s_mov_b32 m0, s81
	s_nop 0
	global_load_lds_dwordx4 v132, s[82:83] sc1
	s_add_i32 m0, s81, 0x2000
	s_nop 0
	global_load_lds_dwordx4 v136, s[82:83] sc1
	s_mov_b32 m0, s37
	s_nop 0
	global_load_lds_dwordx4 v130, s[66:67] sc1
	s_mov_b32 m0, s39
	s_nop 0
	global_load_lds_dwordx4 v134, s[66:67] sc1
	s_waitcnt vmcnt(8)
	s_waitcnt lgkmcnt(0)
	s_setprio 1
	s_barrier
	v_mfma_f32_16x16x32_bf16 v[50:53], v[162:165], v[204:207], v[50:53]
	v_mfma_f32_16x16x32_bf16 v[54:57], v[170:173], v[204:207], v[54:57]
	v_mfma_f32_16x16x32_bf16 v[34:37], v[162:165], v[212:215], v[34:37]
	v_mfma_f32_16x16x32_bf16 v[38:41], v[170:173], v[212:215], v[38:41]
	v_mfma_f32_16x16x32_bf16 v[18:21], v[162:165], v[220:223], v[18:21]
	v_mfma_f32_16x16x32_bf16 v[22:25], v[170:173], v[220:223], v[22:25]
	v_mfma_f32_16x16x32_bf16 v[2:5], v[162:165], v[228:231], v[2:5]
	v_mfma_f32_16x16x32_bf16 v[6:9], v[170:173], v[228:231], v[6:9]
	v_mfma_f32_16x16x32_bf16 v[50:53], v[166:169], v[208:211], v[50:53]
	v_mfma_f32_16x16x32_bf16 v[54:57], v[174:177], v[208:211], v[54:57]
	v_mfma_f32_16x16x32_bf16 v[34:37], v[166:169], v[216:219], v[34:37]
	v_mfma_f32_16x16x32_bf16 v[38:41], v[174:177], v[216:219], v[38:41]
	v_mfma_f32_16x16x32_bf16 v[18:21], v[166:169], v[224:227], v[18:21]
	v_mfma_f32_16x16x32_bf16 v[22:25], v[174:177], v[224:227], v[22:25]
	v_mfma_f32_16x16x32_bf16 v[2:5], v[166:169], v[232:235], v[2:5]
	v_mfma_f32_16x16x32_bf16 v[6:9], v[174:177], v[232:235], v[6:9]
	v_mfma_f32_16x16x32_bf16 v[58:61], v[178:181], v[204:207], v[58:61]
	v_mfma_f32_16x16x32_bf16 v[62:65], v[192:195], v[204:207], v[62:65]
	v_mfma_f32_16x16x32_bf16 v[42:45], v[178:181], v[212:215], v[42:45]
	v_mfma_f32_16x16x32_bf16 v[46:49], v[192:195], v[212:215], v[46:49]
	v_mfma_f32_16x16x32_bf16 v[26:29], v[178:181], v[220:223], v[26:29]
	v_mfma_f32_16x16x32_bf16 v[30:33], v[192:195], v[220:223], v[30:33]
	v_mfma_f32_16x16x32_bf16 v[10:13], v[178:181], v[228:231], v[10:13]
	v_mfma_f32_16x16x32_bf16 v[14:17], v[192:195], v[228:231], v[14:17]
	v_mfma_f32_16x16x32_bf16 v[58:61], v[182:185], v[208:211], v[58:61]
	v_mfma_f32_16x16x32_bf16 v[62:65], v[200:203], v[208:211], v[62:65]
	v_mfma_f32_16x16x32_bf16 v[42:45], v[182:185], v[216:219], v[42:45]
	v_mfma_f32_16x16x32_bf16 v[46:49], v[200:203], v[216:219], v[46:49]
	v_mfma_f32_16x16x32_bf16 v[26:29], v[182:185], v[224:227], v[26:29]
	v_mfma_f32_16x16x32_bf16 v[30:33], v[200:203], v[224:227], v[30:33]
	s_setprio 2
	s_barrier
	v_mfma_f32_16x16x32_bf16 v[10:13], v[182:185], v[232:235], v[10:13]
	v_mfma_f32_16x16x32_bf16 v[14:17], v[200:203], v[232:235], v[14:17]
	s_setprio 0
	ds_read_b128 v[162:165], v255 offset:33024
	ds_read_b128 v[166:169], v255 offset:34048
	ds_read_b128 v[170:173], v255 offset:35072
	ds_read_b128 v[174:177], v255 offset:36096
	ds_read_b128 v[178:181], v255 offset:49408
	ds_read_b128 v[182:185], v255 offset:50432
	ds_read_b128 v[192:195], v255 offset:51456
	ds_read_b128 v[200:203], v255 offset:52480
	s_add_u32 s66, s66, 0x4000
	s_addc_u32 s67, s67, 0
	s_mov_b32 m0, s40
	ds_read_b128 v[204:207], v155 offset:32768
	ds_read_b128 v[208:211], v155 offset:33792
	ds_read_b128 v[212:215], v155 offset:34816
	ds_read_b128 v[216:219], v155 offset:35840
	ds_read_b128 v[220:223], v155 offset:36864
	ds_read_b128 v[224:227], v155 offset:37888
	ds_read_b128 v[228:231], v155 offset:38912
	ds_read_b128 v[232:235], v155 offset:39936
	global_load_lds_dwordx4 v130, s[66:67] sc1
	s_mov_b32 m0, s41
	s_nop 0
	global_load_lds_dwordx4 v134, s[66:67] sc1
	s_waitcnt vmcnt(8)
	s_waitcnt lgkmcnt(0)
	s_setprio 1
	s_barrier
	v_mfma_f32_16x16x32_bf16 v[114:117], v[162:165], v[204:207], v[114:117]
	v_mfma_f32_16x16x32_bf16 v[118:121], v[170:173], v[204:207], v[118:121]
	v_mfma_f32_16x16x32_bf16 v[98:101], v[162:165], v[212:215], v[98:101]
	v_mfma_f32_16x16x32_bf16 v[102:105], v[170:173], v[212:215], v[102:105]
	v_mfma_f32_16x16x32_bf16 v[82:85], v[162:165], v[220:223], v[82:85]
	v_mfma_f32_16x16x32_bf16 v[86:89], v[170:173], v[220:223], v[86:89]
	v_mfma_f32_16x16x32_bf16 v[66:69], v[162:165], v[228:231], v[66:69]
	v_mfma_f32_16x16x32_bf16 v[70:73], v[170:173], v[228:231], v[70:73]
	v_mfma_f32_16x16x32_bf16 v[114:117], v[166:169], v[208:211], v[114:117]
	v_mfma_f32_16x16x32_bf16 v[118:121], v[174:177], v[208:211], v[118:121]
	v_mfma_f32_16x16x32_bf16 v[98:101], v[166:169], v[216:219], v[98:101]
	v_mfma_f32_16x16x32_bf16 v[102:105], v[174:177], v[216:219], v[102:105]
	v_mfma_f32_16x16x32_bf16 v[82:85], v[166:169], v[224:227], v[82:85]
	v_mfma_f32_16x16x32_bf16 v[86:89], v[174:177], v[224:227], v[86:89]
	v_mfma_f32_16x16x32_bf16 v[66:69], v[166:169], v[232:235], v[66:69]
	v_mfma_f32_16x16x32_bf16 v[70:73], v[174:177], v[232:235], v[70:73]
	v_mfma_f32_16x16x32_bf16 v[122:125], v[178:181], v[204:207], v[122:125]
	v_mfma_f32_16x16x32_bf16 v[126:129], v[192:195], v[204:207], v[126:129]
	v_mfma_f32_16x16x32_bf16 v[106:109], v[178:181], v[212:215], v[106:109]
	v_mfma_f32_16x16x32_bf16 v[110:113], v[192:195], v[212:215], v[110:113]
	v_mfma_f32_16x16x32_bf16 v[90:93], v[178:181], v[220:223], v[90:93]
	v_mfma_f32_16x16x32_bf16 v[94:97], v[192:195], v[220:223], v[94:97]
	v_mfma_f32_16x16x32_bf16 v[74:77], v[178:181], v[228:231], v[74:77]
	v_mfma_f32_16x16x32_bf16 v[78:81], v[192:195], v[228:231], v[78:81]
	v_mfma_f32_16x16x32_bf16 v[122:125], v[182:185], v[208:211], v[122:125]
	v_mfma_f32_16x16x32_bf16 v[126:129], v[200:203], v[208:211], v[126:129]
	v_mfma_f32_16x16x32_bf16 v[106:109], v[182:185], v[216:219], v[106:109]
	v_mfma_f32_16x16x32_bf16 v[110:113], v[200:203], v[216:219], v[110:113]
	v_mfma_f32_16x16x32_bf16 v[90:93], v[182:185], v[224:227], v[90:93]
	v_mfma_f32_16x16x32_bf16 v[94:97], v[200:203], v[224:227], v[94:97]
	s_setprio 2
	s_barrier
	v_mfma_f32_16x16x32_bf16 v[74:77], v[182:185], v[232:235], v[74:77]
	v_mfma_f32_16x16x32_bf16 v[78:81], v[200:203], v[232:235], v[78:81]
	s_setprio 0
	s_add_u32 s66, s64, 0x8000
	s_addc_u32 s67, s65, 0
	s_add_i32 s81, s48, s35
	s_mov_b32 m0, s81
	ds_read_b128 v[204:207], v155 offset:49152
	ds_read_b128 v[208:211], v155 offset:50176
	ds_read_b128 v[212:215], v155 offset:51200
	ds_read_b128 v[216:219], v155 offset:52224
	ds_read_b128 v[220:223], v155 offset:53248
	ds_read_b128 v[224:227], v155 offset:54272
	ds_read_b128 v[228:231], v155 offset:55296
	ds_read_b128 v[232:235], v155 offset:56320
	global_load_lds_dwordx4 v132, s[66:67] sc1
	s_add_i32 m0, s81, 0x2000
	s_add_u32 s64, s64, 0xc000
	global_load_lds_dwordx4 v136, s[66:67] sc1
	s_addc_u32 s65, s65, 0
	s_add_i32 s66, s49, s35
	s_mov_b32 m0, s66
	s_nop 0
	global_load_lds_dwordx4 v132, s[64:65] sc1
	s_add_i32 m0, s66, 0x2000
	s_nop 0
	global_load_lds_dwordx4 v136, s[64:65] sc1
	s_mov_b32 m0, s43
	s_nop 0
	global_load_lds_dwordx4 v130, s[62:63] sc1
	s_mov_b32 m0, s44
	s_nop 0
	global_load_lds_dwordx4 v134, s[62:63] sc1
	s_waitcnt vmcnt(8)
	s_waitcnt lgkmcnt(0)
	s_setprio 1
	s_barrier
	v_mfma_f32_16x16x32_bf16 v[50:53], v[162:165], v[204:207], v[50:53]
	v_mfma_f32_16x16x32_bf16 v[54:57], v[170:173], v[204:207], v[54:57]
	v_mfma_f32_16x16x32_bf16 v[34:37], v[162:165], v[212:215], v[34:37]
	v_mfma_f32_16x16x32_bf16 v[38:41], v[170:173], v[212:215], v[38:41]
	v_mfma_f32_16x16x32_bf16 v[18:21], v[162:165], v[220:223], v[18:21]
	v_mfma_f32_16x16x32_bf16 v[22:25], v[170:173], v[220:223], v[22:25]
	v_mfma_f32_16x16x32_bf16 v[2:5], v[162:165], v[228:231], v[2:5]
	v_mfma_f32_16x16x32_bf16 v[6:9], v[170:173], v[228:231], v[6:9]
	v_mfma_f32_16x16x32_bf16 v[50:53], v[166:169], v[208:211], v[50:53]
	v_mfma_f32_16x16x32_bf16 v[54:57], v[174:177], v[208:211], v[54:57]
	v_mfma_f32_16x16x32_bf16 v[34:37], v[166:169], v[216:219], v[34:37]
	v_mfma_f32_16x16x32_bf16 v[38:41], v[174:177], v[216:219], v[38:41]
	v_mfma_f32_16x16x32_bf16 v[18:21], v[166:169], v[224:227], v[18:21]
	v_mfma_f32_16x16x32_bf16 v[22:25], v[174:177], v[224:227], v[22:25]
	v_mfma_f32_16x16x32_bf16 v[2:5], v[166:169], v[232:235], v[2:5]
	v_mfma_f32_16x16x32_bf16 v[6:9], v[174:177], v[232:235], v[6:9]
	v_mfma_f32_16x16x32_bf16 v[58:61], v[178:181], v[204:207], v[58:61]
	v_mfma_f32_16x16x32_bf16 v[62:65], v[192:195], v[204:207], v[62:65]
	v_mfma_f32_16x16x32_bf16 v[42:45], v[178:181], v[212:215], v[42:45]
	v_mfma_f32_16x16x32_bf16 v[46:49], v[192:195], v[212:215], v[46:49]
	v_mfma_f32_16x16x32_bf16 v[26:29], v[178:181], v[220:223], v[26:29]
	v_mfma_f32_16x16x32_bf16 v[30:33], v[192:195], v[220:223], v[30:33]
	v_mfma_f32_16x16x32_bf16 v[10:13], v[178:181], v[228:231], v[10:13]
	v_mfma_f32_16x16x32_bf16 v[14:17], v[192:195], v[228:231], v[14:17]
	v_mfma_f32_16x16x32_bf16 v[58:61], v[182:185], v[208:211], v[58:61]
	v_mfma_f32_16x16x32_bf16 v[62:65], v[200:203], v[208:211], v[62:65]
	v_mfma_f32_16x16x32_bf16 v[42:45], v[182:185], v[216:219], v[42:45]
	v_mfma_f32_16x16x32_bf16 v[46:49], v[200:203], v[216:219], v[46:49]
	v_mfma_f32_16x16x32_bf16 v[26:29], v[182:185], v[224:227], v[26:29]
	v_mfma_f32_16x16x32_bf16 v[30:33], v[200:203], v[224:227], v[30:33]
	s_setprio 2
	s_barrier
	v_mfma_f32_16x16x32_bf16 v[10:13], v[182:185], v[232:235], v[10:13]
	v_mfma_f32_16x16x32_bf16 v[14:17], v[200:203], v[232:235], v[14:17]
	s_setprio 0
	s_add_i32 s80, s80, 2
	s_add_u32 s8, s8, 0x10000
	s_addc_u32 s9, s9, 0
	s_cmp_gt_u32 s80, 41
	s_cbranch_scc0 .LBB0_404
	s_add_u32 s8, s61, 0xffff0000
	s_addc_u32 s9, s69, -1
	s_and_b64 vcc, exec, s[6:7]
	s_cbranch_vccnz .LBB0_391
	s_mov_b32 s10, s50
	s_mov_b32 s28, s51
	s_mov_b64 s[30:31], s[56:57]
	s_mov_b32 s46, s54
	s_andn2_b64 vcc, exec, s[4:5]
	s_cbranch_vccnz .LBB0_392

.LBB0_459:
	s_mov_b32 s40, s38
	s_add_i32 s38, s38, 1
	s_cmp_lt_u32 s38, s7
	s_mov_b32 s35, s39
	s_cselect_b64 s[42:43], -1, 0
	s_add_i32 s39, s38, s6
	s_sub_i32 s98, s39, 11
	s_cmp_lt_u32 s98, 3
	s_cselect_b32 s99, 7, 0
	s_sub_i32 s98, s39, 18
	s_cmp_lt_u32 s98, 3
	s_cselect_b32 s98, 0xfffffff9, 0
	s_add_i32 s99, s99, s98
	s_cmp_eq_u32 s39, 6
	s_cselect_b32 s98, 11, 0
	s_add_i32 s99, s99, s98
	s_cmp_eq_u32 s39, 17
	s_cselect_b32 s98, 0xfffffff5, 0
	s_add_i32 s99, s99, s98
	s_add_i32 s39, s39, s99
	s_and_b64 s[44:45], s[42:43], exec
	s_cselect_b32 s46, s58, s58
	s_cselect_b32 s44, s39, s35
	s_ashr_i32 s47, s46, 31
	s_lshl_b64 s[46:47], s[46:47], 19
	s_mov_b64 s[4:5], s[82:83]
	s_add_u32 s82, s60, s46
	s_addc_u32 s83, s33, s47
	s_and_b64 s[46:47], s[42:43], exec
	s_cselect_b32 s35, s83, s5
	s_cselect_b32 s41, s82, s4
	s_ashr_i32 s45, s44, 31
	s_lshl_b64 s[44:45], s[44:45], 19
	v_readlane_b32 s12, v253, 61
	s_mov_b64 s[8:9], s[62:63]
	v_readlane_b32 s13, v253, 62
	s_add_u32 s62, s12, s44
	s_addc_u32 s63, s13, s45
	s_and_b64 s[42:43], s[42:43], exec
	s_cselect_b32 s42, s63, s9
	s_cselect_b32 s43, s62, s8
	s_add_u32 s44, s8, 0x10000
	s_addc_u32 s45, s9, 0
	s_mov_b32 s46, -2
	v_add_u32_e32 v255, 0x10000, v1
	ds_read_b128 v[130:133], v255 offset:256
	ds_read_b128 v[136:139], v255 offset:1280
	ds_read_b128 v[140:143], v255 offset:2304
	ds_read_b128 v[144:147], v255 offset:3328
	ds_read_b128 v[170:173], v255 offset:16640
	ds_read_b128 v[200:203], v255 offset:17664
	ds_read_b128 v[204:207], v255 offset:18688
	ds_read_b128 v[208:211], v255 offset:19712
	s_add_u32 s8, s4, 0x10000
	s_addc_u32 s9, s5, 0
	s_cmp_eq_u32 s46, 12
	s_cselect_b32 s84, s41, s8
	s_cselect_b32 s85, s35, s9
	s_cselect_b32 s64, s43, s44
	s_cselect_b32 s65, s42, s45
	s_add_u32 s56, s84, 0x8000
	s_addc_u32 s57, s85, 0
	s_add_i32 m0, s69, 0xc000
	ds_read_b128 v[212:215], v194
	ds_read_b128 v[216:219], v194 offset:1024
	ds_read_b128 v[220:223], v194 offset:2048
	ds_read_b128 v[224:227], v194 offset:3072
	ds_read_b128 v[228:231], v194 offset:4096
	ds_read_b128 v[232:235], v194 offset:5120
	ds_read_b128 v[236:239], v194 offset:6144
	ds_read_b128 v[240:243], v194 offset:7168
	global_load_lds_dwordx4 v166, s[4:5] sc1
	s_add_i32 m0, s69, 0xe000
	s_nop 0
	global_load_lds_dwordx4 v168, s[4:5] sc1
	s_waitcnt vmcnt(8)
	s_waitcnt lgkmcnt(0)
	s_setprio 1
	s_barrier
	v_mfma_f32_16x16x32_bf16 v[122:125], v[130:133], v[212:215], 0
	v_mfma_f32_16x16x32_bf16 v[126:129], v[140:143], v[212:215], 0
	v_mfma_f32_16x16x32_bf16 v[106:109], v[130:133], v[220:223], 0
	v_mfma_f32_16x16x32_bf16 v[110:113], v[140:143], v[220:223], 0
	v_mfma_f32_16x16x32_bf16 v[90:93], v[130:133], v[228:231], 0
	v_mfma_f32_16x16x32_bf16 v[94:97], v[140:143], v[228:231], 0
	v_mfma_f32_16x16x32_bf16 v[74:77], v[130:133], v[236:239], 0
	v_mfma_f32_16x16x32_bf16 v[78:81], v[140:143], v[236:239], 0
	v_mfma_f32_16x16x32_bf16 v[122:125], v[136:139], v[216:219], v[122:125]
	v_mfma_f32_16x16x32_bf16 v[126:129], v[144:147], v[216:219], v[126:129]
	v_mfma_f32_16x16x32_bf16 v[106:109], v[136:139], v[224:227], v[106:109]
	v_mfma_f32_16x16x32_bf16 v[110:113], v[144:147], v[224:227], v[110:113]
	v_mfma_f32_16x16x32_bf16 v[90:93], v[136:139], v[232:235], v[90:93]
	v_mfma_f32_16x16x32_bf16 v[94:97], v[144:147], v[232:235], v[94:97]
	v_mfma_f32_16x16x32_bf16 v[74:77], v[136:139], v[240:243], v[74:77]
	v_mfma_f32_16x16x32_bf16 v[78:81], v[144:147], v[240:243], v[78:81]
	v_mfma_f32_16x16x32_bf16 v[114:117], v[170:173], v[212:215], 0
	v_mfma_f32_16x16x32_bf16 v[118:121], v[204:207], v[212:215], 0
	v_mfma_f32_16x16x32_bf16 v[98:101], v[170:173], v[220:223], 0
	v_mfma_f32_16x16x32_bf16 v[102:105], v[204:207], v[220:223], 0
	v_mfma_f32_16x16x32_bf16 v[82:85], v[170:173], v[228:231], 0
	v_mfma_f32_16x16x32_bf16 v[86:89], v[204:207], v[228:231], 0
	v_mfma_f32_16x16x32_bf16 v[66:69], v[170:173], v[236:239], 0
	v_mfma_f32_16x16x32_bf16 v[70:73], v[204:207], v[236:239], 0
	v_mfma_f32_16x16x32_bf16 v[114:117], v[200:203], v[216:219], v[114:117]
	v_mfma_f32_16x16x32_bf16 v[118:121], v[208:211], v[216:219], v[118:121]
	v_mfma_f32_16x16x32_bf16 v[98:101], v[200:203], v[224:227], v[98:101]
	v_mfma_f32_16x16x32_bf16 v[102:105], v[208:211], v[224:227], v[102:105]
	v_mfma_f32_16x16x32_bf16 v[82:85], v[200:203], v[232:235], v[82:85]
	v_mfma_f32_16x16x32_bf16 v[86:89], v[208:211], v[232:235], v[86:89]
	s_setprio 2
	s_barrier
	v_mfma_f32_16x16x32_bf16 v[66:69], v[200:203], v[240:243], v[66:69]
	v_mfma_f32_16x16x32_bf16 v[70:73], v[208:211], v[240:243], v[70:73]
	s_setprio 0
	s_add_i32 s4, s95, s61
	s_mov_b32 m0, s4
	ds_read_b128 v[212:215], v194 offset:16384
	ds_read_b128 v[216:219], v194 offset:17408
	ds_read_b128 v[220:223], v194 offset:18432
	ds_read_b128 v[224:227], v194 offset:19456
	ds_read_b128 v[228:231], v194 offset:20480
	ds_read_b128 v[232:235], v194 offset:21504
	ds_read_b128 v[236:239], v194 offset:22528
	ds_read_b128 v[240:243], v194 offset:23552
	global_load_lds_dwordx4 v152, s[64:65] sc1
	s_add_i32 m0, s4, 0x2000
	s_add_u32 s4, s64, 0x4000
	s_addc_u32 s5, s65, 0
	s_add_i32 s47, s93, s61
	global_load_lds_dwordx4 v154, s[64:65] sc1
	s_mov_b32 m0, s47
	s_nop 0
	global_load_lds_dwordx4 v152, s[4:5] sc1
	s_add_i32 m0, s47, 0x2000
	s_nop 0
	global_load_lds_dwordx4 v154, s[4:5] sc1
	s_mov_b32 m0, s69
	s_nop 0
	global_load_lds_dwordx4 v150, s[84:85] sc1
	s_mov_b32 m0, s77
	s_nop 0
	global_load_lds_dwordx4 v148, s[84:85] sc1
	s_waitcnt vmcnt(8)
	s_waitcnt lgkmcnt(0)
	s_setprio 1
	s_barrier
	v_mfma_f32_16x16x32_bf16 v[58:61], v[130:133], v[212:215], 0
	v_mfma_f32_16x16x32_bf16 v[62:65], v[140:143], v[212:215], 0
	v_mfma_f32_16x16x32_bf16 v[42:45], v[130:133], v[220:223], 0
	v_mfma_f32_16x16x32_bf16 v[46:49], v[140:143], v[220:223], 0
	v_mfma_f32_16x16x32_bf16 v[26:29], v[130:133], v[228:231], 0
	v_mfma_f32_16x16x32_bf16 v[30:33], v[140:143], v[228:231], 0
	v_mfma_f32_16x16x32_bf16 v[10:13], v[130:133], v[236:239], 0
	v_mfma_f32_16x16x32_bf16 v[14:17], v[140:143], v[236:239], 0
	v_mfma_f32_16x16x32_bf16 v[58:61], v[136:139], v[216:219], v[58:61]
	v_mfma_f32_16x16x32_bf16 v[62:65], v[144:147], v[216:219], v[62:65]
	v_mfma_f32_16x16x32_bf16 v[42:45], v[136:139], v[224:227], v[42:45]
	v_mfma_f32_16x16x32_bf16 v[46:49], v[144:147], v[224:227], v[46:49]
	v_mfma_f32_16x16x32_bf16 v[26:29], v[136:139], v[232:235], v[26:29]
	v_mfma_f32_16x16x32_bf16 v[30:33], v[144:147], v[232:235], v[30:33]
	v_mfma_f32_16x16x32_bf16 v[10:13], v[136:139], v[240:243], v[10:13]
	v_mfma_f32_16x16x32_bf16 v[14:17], v[144:147], v[240:243], v[14:17]
	v_mfma_f32_16x16x32_bf16 v[50:53], v[170:173], v[212:215], 0
	v_mfma_f32_16x16x32_bf16 v[54:57], v[204:207], v[212:215], 0
	v_mfma_f32_16x16x32_bf16 v[34:37], v[170:173], v[220:223], 0
	v_mfma_f32_16x16x32_bf16 v[38:41], v[204:207], v[220:223], 0
	v_mfma_f32_16x16x32_bf16 v[18:21], v[170:173], v[228:231], 0
	v_mfma_f32_16x16x32_bf16 v[22:25], v[204:207], v[228:231], 0
	v_mfma_f32_16x16x32_bf16 v[2:5], v[170:173], v[236:239], 0
	v_mfma_f32_16x16x32_bf16 v[6:9], v[204:207], v[236:239], 0
	v_mfma_f32_16x16x32_bf16 v[50:53], v[200:203], v[216:219], v[50:53]
	v_mfma_f32_16x16x32_bf16 v[54:57], v[208:211], v[216:219], v[54:57]
	v_mfma_f32_16x16x32_bf16 v[34:37], v[200:203], v[224:227], v[34:37]
	v_mfma_f32_16x16x32_bf16 v[38:41], v[208:211], v[224:227], v[38:41]
	v_mfma_f32_16x16x32_bf16 v[18:21], v[200:203], v[232:235], v[18:21]
	v_mfma_f32_16x16x32_bf16 v[22:25], v[208:211], v[232:235], v[22:25]
	s_setprio 2
	s_barrier
	v_mfma_f32_16x16x32_bf16 v[2:5], v[200:203], v[240:243], v[2:5]
	v_mfma_f32_16x16x32_bf16 v[6:9], v[208:211], v[240:243], v[6:9]
	s_setprio 0
	ds_read_b128 v[130:133], v255 offset:33024
	ds_read_b128 v[136:139], v255 offset:34048
	ds_read_b128 v[140:143], v255 offset:35072
	ds_read_b128 v[144:147], v255 offset:36096
	ds_read_b128 v[170:173], v255 offset:49408
	ds_read_b128 v[200:203], v255 offset:50432
	ds_read_b128 v[204:207], v255 offset:51456
	ds_read_b128 v[208:211], v255 offset:52480
	s_add_u32 s4, s84, 0x4000
	s_addc_u32 s5, s85, 0
	s_mov_b32 m0, s86
	ds_read_b128 v[212:215], v194 offset:32768
	ds_read_b128 v[216:219], v194 offset:33792
	ds_read_b128 v[220:223], v194 offset:34816
	ds_read_b128 v[224:227], v194 offset:35840
	ds_read_b128 v[228:231], v194 offset:36864
	ds_read_b128 v[232:235], v194 offset:37888
	ds_read_b128 v[236:239], v194 offset:38912
	ds_read_b128 v[240:243], v194 offset:39936
	global_load_lds_dwordx4 v150, s[4:5] sc1
	s_mov_b32 m0, s87
	s_nop 0
	global_load_lds_dwordx4 v148, s[4:5] sc1
	s_waitcnt vmcnt(8)
	s_waitcnt lgkmcnt(0)
	s_setprio 1
	s_barrier
	v_mfma_f32_16x16x32_bf16 v[122:125], v[130:133], v[212:215], v[122:125]
	v_mfma_f32_16x16x32_bf16 v[126:129], v[140:143], v[212:215], v[126:129]
	v_mfma_f32_16x16x32_bf16 v[106:109], v[130:133], v[220:223], v[106:109]
	v_mfma_f32_16x16x32_bf16 v[110:113], v[140:143], v[220:223], v[110:113]
	v_mfma_f32_16x16x32_bf16 v[90:93], v[130:133], v[228:231], v[90:93]
	v_mfma_f32_16x16x32_bf16 v[94:97], v[140:143], v[228:231], v[94:97]
	v_mfma_f32_16x16x32_bf16 v[74:77], v[130:133], v[236:239], v[74:77]
	v_mfma_f32_16x16x32_bf16 v[78:81], v[140:143], v[236:239], v[78:81]
	v_mfma_f32_16x16x32_bf16 v[122:125], v[136:139], v[216:219], v[122:125]
	v_mfma_f32_16x16x32_bf16 v[126:129], v[144:147], v[216:219], v[126:129]
	v_mfma_f32_16x16x32_bf16 v[106:109], v[136:139], v[224:227], v[106:109]
	v_mfma_f32_16x16x32_bf16 v[110:113], v[144:147], v[224:227], v[110:113]
	v_mfma_f32_16x16x32_bf16 v[90:93], v[136:139], v[232:235], v[90:93]
	v_mfma_f32_16x16x32_bf16 v[94:97], v[144:147], v[232:235], v[94:97]
	v_mfma_f32_16x16x32_bf16 v[74:77], v[136:139], v[240:243], v[74:77]
	v_mfma_f32_16x16x32_bf16 v[78:81], v[144:147], v[240:243], v[78:81]
	v_mfma_f32_16x16x32_bf16 v[114:117], v[170:173], v[212:215], v[114:117]
	v_mfma_f32_16x16x32_bf16 v[118:121], v[204:207], v[212:215], v[118:121]
	v_mfma_f32_16x16x32_bf16 v[98:101], v[170:173], v[220:223], v[98:101]
	v_mfma_f32_16x16x32_bf16 v[102:105], v[204:207], v[220:223], v[102:105]
	v_mfma_f32_16x16x32_bf16 v[82:85], v[170:173], v[228:231], v[82:85]
	v_mfma_f32_16x16x32_bf16 v[86:89], v[204:207], v[228:231], v[86:89]
	v_mfma_f32_16x16x32_bf16 v[66:69], v[170:173], v[236:239], v[66:69]
	v_mfma_f32_16x16x32_bf16 v[70:73], v[204:207], v[236:239], v[70:73]
	v_mfma_f32_16x16x32_bf16 v[114:117], v[200:203], v[216:219], v[114:117]
	v_mfma_f32_16x16x32_bf16 v[118:121], v[208:211], v[216:219], v[118:121]
	v_mfma_f32_16x16x32_bf16 v[98:101], v[200:203], v[224:227], v[98:101]
	v_mfma_f32_16x16x32_bf16 v[102:105], v[208:211], v[224:227], v[102:105]
	v_mfma_f32_16x16x32_bf16 v[82:85], v[200:203], v[232:235], v[82:85]
	v_mfma_f32_16x16x32_bf16 v[86:89], v[208:211], v[232:235], v[86:89]
	s_setprio 2
	s_barrier
	v_mfma_f32_16x16x32_bf16 v[66:69], v[200:203], v[240:243], v[66:69]
	v_mfma_f32_16x16x32_bf16 v[70:73], v[208:211], v[240:243], v[70:73]
	s_setprio 0
	s_add_u32 s4, s64, 0x8000
	s_addc_u32 s5, s65, 0
	s_add_i32 s47, s36, s61
	s_mov_b32 m0, s47
	ds_read_b128 v[212:215], v194 offset:49152
	ds_read_b128 v[216:219], v194 offset:50176
	ds_read_b128 v[220:223], v194 offset:51200
	ds_read_b128 v[224:227], v194 offset:52224
	ds_read_b128 v[228:231], v194 offset:53248
	ds_read_b128 v[232:235], v194 offset:54272
	ds_read_b128 v[236:239], v194 offset:55296
	ds_read_b128 v[240:243], v194 offset:56320
	global_load_lds_dwordx4 v152, s[4:5] sc1
	s_add_i32 m0, s47, 0x2000
	s_nop 0
	global_load_lds_dwordx4 v154, s[4:5] sc1
	s_add_u32 s4, s64, 0xc000
	s_addc_u32 s5, s65, 0
	s_add_i32 s47, s37, s61
	s_mov_b32 m0, s47
	s_nop 0
	global_load_lds_dwordx4 v152, s[4:5] sc1
	s_add_i32 m0, s47, 0x2000
	s_nop 0
	global_load_lds_dwordx4 v154, s[4:5] sc1
	s_mov_b32 m0, s91
	s_nop 0
	global_load_lds_dwordx4 v150, s[56:57] sc1
	s_mov_b32 m0, s92
	s_nop 0
	global_load_lds_dwordx4 v148, s[56:57] sc1
	s_waitcnt vmcnt(8)
	s_waitcnt lgkmcnt(0)
	s_setprio 1
	s_barrier
	v_mfma_f32_16x16x32_bf16 v[58:61], v[130:133], v[212:215], v[58:61]
	v_mfma_f32_16x16x32_bf16 v[62:65], v[140:143], v[212:215], v[62:65]
	v_mfma_f32_16x16x32_bf16 v[42:45], v[130:133], v[220:223], v[42:45]
	v_mfma_f32_16x16x32_bf16 v[46:49], v[140:143], v[220:223], v[46:49]
	v_mfma_f32_16x16x32_bf16 v[26:29], v[130:133], v[228:231], v[26:29]
	v_mfma_f32_16x16x32_bf16 v[30:33], v[140:143], v[228:231], v[30:33]
	v_mfma_f32_16x16x32_bf16 v[10:13], v[130:133], v[236:239], v[10:13]
	v_mfma_f32_16x16x32_bf16 v[14:17], v[140:143], v[236:239], v[14:17]
	v_mfma_f32_16x16x32_bf16 v[58:61], v[136:139], v[216:219], v[58:61]
	v_mfma_f32_16x16x32_bf16 v[62:65], v[144:147], v[216:219], v[62:65]
	v_mfma_f32_16x16x32_bf16 v[42:45], v[136:139], v[224:227], v[42:45]
	v_mfma_f32_16x16x32_bf16 v[46:49], v[144:147], v[224:227], v[46:49]
	v_mfma_f32_16x16x32_bf16 v[26:29], v[136:139], v[232:235], v[26:29]
	v_mfma_f32_16x16x32_bf16 v[30:33], v[144:147], v[232:235], v[30:33]
	v_mfma_f32_16x16x32_bf16 v[10:13], v[136:139], v[240:243], v[10:13]
	v_mfma_f32_16x16x32_bf16 v[14:17], v[144:147], v[240:243], v[14:17]
	v_mfma_f32_16x16x32_bf16 v[50:53], v[170:173], v[212:215], v[50:53]
	v_mfma_f32_16x16x32_bf16 v[54:57], v[204:207], v[212:215], v[54:57]
	v_mfma_f32_16x16x32_bf16 v[34:37], v[170:173], v[220:223], v[34:37]
	v_mfma_f32_16x16x32_bf16 v[38:41], v[204:207], v[220:223], v[38:41]
	v_mfma_f32_16x16x32_bf16 v[18:21], v[170:173], v[228:231], v[18:21]
	v_mfma_f32_16x16x32_bf16 v[22:25], v[204:207], v[228:231], v[22:25]
	v_mfma_f32_16x16x32_bf16 v[2:5], v[170:173], v[236:239], v[2:5]
	v_mfma_f32_16x16x32_bf16 v[6:9], v[204:207], v[236:239], v[6:9]
	v_mfma_f32_16x16x32_bf16 v[50:53], v[200:203], v[216:219], v[50:53]
	v_mfma_f32_16x16x32_bf16 v[54:57], v[208:211], v[216:219], v[54:57]
	v_mfma_f32_16x16x32_bf16 v[34:37], v[200:203], v[224:227], v[34:37]
	v_mfma_f32_16x16x32_bf16 v[38:41], v[208:211], v[224:227], v[38:41]
	v_mfma_f32_16x16x32_bf16 v[18:21], v[200:203], v[232:235], v[18:21]
	v_mfma_f32_16x16x32_bf16 v[22:25], v[208:211], v[232:235], v[22:25]
	s_setprio 2
	s_barrier
	v_mfma_f32_16x16x32_bf16 v[2:5], v[200:203], v[240:243], v[2:5]
	v_mfma_f32_16x16x32_bf16 v[6:9], v[208:211], v[240:243], v[6:9]
	s_setprio 0
	s_add_i32 s46, s46, 2
	s_add_u32 s44, s44, 0x10000
	s_addc_u32 s45, s45, 0
	s_cmp_gt_u32 s46, 13
	s_mov_b64 s[4:5], s[8:9]
.LBB0_460:
	ds_read_b128 v[130:133], v255 offset:256
	ds_read_b128 v[136:139], v255 offset:1280
	ds_read_b128 v[140:143], v255 offset:2304
	ds_read_b128 v[144:147], v255 offset:3328
	ds_read_b128 v[170:173], v255 offset:16640
	ds_read_b128 v[200:203], v255 offset:17664
	ds_read_b128 v[204:207], v255 offset:18688
	ds_read_b128 v[208:211], v255 offset:19712
	s_add_u32 s8, s4, 0x10000
	s_addc_u32 s9, s5, 0
	s_cmp_eq_u32 s46, 12
	s_cselect_b32 s84, s41, s8
	s_cselect_b32 s85, s35, s9
	s_cselect_b32 s64, s43, s44
	s_cselect_b32 s65, s42, s45
	s_add_u32 s56, s84, 0x8000
	s_addc_u32 s57, s85, 0
	s_add_i32 m0, s69, 0xc000
	ds_read_b128 v[212:215], v194
	ds_read_b128 v[216:219], v194 offset:1024
	ds_read_b128 v[220:223], v194 offset:2048
	ds_read_b128 v[224:227], v194 offset:3072
	ds_read_b128 v[228:231], v194 offset:4096
	ds_read_b128 v[232:235], v194 offset:5120
	ds_read_b128 v[236:239], v194 offset:6144
	ds_read_b128 v[240:243], v194 offset:7168
	global_load_lds_dwordx4 v166, s[4:5] sc1
	s_add_i32 m0, s69, 0xe000
	s_nop 0
	global_load_lds_dwordx4 v168, s[4:5] sc1
	s_waitcnt vmcnt(8)
	s_waitcnt lgkmcnt(0)
	s_setprio 1
	s_barrier
	v_mfma_f32_16x16x32_bf16 v[122:125], v[130:133], v[212:215], v[122:125]
	v_mfma_f32_16x16x32_bf16 v[126:129], v[140:143], v[212:215], v[126:129]
	v_mfma_f32_16x16x32_bf16 v[106:109], v[130:133], v[220:223], v[106:109]
	v_mfma_f32_16x16x32_bf16 v[110:113], v[140:143], v[220:223], v[110:113]
	v_mfma_f32_16x16x32_bf16 v[90:93], v[130:133], v[228:231], v[90:93]
	v_mfma_f32_16x16x32_bf16 v[94:97], v[140:143], v[228:231], v[94:97]
	v_mfma_f32_16x16x32_bf16 v[74:77], v[130:133], v[236:239], v[74:77]
	v_mfma_f32_16x16x32_bf16 v[78:81], v[140:143], v[236:239], v[78:81]
	v_mfma_f32_16x16x32_bf16 v[122:125], v[136:139], v[216:219], v[122:125]
	v_mfma_f32_16x16x32_bf16 v[126:129], v[144:147], v[216:219], v[126:129]
	v_mfma_f32_16x16x32_bf16 v[106:109], v[136:139], v[224:227], v[106:109]
	v_mfma_f32_16x16x32_bf16 v[110:113], v[144:147], v[224:227], v[110:113]
	v_mfma_f32_16x16x32_bf16 v[90:93], v[136:139], v[232:235], v[90:93]
	v_mfma_f32_16x16x32_bf16 v[94:97], v[144:147], v[232:235], v[94:97]
	v_mfma_f32_16x16x32_bf16 v[74:77], v[136:139], v[240:243], v[74:77]
	v_mfma_f32_16x16x32_bf16 v[78:81], v[144:147], v[240:243], v[78:81]
	v_mfma_f32_16x16x32_bf16 v[114:117], v[170:173], v[212:215], v[114:117]
	v_mfma_f32_16x16x32_bf16 v[118:121], v[204:207], v[212:215], v[118:121]
	v_mfma_f32_16x16x32_bf16 v[98:101], v[170:173], v[220:223], v[98:101]
	v_mfma_f32_16x16x32_bf16 v[102:105], v[204:207], v[220:223], v[102:105]
	v_mfma_f32_16x16x32_bf16 v[82:85], v[170:173], v[228:231], v[82:85]
	v_mfma_f32_16x16x32_bf16 v[86:89], v[204:207], v[228:231], v[86:89]
	v_mfma_f32_16x16x32_bf16 v[66:69], v[170:173], v[236:239], v[66:69]
	v_mfma_f32_16x16x32_bf16 v[70:73], v[204:207], v[236:239], v[70:73]
	v_mfma_f32_16x16x32_bf16 v[114:117], v[200:203], v[216:219], v[114:117]
	v_mfma_f32_16x16x32_bf16 v[118:121], v[208:211], v[216:219], v[118:121]
	v_mfma_f32_16x16x32_bf16 v[98:101], v[200:203], v[224:227], v[98:101]
	v_mfma_f32_16x16x32_bf16 v[102:105], v[208:211], v[224:227], v[102:105]
	v_mfma_f32_16x16x32_bf16 v[82:85], v[200:203], v[232:235], v[82:85]
	v_mfma_f32_16x16x32_bf16 v[86:89], v[208:211], v[232:235], v[86:89]
	s_setprio 2
	s_barrier
	v_mfma_f32_16x16x32_bf16 v[66:69], v[200:203], v[240:243], v[66:69]
	v_mfma_f32_16x16x32_bf16 v[70:73], v[208:211], v[240:243], v[70:73]
	s_setprio 0
	s_add_i32 s4, s95, s61
	s_mov_b32 m0, s4
	ds_read_b128 v[212:215], v194 offset:16384
	ds_read_b128 v[216:219], v194 offset:17408
	ds_read_b128 v[220:223], v194 offset:18432
	ds_read_b128 v[224:227], v194 offset:19456
	ds_read_b128 v[228:231], v194 offset:20480
	ds_read_b128 v[232:235], v194 offset:21504
	ds_read_b128 v[236:239], v194 offset:22528
	ds_read_b128 v[240:243], v194 offset:23552
	global_load_lds_dwordx4 v152, s[64:65] sc1
	s_add_i32 m0, s4, 0x2000
	s_add_u32 s4, s64, 0x4000
	s_addc_u32 s5, s65, 0
	s_add_i32 s47, s93, s61
	global_load_lds_dwordx4 v154, s[64:65] sc1
	s_mov_b32 m0, s47
	s_nop 0
	global_load_lds_dwordx4 v152, s[4:5] sc1
	s_add_i32 m0, s47, 0x2000
	s_nop 0
	global_load_lds_dwordx4 v154, s[4:5] sc1
	s_mov_b32 m0, s69
	s_nop 0
	global_load_lds_dwordx4 v150, s[84:85] sc1
	s_mov_b32 m0, s77
	s_nop 0
	global_load_lds_dwordx4 v148, s[84:85] sc1
	s_waitcnt vmcnt(8)
	s_waitcnt lgkmcnt(0)
	s_setprio 1
	s_barrier
	v_mfma_f32_16x16x32_bf16 v[58:61], v[130:133], v[212:215], v[58:61]
	v_mfma_f32_16x16x32_bf16 v[62:65], v[140:143], v[212:215], v[62:65]
	v_mfma_f32_16x16x32_bf16 v[42:45], v[130:133], v[220:223], v[42:45]
	v_mfma_f32_16x16x32_bf16 v[46:49], v[140:143], v[220:223], v[46:49]
	v_mfma_f32_16x16x32_bf16 v[26:29], v[130:133], v[228:231], v[26:29]
	v_mfma_f32_16x16x32_bf16 v[30:33], v[140:143], v[228:231], v[30:33]
	v_mfma_f32_16x16x32_bf16 v[10:13], v[130:133], v[236:239], v[10:13]
	v_mfma_f32_16x16x32_bf16 v[14:17], v[140:143], v[236:239], v[14:17]
	v_mfma_f32_16x16x32_bf16 v[58:61], v[136:139], v[216:219], v[58:61]
	v_mfma_f32_16x16x32_bf16 v[62:65], v[144:147], v[216:219], v[62:65]
	v_mfma_f32_16x16x32_bf16 v[42:45], v[136:139], v[224:227], v[42:45]
	v_mfma_f32_16x16x32_bf16 v[46:49], v[144:147], v[224:227], v[46:49]
	v_mfma_f32_16x16x32_bf16 v[26:29], v[136:139], v[232:235], v[26:29]
	v_mfma_f32_16x16x32_bf16 v[30:33], v[144:147], v[232:235], v[30:33]
	v_mfma_f32_16x16x32_bf16 v[10:13], v[136:139], v[240:243], v[10:13]
	v_mfma_f32_16x16x32_bf16 v[14:17], v[144:147], v[240:243], v[14:17]
	v_mfma_f32_16x16x32_bf16 v[50:53], v[170:173], v[212:215], v[50:53]
	v_mfma_f32_16x16x32_bf16 v[54:57], v[204:207], v[212:215], v[54:57]
	v_mfma_f32_16x16x32_bf16 v[34:37], v[170:173], v[220:223], v[34:37]
	v_mfma_f32_16x16x32_bf16 v[38:41], v[204:207], v[220:223], v[38:41]
	v_mfma_f32_16x16x32_bf16 v[18:21], v[170:173], v[228:231], v[18:21]
	v_mfma_f32_16x16x32_bf16 v[22:25], v[204:207], v[228:231], v[22:25]
	v_mfma_f32_16x16x32_bf16 v[2:5], v[170:173], v[236:239], v[2:5]
	v_mfma_f32_16x16x32_bf16 v[6:9], v[204:207], v[236:239], v[6:9]
	v_mfma_f32_16x16x32_bf16 v[50:53], v[200:203], v[216:219], v[50:53]
	v_mfma_f32_16x16x32_bf16 v[54:57], v[208:211], v[216:219], v[54:57]
	v_mfma_f32_16x16x32_bf16 v[34:37], v[200:203], v[224:227], v[34:37]
	v_mfma_f32_16x16x32_bf16 v[38:41], v[208:211], v[224:227], v[38:41]
	v_mfma_f32_16x16x32_bf16 v[18:21], v[200:203], v[232:235], v[18:21]
	v_mfma_f32_16x16x32_bf16 v[22:25], v[208:211], v[232:235], v[22:25]
	s_setprio 2
	s_barrier
	v_mfma_f32_16x16x32_bf16 v[2:5], v[200:203], v[240:243], v[2:5]
	v_mfma_f32_16x16x32_bf16 v[6:9], v[208:211], v[240:243], v[6:9]
	s_setprio 0
	ds_read_b128 v[130:133], v255 offset:33024
	ds_read_b128 v[136:139], v255 offset:34048
	ds_read_b128 v[140:143], v255 offset:35072
	ds_read_b128 v[144:147], v255 offset:36096
	ds_read_b128 v[170:173], v255 offset:49408
	ds_read_b128 v[200:203], v255 offset:50432
	ds_read_b128 v[204:207], v255 offset:51456
	ds_read_b128 v[208:211], v255 offset:52480
	s_add_u32 s4, s84, 0x4000
	s_addc_u32 s5, s85, 0
	s_mov_b32 m0, s86
	ds_read_b128 v[212:215], v194 offset:32768
	ds_read_b128 v[216:219], v194 offset:33792
	ds_read_b128 v[220:223], v194 offset:34816
	ds_read_b128 v[224:227], v194 offset:35840
	ds_read_b128 v[228:231], v194 offset:36864
	ds_read_b128 v[232:235], v194 offset:37888
	ds_read_b128 v[236:239], v194 offset:38912
	ds_read_b128 v[240:243], v194 offset:39936
	global_load_lds_dwordx4 v150, s[4:5] sc1
	s_mov_b32 m0, s87
	s_nop 0
	global_load_lds_dwordx4 v148, s[4:5] sc1
	s_waitcnt vmcnt(8)
	s_waitcnt lgkmcnt(0)
	s_setprio 1
	s_barrier
	v_mfma_f32_16x16x32_bf16 v[122:125], v[130:133], v[212:215], v[122:125]
	v_mfma_f32_16x16x32_bf16 v[126:129], v[140:143], v[212:215], v[126:129]
	v_mfma_f32_16x16x32_bf16 v[106:109], v[130:133], v[220:223], v[106:109]
	v_mfma_f32_16x16x32_bf16 v[110:113], v[140:143], v[220:223], v[110:113]
	v_mfma_f32_16x16x32_bf16 v[90:93], v[130:133], v[228:231], v[90:93]
	v_mfma_f32_16x16x32_bf16 v[94:97], v[140:143], v[228:231], v[94:97]
	v_mfma_f32_16x16x32_bf16 v[74:77], v[130:133], v[236:239], v[74:77]
	v_mfma_f32_16x16x32_bf16 v[78:81], v[140:143], v[236:239], v[78:81]
	v_mfma_f32_16x16x32_bf16 v[122:125], v[136:139], v[216:219], v[122:125]
	v_mfma_f32_16x16x32_bf16 v[126:129], v[144:147], v[216:219], v[126:129]
	v_mfma_f32_16x16x32_bf16 v[106:109], v[136:139], v[224:227], v[106:109]
	v_mfma_f32_16x16x32_bf16 v[110:113], v[144:147], v[224:227], v[110:113]
	v_mfma_f32_16x16x32_bf16 v[90:93], v[136:139], v[232:235], v[90:93]
	v_mfma_f32_16x16x32_bf16 v[94:97], v[144:147], v[232:235], v[94:97]
	v_mfma_f32_16x16x32_bf16 v[74:77], v[136:139], v[240:243], v[74:77]
	v_mfma_f32_16x16x32_bf16 v[78:81], v[144:147], v[240:243], v[78:81]
	v_mfma_f32_16x16x32_bf16 v[114:117], v[170:173], v[212:215], v[114:117]
	v_mfma_f32_16x16x32_bf16 v[118:121], v[204:207], v[212:215], v[118:121]
	v_mfma_f32_16x16x32_bf16 v[98:101], v[170:173], v[220:223], v[98:101]
	v_mfma_f32_16x16x32_bf16 v[102:105], v[204:207], v[220:223], v[102:105]
	v_mfma_f32_16x16x32_bf16 v[82:85], v[170:173], v[228:231], v[82:85]
	v_mfma_f32_16x16x32_bf16 v[86:89], v[204:207], v[228:231], v[86:89]
	v_mfma_f32_16x16x32_bf16 v[66:69], v[170:173], v[236:239], v[66:69]
	v_mfma_f32_16x16x32_bf16 v[70:73], v[204:207], v[236:239], v[70:73]
	v_mfma_f32_16x16x32_bf16 v[114:117], v[200:203], v[216:219], v[114:117]
	v_mfma_f32_16x16x32_bf16 v[118:121], v[208:211], v[216:219], v[118:121]
	v_mfma_f32_16x16x32_bf16 v[98:101], v[200:203], v[224:227], v[98:101]
	v_mfma_f32_16x16x32_bf16 v[102:105], v[208:211], v[224:227], v[102:105]
	v_mfma_f32_16x16x32_bf16 v[82:85], v[200:203], v[232:235], v[82:85]
	v_mfma_f32_16x16x32_bf16 v[86:89], v[208:211], v[232:235], v[86:89]
	s_setprio 2
	s_barrier
	v_mfma_f32_16x16x32_bf16 v[66:69], v[200:203], v[240:243], v[66:69]
	v_mfma_f32_16x16x32_bf16 v[70:73], v[208:211], v[240:243], v[70:73]
	s_setprio 0
	s_add_u32 s4, s64, 0x8000
	s_addc_u32 s5, s65, 0
	s_add_i32 s47, s36, s61
	s_mov_b32 m0, s47
	ds_read_b128 v[212:215], v194 offset:49152
	ds_read_b128 v[216:219], v194 offset:50176
	ds_read_b128 v[220:223], v194 offset:51200
	ds_read_b128 v[224:227], v194 offset:52224
	ds_read_b128 v[228:231], v194 offset:53248
	ds_read_b128 v[232:235], v194 offset:54272
	ds_read_b128 v[236:239], v194 offset:55296
	ds_read_b128 v[240:243], v194 offset:56320
	global_load_lds_dwordx4 v152, s[4:5] sc1
	s_add_i32 m0, s47, 0x2000
	s_nop 0
	global_load_lds_dwordx4 v154, s[4:5] sc1
	s_add_u32 s4, s64, 0xc000
	s_addc_u32 s5, s65, 0
	s_add_i32 s47, s37, s61
	s_mov_b32 m0, s47
	s_nop 0
	global_load_lds_dwordx4 v152, s[4:5] sc1
	s_add_i32 m0, s47, 0x2000
	s_nop 0
	global_load_lds_dwordx4 v154, s[4:5] sc1
	s_mov_b32 m0, s91
	s_nop 0
	global_load_lds_dwordx4 v150, s[56:57] sc1
	s_mov_b32 m0, s92
	s_nop 0
	global_load_lds_dwordx4 v148, s[56:57] sc1
	s_waitcnt vmcnt(8)
	s_waitcnt lgkmcnt(0)
	s_setprio 1
	s_barrier
	v_mfma_f32_16x16x32_bf16 v[58:61], v[130:133], v[212:215], v[58:61]
	v_mfma_f32_16x16x32_bf16 v[62:65], v[140:143], v[212:215], v[62:65]
	v_mfma_f32_16x16x32_bf16 v[42:45], v[130:133], v[220:223], v[42:45]
	v_mfma_f32_16x16x32_bf16 v[46:49], v[140:143], v[220:223], v[46:49]
	v_mfma_f32_16x16x32_bf16 v[26:29], v[130:133], v[228:231], v[26:29]
	v_mfma_f32_16x16x32_bf16 v[30:33], v[140:143], v[228:231], v[30:33]
	v_mfma_f32_16x16x32_bf16 v[10:13], v[130:133], v[236:239], v[10:13]
	v_mfma_f32_16x16x32_bf16 v[14:17], v[140:143], v[236:239], v[14:17]
	v_mfma_f32_16x16x32_bf16 v[58:61], v[136:139], v[216:219], v[58:61]
	v_mfma_f32_16x16x32_bf16 v[62:65], v[144:147], v[216:219], v[62:65]
	v_mfma_f32_16x16x32_bf16 v[42:45], v[136:139], v[224:227], v[42:45]
	v_mfma_f32_16x16x32_bf16 v[46:49], v[144:147], v[224:227], v[46:49]
	v_mfma_f32_16x16x32_bf16 v[26:29], v[136:139], v[232:235], v[26:29]
	v_mfma_f32_16x16x32_bf16 v[30:33], v[144:147], v[232:235], v[30:33]
	v_mfma_f32_16x16x32_bf16 v[10:13], v[136:139], v[240:243], v[10:13]
	v_mfma_f32_16x16x32_bf16 v[14:17], v[144:147], v[240:243], v[14:17]
	v_mfma_f32_16x16x32_bf16 v[50:53], v[170:173], v[212:215], v[50:53]
	v_mfma_f32_16x16x32_bf16 v[54:57], v[204:207], v[212:215], v[54:57]
	v_mfma_f32_16x16x32_bf16 v[34:37], v[170:173], v[220:223], v[34:37]
	v_mfma_f32_16x16x32_bf16 v[38:41], v[204:207], v[220:223], v[38:41]
	v_mfma_f32_16x16x32_bf16 v[18:21], v[170:173], v[228:231], v[18:21]
	v_mfma_f32_16x16x32_bf16 v[22:25], v[204:207], v[228:231], v[22:25]
	v_mfma_f32_16x16x32_bf16 v[2:5], v[170:173], v[236:239], v[2:5]
	v_mfma_f32_16x16x32_bf16 v[6:9], v[204:207], v[236:239], v[6:9]
	v_mfma_f32_16x16x32_bf16 v[50:53], v[200:203], v[216:219], v[50:53]
	v_mfma_f32_16x16x32_bf16 v[54:57], v[208:211], v[216:219], v[54:57]
	v_mfma_f32_16x16x32_bf16 v[34:37], v[200:203], v[224:227], v[34:37]
	v_mfma_f32_16x16x32_bf16 v[38:41], v[208:211], v[224:227], v[38:41]
	v_mfma_f32_16x16x32_bf16 v[18:21], v[200:203], v[232:235], v[18:21]
	v_mfma_f32_16x16x32_bf16 v[22:25], v[208:211], v[232:235], v[22:25]
	s_setprio 2
	s_barrier
	v_mfma_f32_16x16x32_bf16 v[2:5], v[200:203], v[240:243], v[2:5]
	v_mfma_f32_16x16x32_bf16 v[6:9], v[208:211], v[240:243], v[6:9]
	s_setprio 0
	s_add_i32 s46, s46, 2
	s_add_u32 s44, s44, 0x10000
	s_addc_u32 s45, s45, 0
	s_cmp_gt_u32 s46, 13
	s_mov_b64 s[4:5], s[8:9]
	s_cbranch_scc0 .LBB0_460
	s_and_b64 vcc, exec, s[70:71]
	s_cbranch_vccz .LBB0_463
	s_barrier

.LBB0_622:
	s_ashr_i32 s57, s56, 31
	s_lshl_b64 s[62:63], s[56:57], 19
	s_add_u32 s62, s68, s62
	v_readlane_b32 s11, v253, 33
	s_addc_u32 s63, s11, s63
	s_and_b64 s[64:65], s[66:67], exec
	s_cselect_b32 s55, s63, s71
	s_cselect_b32 s57, s62, s70
	s_ashr_i32 s11, s10, 31
	s_lshl_b64 s[64:65], s[10:11], 19
	s_add_u32 s64, s37, s64
	s_addc_u32 s65, s38, s65
	s_and_b64 s[82:83], s[66:67], exec
	s_cselect_b32 s11, s65, s79
	s_cselect_b32 s61, s64, s78
	s_add_u32 s69, s78, 0x10000
	s_addc_u32 s77, s79, 0
	s_mov_b32 s94, -2
	v_add_u32_e32 v255, 0x10000, v142
	ds_read_b128 v[152:155], v255 offset:256
	ds_read_b128 v[156:159], v255 offset:1280
	ds_read_b128 v[162:165], v255 offset:2304
	ds_read_b128 v[166:169], v255 offset:3328
	ds_read_b128 v[170:173], v255 offset:16640
	ds_read_b128 v[174:177], v255 offset:17664
	ds_read_b128 v[178:181], v255 offset:18688
	ds_read_b128 v[182:185], v255 offset:19712
	s_add_u32 s78, s70, 0x10000
	s_addc_u32 s79, s71, 0
	s_cmp_eq_u32 s94, 12
	s_cselect_b32 s92, s57, s78
	s_cselect_b32 s93, s55, s79
	s_cselect_b32 s90, s61, s69
	s_cselect_b32 s91, s11, s77
	s_add_u32 s82, s92, 0x8000
	s_addc_u32 s83, s93, 0
	s_add_i32 m0, s39, 0xc000
	ds_read_b128 v[192:195], v150
	ds_read_b128 v[200:203], v150 offset:1024
	ds_read_b128 v[204:207], v150 offset:2048
	ds_read_b128 v[208:211], v150 offset:3072
	ds_read_b128 v[212:215], v150 offset:4096
	ds_read_b128 v[216:219], v150 offset:5120
	ds_read_b128 v[220:223], v150 offset:6144
	ds_read_b128 v[224:227], v150 offset:7168
	global_load_lds_dwordx4 v138, s[70:71] sc1
	s_add_i32 m0, s39, 0xe000
	s_nop 0
	global_load_lds_dwordx4 v140, s[70:71] sc1
	s_waitcnt vmcnt(8)
	s_waitcnt lgkmcnt(0)
	s_setprio 1
	s_barrier
	v_mfma_f32_16x16x32_bf16 v[98:101], v[152:155], v[192:195], 0
	v_mfma_f32_16x16x32_bf16 v[102:105], v[162:165], v[192:195], 0
	v_mfma_f32_16x16x32_bf16 v[62:65], v[152:155], v[204:207], 0
	v_mfma_f32_16x16x32_bf16 v[78:81], v[162:165], v[204:207], 0
	v_mfma_f32_16x16x32_bf16 v[34:37], v[152:155], v[212:215], 0
	v_mfma_f32_16x16x32_bf16 v[46:49], v[162:165], v[212:215], 0
	v_mfma_f32_16x16x32_bf16 v[14:17], v[152:155], v[220:223], 0
	v_mfma_f32_16x16x32_bf16 v[22:25], v[162:165], v[220:223], 0
	v_mfma_f32_16x16x32_bf16 v[98:101], v[156:159], v[200:203], v[98:101]
	v_mfma_f32_16x16x32_bf16 v[102:105], v[166:169], v[200:203], v[102:105]
	v_mfma_f32_16x16x32_bf16 v[62:65], v[156:159], v[208:211], v[62:65]
	v_mfma_f32_16x16x32_bf16 v[78:81], v[166:169], v[208:211], v[78:81]
	v_mfma_f32_16x16x32_bf16 v[34:37], v[156:159], v[216:219], v[34:37]
	v_mfma_f32_16x16x32_bf16 v[46:49], v[166:169], v[216:219], v[46:49]
	v_mfma_f32_16x16x32_bf16 v[14:17], v[156:159], v[224:227], v[14:17]
	v_mfma_f32_16x16x32_bf16 v[22:25], v[166:169], v[224:227], v[22:25]
	v_mfma_f32_16x16x32_bf16 v[122:125], v[170:173], v[192:195], 0
	v_mfma_f32_16x16x32_bf16 v[126:129], v[178:181], v[192:195], 0
	v_mfma_f32_16x16x32_bf16 v[110:113], v[170:173], v[204:207], 0
	v_mfma_f32_16x16x32_bf16 v[118:121], v[178:181], v[204:207], 0
	v_mfma_f32_16x16x32_bf16 v[86:89], v[170:173], v[212:215], 0
	v_mfma_f32_16x16x32_bf16 v[94:97], v[178:181], v[212:215], 0
	v_mfma_f32_16x16x32_bf16 v[54:57], v[170:173], v[220:223], 0
	v_mfma_f32_16x16x32_bf16 v[70:73], v[178:181], v[220:223], 0
	v_mfma_f32_16x16x32_bf16 v[122:125], v[174:177], v[200:203], v[122:125]
	v_mfma_f32_16x16x32_bf16 v[126:129], v[182:185], v[200:203], v[126:129]
	v_mfma_f32_16x16x32_bf16 v[110:113], v[174:177], v[208:211], v[110:113]
	v_mfma_f32_16x16x32_bf16 v[118:121], v[182:185], v[208:211], v[118:121]
	v_mfma_f32_16x16x32_bf16 v[86:89], v[174:177], v[216:219], v[86:89]
	v_mfma_f32_16x16x32_bf16 v[94:97], v[182:185], v[216:219], v[94:97]
	s_setprio 2
	s_barrier
	v_mfma_f32_16x16x32_bf16 v[54:57], v[174:177], v[224:227], v[54:57]
	v_mfma_f32_16x16x32_bf16 v[70:73], v[182:185], v[224:227], v[70:73]
	s_setprio 0
	s_add_i32 s70, s47, s35
	s_mov_b32 m0, s70
	ds_read_b128 v[192:195], v150 offset:16384
	ds_read_b128 v[200:203], v150 offset:17408
	ds_read_b128 v[204:207], v150 offset:18432
	ds_read_b128 v[208:211], v150 offset:19456
	ds_read_b128 v[212:215], v150 offset:20480
	ds_read_b128 v[216:219], v150 offset:21504
	ds_read_b128 v[220:223], v150 offset:22528
	ds_read_b128 v[224:227], v150 offset:23552
	global_load_lds_dwordx4 v132, s[90:91] sc1
	s_add_i32 m0, s70, 0x2000
	s_add_u32 s70, s90, 0x4000
	s_addc_u32 s71, s91, 0
	s_add_i32 s95, s48, s35
	global_load_lds_dwordx4 v136, s[90:91] sc1
	s_mov_b32 m0, s95
	s_nop 0
	global_load_lds_dwordx4 v132, s[70:71] sc1
	s_add_i32 m0, s95, 0x2000
	s_nop 0
	global_load_lds_dwordx4 v136, s[70:71] sc1
	s_mov_b32 m0, s39
	s_nop 0
	global_load_lds_dwordx4 v130, s[92:93] sc1
	s_mov_b32 m0, s40
	s_nop 0
	global_load_lds_dwordx4 v134, s[92:93] sc1
	s_waitcnt vmcnt(8)
	s_waitcnt lgkmcnt(0)
	s_setprio 1
	s_barrier
	v_mfma_f32_16x16x32_bf16 v[58:61], v[152:155], v[192:195], 0
	v_mfma_f32_16x16x32_bf16 v[74:77], v[162:165], v[192:195], 0
	v_mfma_f32_16x16x32_bf16 v[30:33], v[152:155], v[204:207], 0
	v_mfma_f32_16x16x32_bf16 v[42:45], v[162:165], v[204:207], 0
	v_mfma_f32_16x16x32_bf16 v[10:13], v[152:155], v[212:215], 0
	v_mfma_f32_16x16x32_bf16 v[18:21], v[162:165], v[212:215], 0
	v_mfma_f32_16x16x32_bf16 v[2:5], v[152:155], v[220:223], 0
	v_mfma_f32_16x16x32_bf16 v[6:9], v[162:165], v[220:223], 0
	v_mfma_f32_16x16x32_bf16 v[58:61], v[156:159], v[200:203], v[58:61]
	v_mfma_f32_16x16x32_bf16 v[74:77], v[166:169], v[200:203], v[74:77]
	v_mfma_f32_16x16x32_bf16 v[30:33], v[156:159], v[208:211], v[30:33]
	v_mfma_f32_16x16x32_bf16 v[42:45], v[166:169], v[208:211], v[42:45]
	v_mfma_f32_16x16x32_bf16 v[10:13], v[156:159], v[216:219], v[10:13]
	v_mfma_f32_16x16x32_bf16 v[18:21], v[166:169], v[216:219], v[18:21]
	v_mfma_f32_16x16x32_bf16 v[2:5], v[156:159], v[224:227], v[2:5]
	v_mfma_f32_16x16x32_bf16 v[6:9], v[166:169], v[224:227], v[6:9]
	v_mfma_f32_16x16x32_bf16 v[106:109], v[170:173], v[192:195], 0
	v_mfma_f32_16x16x32_bf16 v[114:117], v[178:181], v[192:195], 0
	v_mfma_f32_16x16x32_bf16 v[82:85], v[170:173], v[204:207], 0
	v_mfma_f32_16x16x32_bf16 v[90:93], v[178:181], v[204:207], 0
	v_mfma_f32_16x16x32_bf16 v[50:53], v[170:173], v[212:215], 0
	v_mfma_f32_16x16x32_bf16 v[66:69], v[178:181], v[212:215], 0
	v_mfma_f32_16x16x32_bf16 v[26:29], v[170:173], v[220:223], 0
	v_mfma_f32_16x16x32_bf16 v[38:41], v[178:181], v[220:223], 0
	v_mfma_f32_16x16x32_bf16 v[106:109], v[174:177], v[200:203], v[106:109]
	v_mfma_f32_16x16x32_bf16 v[114:117], v[182:185], v[200:203], v[114:117]
	v_mfma_f32_16x16x32_bf16 v[82:85], v[174:177], v[208:211], v[82:85]
	v_mfma_f32_16x16x32_bf16 v[90:93], v[182:185], v[208:211], v[90:93]
	v_mfma_f32_16x16x32_bf16 v[50:53], v[174:177], v[216:219], v[50:53]
	v_mfma_f32_16x16x32_bf16 v[66:69], v[182:185], v[216:219], v[66:69]
	s_setprio 2
	s_barrier
	v_mfma_f32_16x16x32_bf16 v[26:29], v[174:177], v[224:227], v[26:29]
	v_mfma_f32_16x16x32_bf16 v[38:41], v[182:185], v[224:227], v[38:41]
	s_setprio 0
	ds_read_b128 v[152:155], v255 offset:33024
	ds_read_b128 v[156:159], v255 offset:34048
	ds_read_b128 v[162:165], v255 offset:35072
	ds_read_b128 v[166:169], v255 offset:36096
	ds_read_b128 v[170:173], v255 offset:49408
	ds_read_b128 v[174:177], v255 offset:50432
	ds_read_b128 v[178:181], v255 offset:51456
	ds_read_b128 v[182:185], v255 offset:52480
	s_add_u32 s70, s92, 0x4000
	s_addc_u32 s71, s93, 0
	s_mov_b32 m0, s41
	ds_read_b128 v[192:195], v150 offset:32768
	ds_read_b128 v[200:203], v150 offset:33792
	ds_read_b128 v[204:207], v150 offset:34816
	ds_read_b128 v[208:211], v150 offset:35840
	ds_read_b128 v[212:215], v150 offset:36864
	ds_read_b128 v[216:219], v150 offset:37888
	ds_read_b128 v[220:223], v150 offset:38912
	ds_read_b128 v[224:227], v150 offset:39936
	global_load_lds_dwordx4 v130, s[70:71] sc1
	s_mov_b32 m0, s42
	s_nop 0
	global_load_lds_dwordx4 v134, s[70:71] sc1
	s_waitcnt vmcnt(8)
	s_waitcnt lgkmcnt(0)
	s_setprio 1
	s_barrier
	v_mfma_f32_16x16x32_bf16 v[98:101], v[152:155], v[192:195], v[98:101]
	v_mfma_f32_16x16x32_bf16 v[102:105], v[162:165], v[192:195], v[102:105]
	v_mfma_f32_16x16x32_bf16 v[62:65], v[152:155], v[204:207], v[62:65]
	v_mfma_f32_16x16x32_bf16 v[78:81], v[162:165], v[204:207], v[78:81]
	v_mfma_f32_16x16x32_bf16 v[34:37], v[152:155], v[212:215], v[34:37]
	v_mfma_f32_16x16x32_bf16 v[46:49], v[162:165], v[212:215], v[46:49]
	v_mfma_f32_16x16x32_bf16 v[14:17], v[152:155], v[220:223], v[14:17]
	v_mfma_f32_16x16x32_bf16 v[22:25], v[162:165], v[220:223], v[22:25]
	v_mfma_f32_16x16x32_bf16 v[98:101], v[156:159], v[200:203], v[98:101]
	v_mfma_f32_16x16x32_bf16 v[102:105], v[166:169], v[200:203], v[102:105]
	v_mfma_f32_16x16x32_bf16 v[62:65], v[156:159], v[208:211], v[62:65]
	v_mfma_f32_16x16x32_bf16 v[78:81], v[166:169], v[208:211], v[78:81]
	v_mfma_f32_16x16x32_bf16 v[34:37], v[156:159], v[216:219], v[34:37]
	v_mfma_f32_16x16x32_bf16 v[46:49], v[166:169], v[216:219], v[46:49]
	v_mfma_f32_16x16x32_bf16 v[14:17], v[156:159], v[224:227], v[14:17]
	v_mfma_f32_16x16x32_bf16 v[22:25], v[166:169], v[224:227], v[22:25]
	v_mfma_f32_16x16x32_bf16 v[122:125], v[170:173], v[192:195], v[122:125]
	v_mfma_f32_16x16x32_bf16 v[126:129], v[178:181], v[192:195], v[126:129]
	v_mfma_f32_16x16x32_bf16 v[110:113], v[170:173], v[204:207], v[110:113]
	v_mfma_f32_16x16x32_bf16 v[118:121], v[178:181], v[204:207], v[118:121]
	v_mfma_f32_16x16x32_bf16 v[86:89], v[170:173], v[212:215], v[86:89]
	v_mfma_f32_16x16x32_bf16 v[94:97], v[178:181], v[212:215], v[94:97]
	v_mfma_f32_16x16x32_bf16 v[54:57], v[170:173], v[220:223], v[54:57]
	v_mfma_f32_16x16x32_bf16 v[70:73], v[178:181], v[220:223], v[70:73]
	v_mfma_f32_16x16x32_bf16 v[122:125], v[174:177], v[200:203], v[122:125]
	v_mfma_f32_16x16x32_bf16 v[126:129], v[182:185], v[200:203], v[126:129]
	v_mfma_f32_16x16x32_bf16 v[110:113], v[174:177], v[208:211], v[110:113]
	v_mfma_f32_16x16x32_bf16 v[118:121], v[182:185], v[208:211], v[118:121]
	v_mfma_f32_16x16x32_bf16 v[86:89], v[174:177], v[216:219], v[86:89]
	v_mfma_f32_16x16x32_bf16 v[94:97], v[182:185], v[216:219], v[94:97]
	s_setprio 2
	s_barrier
	v_mfma_f32_16x16x32_bf16 v[54:57], v[174:177], v[224:227], v[54:57]
	v_mfma_f32_16x16x32_bf16 v[70:73], v[182:185], v[224:227], v[70:73]
	s_setprio 0
	s_add_u32 s70, s90, 0x8000
	s_addc_u32 s71, s91, 0
	s_add_i32 s92, s49, s35
	s_mov_b32 m0, s92
	ds_read_b128 v[192:195], v150 offset:49152
	ds_read_b128 v[200:203], v150 offset:50176
	ds_read_b128 v[204:207], v150 offset:51200
	ds_read_b128 v[208:211], v150 offset:52224
	ds_read_b128 v[212:215], v150 offset:53248
	ds_read_b128 v[216:219], v150 offset:54272
	ds_read_b128 v[220:223], v150 offset:55296
	ds_read_b128 v[224:227], v150 offset:56320
	global_load_lds_dwordx4 v132, s[70:71] sc1
	s_add_i32 m0, s92, 0x2000
	s_nop 0
	global_load_lds_dwordx4 v136, s[70:71] sc1
	s_add_u32 s70, s90, 0xc000
	s_addc_u32 s71, s91, 0
	s_add_i32 s90, s50, s35
	s_mov_b32 m0, s90
	s_nop 0
	global_load_lds_dwordx4 v132, s[70:71] sc1
	s_add_i32 m0, s90, 0x2000
	s_nop 0
	global_load_lds_dwordx4 v136, s[70:71] sc1
	s_mov_b32 m0, s44
	s_nop 0
	global_load_lds_dwordx4 v130, s[82:83] sc1
	s_mov_b32 m0, s45
	s_nop 0
	global_load_lds_dwordx4 v134, s[82:83] sc1
	s_waitcnt vmcnt(8)
	s_waitcnt lgkmcnt(0)
	s_setprio 1
	s_barrier
	v_mfma_f32_16x16x32_bf16 v[58:61], v[152:155], v[192:195], v[58:61]
	v_mfma_f32_16x16x32_bf16 v[74:77], v[162:165], v[192:195], v[74:77]
	v_mfma_f32_16x16x32_bf16 v[30:33], v[152:155], v[204:207], v[30:33]
	v_mfma_f32_16x16x32_bf16 v[42:45], v[162:165], v[204:207], v[42:45]
	v_mfma_f32_16x16x32_bf16 v[10:13], v[152:155], v[212:215], v[10:13]
	v_mfma_f32_16x16x32_bf16 v[18:21], v[162:165], v[212:215], v[18:21]
	v_mfma_f32_16x16x32_bf16 v[2:5], v[152:155], v[220:223], v[2:5]
	v_mfma_f32_16x16x32_bf16 v[6:9], v[162:165], v[220:223], v[6:9]
	v_mfma_f32_16x16x32_bf16 v[58:61], v[156:159], v[200:203], v[58:61]
	v_mfma_f32_16x16x32_bf16 v[74:77], v[166:169], v[200:203], v[74:77]
	v_mfma_f32_16x16x32_bf16 v[30:33], v[156:159], v[208:211], v[30:33]
	v_mfma_f32_16x16x32_bf16 v[42:45], v[166:169], v[208:211], v[42:45]
	v_mfma_f32_16x16x32_bf16 v[10:13], v[156:159], v[216:219], v[10:13]
	v_mfma_f32_16x16x32_bf16 v[18:21], v[166:169], v[216:219], v[18:21]
	v_mfma_f32_16x16x32_bf16 v[2:5], v[156:159], v[224:227], v[2:5]
	v_mfma_f32_16x16x32_bf16 v[6:9], v[166:169], v[224:227], v[6:9]
	v_mfma_f32_16x16x32_bf16 v[106:109], v[170:173], v[192:195], v[106:109]
	v_mfma_f32_16x16x32_bf16 v[114:117], v[178:181], v[192:195], v[114:117]
	v_mfma_f32_16x16x32_bf16 v[82:85], v[170:173], v[204:207], v[82:85]
	v_mfma_f32_16x16x32_bf16 v[90:93], v[178:181], v[204:207], v[90:93]
	v_mfma_f32_16x16x32_bf16 v[50:53], v[170:173], v[212:215], v[50:53]
	v_mfma_f32_16x16x32_bf16 v[66:69], v[178:181], v[212:215], v[66:69]
	v_mfma_f32_16x16x32_bf16 v[26:29], v[170:173], v[220:223], v[26:29]
	v_mfma_f32_16x16x32_bf16 v[38:41], v[178:181], v[220:223], v[38:41]
	v_mfma_f32_16x16x32_bf16 v[106:109], v[174:177], v[200:203], v[106:109]
	v_mfma_f32_16x16x32_bf16 v[114:117], v[182:185], v[200:203], v[114:117]
	v_mfma_f32_16x16x32_bf16 v[82:85], v[174:177], v[208:211], v[82:85]
	v_mfma_f32_16x16x32_bf16 v[90:93], v[182:185], v[208:211], v[90:93]
	v_mfma_f32_16x16x32_bf16 v[50:53], v[174:177], v[216:219], v[50:53]
	v_mfma_f32_16x16x32_bf16 v[66:69], v[182:185], v[216:219], v[66:69]
	s_setprio 2
	s_barrier
	v_mfma_f32_16x16x32_bf16 v[26:29], v[174:177], v[224:227], v[26:29]
	v_mfma_f32_16x16x32_bf16 v[38:41], v[182:185], v[224:227], v[38:41]
	s_setprio 0
	s_add_i32 s94, s94, 2
	s_add_u32 s69, s69, 0x10000
	s_addc_u32 s77, s77, 0
	s_cmp_gt_u32 s94, 13
	s_mov_b64 s[70:71], s[78:79]
.LBB0_623:
	ds_read_b128 v[152:155], v255 offset:256
	ds_read_b128 v[156:159], v255 offset:1280
	ds_read_b128 v[162:165], v255 offset:2304
	ds_read_b128 v[166:169], v255 offset:3328
	ds_read_b128 v[170:173], v255 offset:16640
	ds_read_b128 v[174:177], v255 offset:17664
	ds_read_b128 v[178:181], v255 offset:18688
	ds_read_b128 v[182:185], v255 offset:19712
	s_add_u32 s78, s70, 0x10000
	s_addc_u32 s79, s71, 0
	s_cmp_eq_u32 s94, 12
	s_cselect_b32 s92, s57, s78
	s_cselect_b32 s93, s55, s79
	s_cselect_b32 s90, s61, s69
	s_cselect_b32 s91, s11, s77
	s_add_u32 s82, s92, 0x8000
	s_addc_u32 s83, s93, 0
	s_add_i32 m0, s39, 0xc000
	ds_read_b128 v[192:195], v150
	ds_read_b128 v[200:203], v150 offset:1024
	ds_read_b128 v[204:207], v150 offset:2048
	ds_read_b128 v[208:211], v150 offset:3072
	ds_read_b128 v[212:215], v150 offset:4096
	ds_read_b128 v[216:219], v150 offset:5120
	ds_read_b128 v[220:223], v150 offset:6144
	ds_read_b128 v[224:227], v150 offset:7168
	global_load_lds_dwordx4 v138, s[70:71] sc1
	s_add_i32 m0, s39, 0xe000
	s_nop 0
	global_load_lds_dwordx4 v140, s[70:71] sc1
	s_waitcnt vmcnt(8)
	s_waitcnt lgkmcnt(0)
	s_setprio 1
	s_barrier
	v_mfma_f32_16x16x32_bf16 v[98:101], v[152:155], v[192:195], v[98:101]
	v_mfma_f32_16x16x32_bf16 v[102:105], v[162:165], v[192:195], v[102:105]
	v_mfma_f32_16x16x32_bf16 v[62:65], v[152:155], v[204:207], v[62:65]
	v_mfma_f32_16x16x32_bf16 v[78:81], v[162:165], v[204:207], v[78:81]
	v_mfma_f32_16x16x32_bf16 v[34:37], v[152:155], v[212:215], v[34:37]
	v_mfma_f32_16x16x32_bf16 v[46:49], v[162:165], v[212:215], v[46:49]
	v_mfma_f32_16x16x32_bf16 v[14:17], v[152:155], v[220:223], v[14:17]
	v_mfma_f32_16x16x32_bf16 v[22:25], v[162:165], v[220:223], v[22:25]
	v_mfma_f32_16x16x32_bf16 v[98:101], v[156:159], v[200:203], v[98:101]
	v_mfma_f32_16x16x32_bf16 v[102:105], v[166:169], v[200:203], v[102:105]
	v_mfma_f32_16x16x32_bf16 v[62:65], v[156:159], v[208:211], v[62:65]
	v_mfma_f32_16x16x32_bf16 v[78:81], v[166:169], v[208:211], v[78:81]
	v_mfma_f32_16x16x32_bf16 v[34:37], v[156:159], v[216:219], v[34:37]
	v_mfma_f32_16x16x32_bf16 v[46:49], v[166:169], v[216:219], v[46:49]
	v_mfma_f32_16x16x32_bf16 v[14:17], v[156:159], v[224:227], v[14:17]
	v_mfma_f32_16x16x32_bf16 v[22:25], v[166:169], v[224:227], v[22:25]
	v_mfma_f32_16x16x32_bf16 v[122:125], v[170:173], v[192:195], v[122:125]
	v_mfma_f32_16x16x32_bf16 v[126:129], v[178:181], v[192:195], v[126:129]
	v_mfma_f32_16x16x32_bf16 v[110:113], v[170:173], v[204:207], v[110:113]
	v_mfma_f32_16x16x32_bf16 v[118:121], v[178:181], v[204:207], v[118:121]
	v_mfma_f32_16x16x32_bf16 v[86:89], v[170:173], v[212:215], v[86:89]
	v_mfma_f32_16x16x32_bf16 v[94:97], v[178:181], v[212:215], v[94:97]
	v_mfma_f32_16x16x32_bf16 v[54:57], v[170:173], v[220:223], v[54:57]
	v_mfma_f32_16x16x32_bf16 v[70:73], v[178:181], v[220:223], v[70:73]
	v_mfma_f32_16x16x32_bf16 v[122:125], v[174:177], v[200:203], v[122:125]
	v_mfma_f32_16x16x32_bf16 v[126:129], v[182:185], v[200:203], v[126:129]
	v_mfma_f32_16x16x32_bf16 v[110:113], v[174:177], v[208:211], v[110:113]
	v_mfma_f32_16x16x32_bf16 v[118:121], v[182:185], v[208:211], v[118:121]
	v_mfma_f32_16x16x32_bf16 v[86:89], v[174:177], v[216:219], v[86:89]
	v_mfma_f32_16x16x32_bf16 v[94:97], v[182:185], v[216:219], v[94:97]
	s_setprio 2
	s_barrier
	v_mfma_f32_16x16x32_bf16 v[54:57], v[174:177], v[224:227], v[54:57]
	v_mfma_f32_16x16x32_bf16 v[70:73], v[182:185], v[224:227], v[70:73]
	s_setprio 0
	s_add_i32 s70, s47, s35
	s_mov_b32 m0, s70
	ds_read_b128 v[192:195], v150 offset:16384
	ds_read_b128 v[200:203], v150 offset:17408
	ds_read_b128 v[204:207], v150 offset:18432
	ds_read_b128 v[208:211], v150 offset:19456
	ds_read_b128 v[212:215], v150 offset:20480
	ds_read_b128 v[216:219], v150 offset:21504
	ds_read_b128 v[220:223], v150 offset:22528
	ds_read_b128 v[224:227], v150 offset:23552
	global_load_lds_dwordx4 v132, s[90:91] sc1
	s_add_i32 m0, s70, 0x2000
	s_add_u32 s70, s90, 0x4000
	s_addc_u32 s71, s91, 0
	s_add_i32 s95, s48, s35
	global_load_lds_dwordx4 v136, s[90:91] sc1
	s_mov_b32 m0, s95
	s_nop 0
	global_load_lds_dwordx4 v132, s[70:71] sc1
	s_add_i32 m0, s95, 0x2000
	s_nop 0
	global_load_lds_dwordx4 v136, s[70:71] sc1
	s_mov_b32 m0, s39
	s_nop 0
	global_load_lds_dwordx4 v130, s[92:93] sc1
	s_mov_b32 m0, s40
	s_nop 0
	global_load_lds_dwordx4 v134, s[92:93] sc1
	s_waitcnt vmcnt(8)
	s_waitcnt lgkmcnt(0)
	s_setprio 1
	s_barrier
	v_mfma_f32_16x16x32_bf16 v[58:61], v[152:155], v[192:195], v[58:61]
	v_mfma_f32_16x16x32_bf16 v[74:77], v[162:165], v[192:195], v[74:77]
	v_mfma_f32_16x16x32_bf16 v[30:33], v[152:155], v[204:207], v[30:33]
	v_mfma_f32_16x16x32_bf16 v[42:45], v[162:165], v[204:207], v[42:45]
	v_mfma_f32_16x16x32_bf16 v[10:13], v[152:155], v[212:215], v[10:13]
	v_mfma_f32_16x16x32_bf16 v[18:21], v[162:165], v[212:215], v[18:21]
	v_mfma_f32_16x16x32_bf16 v[2:5], v[152:155], v[220:223], v[2:5]
	v_mfma_f32_16x16x32_bf16 v[6:9], v[162:165], v[220:223], v[6:9]
	v_mfma_f32_16x16x32_bf16 v[58:61], v[156:159], v[200:203], v[58:61]
	v_mfma_f32_16x16x32_bf16 v[74:77], v[166:169], v[200:203], v[74:77]
	v_mfma_f32_16x16x32_bf16 v[30:33], v[156:159], v[208:211], v[30:33]
	v_mfma_f32_16x16x32_bf16 v[42:45], v[166:169], v[208:211], v[42:45]
	v_mfma_f32_16x16x32_bf16 v[10:13], v[156:159], v[216:219], v[10:13]
	v_mfma_f32_16x16x32_bf16 v[18:21], v[166:169], v[216:219], v[18:21]
	v_mfma_f32_16x16x32_bf16 v[2:5], v[156:159], v[224:227], v[2:5]
	v_mfma_f32_16x16x32_bf16 v[6:9], v[166:169], v[224:227], v[6:9]
	v_mfma_f32_16x16x32_bf16 v[106:109], v[170:173], v[192:195], v[106:109]
	v_mfma_f32_16x16x32_bf16 v[114:117], v[178:181], v[192:195], v[114:117]
	v_mfma_f32_16x16x32_bf16 v[82:85], v[170:173], v[204:207], v[82:85]
	v_mfma_f32_16x16x32_bf16 v[90:93], v[178:181], v[204:207], v[90:93]
	v_mfma_f32_16x16x32_bf16 v[50:53], v[170:173], v[212:215], v[50:53]
	v_mfma_f32_16x16x32_bf16 v[66:69], v[178:181], v[212:215], v[66:69]
	v_mfma_f32_16x16x32_bf16 v[26:29], v[170:173], v[220:223], v[26:29]
	v_mfma_f32_16x16x32_bf16 v[38:41], v[178:181], v[220:223], v[38:41]
	v_mfma_f32_16x16x32_bf16 v[106:109], v[174:177], v[200:203], v[106:109]
	v_mfma_f32_16x16x32_bf16 v[114:117], v[182:185], v[200:203], v[114:117]
	v_mfma_f32_16x16x32_bf16 v[82:85], v[174:177], v[208:211], v[82:85]
	v_mfma_f32_16x16x32_bf16 v[90:93], v[182:185], v[208:211], v[90:93]
	v_mfma_f32_16x16x32_bf16 v[50:53], v[174:177], v[216:219], v[50:53]
	v_mfma_f32_16x16x32_bf16 v[66:69], v[182:185], v[216:219], v[66:69]
	s_setprio 2
	s_barrier
	v_mfma_f32_16x16x32_bf16 v[26:29], v[174:177], v[224:227], v[26:29]
	v_mfma_f32_16x16x32_bf16 v[38:41], v[182:185], v[224:227], v[38:41]
	s_setprio 0
	ds_read_b128 v[152:155], v255 offset:33024
	ds_read_b128 v[156:159], v255 offset:34048
	ds_read_b128 v[162:165], v255 offset:35072
	ds_read_b128 v[166:169], v255 offset:36096
	ds_read_b128 v[170:173], v255 offset:49408
	ds_read_b128 v[174:177], v255 offset:50432
	ds_read_b128 v[178:181], v255 offset:51456
	ds_read_b128 v[182:185], v255 offset:52480
	s_add_u32 s70, s92, 0x4000
	s_addc_u32 s71, s93, 0
	s_mov_b32 m0, s41
	ds_read_b128 v[192:195], v150 offset:32768
	ds_read_b128 v[200:203], v150 offset:33792
	ds_read_b128 v[204:207], v150 offset:34816
	ds_read_b128 v[208:211], v150 offset:35840
	ds_read_b128 v[212:215], v150 offset:36864
	ds_read_b128 v[216:219], v150 offset:37888
	ds_read_b128 v[220:223], v150 offset:38912
	ds_read_b128 v[224:227], v150 offset:39936
	global_load_lds_dwordx4 v130, s[70:71] sc1
	s_mov_b32 m0, s42
	s_nop 0
	global_load_lds_dwordx4 v134, s[70:71] sc1
	s_waitcnt vmcnt(8)
	s_waitcnt lgkmcnt(0)
	s_setprio 1
	s_barrier
	v_mfma_f32_16x16x32_bf16 v[98:101], v[152:155], v[192:195], v[98:101]
	v_mfma_f32_16x16x32_bf16 v[102:105], v[162:165], v[192:195], v[102:105]
	v_mfma_f32_16x16x32_bf16 v[62:65], v[152:155], v[204:207], v[62:65]
	v_mfma_f32_16x16x32_bf16 v[78:81], v[162:165], v[204:207], v[78:81]
	v_mfma_f32_16x16x32_bf16 v[34:37], v[152:155], v[212:215], v[34:37]
	v_mfma_f32_16x16x32_bf16 v[46:49], v[162:165], v[212:215], v[46:49]
	v_mfma_f32_16x16x32_bf16 v[14:17], v[152:155], v[220:223], v[14:17]
	v_mfma_f32_16x16x32_bf16 v[22:25], v[162:165], v[220:223], v[22:25]
	v_mfma_f32_16x16x32_bf16 v[98:101], v[156:159], v[200:203], v[98:101]
	v_mfma_f32_16x16x32_bf16 v[102:105], v[166:169], v[200:203], v[102:105]
	v_mfma_f32_16x16x32_bf16 v[62:65], v[156:159], v[208:211], v[62:65]
	v_mfma_f32_16x16x32_bf16 v[78:81], v[166:169], v[208:211], v[78:81]
	v_mfma_f32_16x16x32_bf16 v[34:37], v[156:159], v[216:219], v[34:37]
	v_mfma_f32_16x16x32_bf16 v[46:49], v[166:169], v[216:219], v[46:49]
	v_mfma_f32_16x16x32_bf16 v[14:17], v[156:159], v[224:227], v[14:17]
	v_mfma_f32_16x16x32_bf16 v[22:25], v[166:169], v[224:227], v[22:25]
	v_mfma_f32_16x16x32_bf16 v[122:125], v[170:173], v[192:195], v[122:125]
	v_mfma_f32_16x16x32_bf16 v[126:129], v[178:181], v[192:195], v[126:129]
	v_mfma_f32_16x16x32_bf16 v[110:113], v[170:173], v[204:207], v[110:113]
	v_mfma_f32_16x16x32_bf16 v[118:121], v[178:181], v[204:207], v[118:121]
	v_mfma_f32_16x16x32_bf16 v[86:89], v[170:173], v[212:215], v[86:89]
	v_mfma_f32_16x16x32_bf16 v[94:97], v[178:181], v[212:215], v[94:97]
	v_mfma_f32_16x16x32_bf16 v[54:57], v[170:173], v[220:223], v[54:57]
	v_mfma_f32_16x16x32_bf16 v[70:73], v[178:181], v[220:223], v[70:73]
	v_mfma_f32_16x16x32_bf16 v[122:125], v[174:177], v[200:203], v[122:125]
	v_mfma_f32_16x16x32_bf16 v[126:129], v[182:185], v[200:203], v[126:129]
	v_mfma_f32_16x16x32_bf16 v[110:113], v[174:177], v[208:211], v[110:113]
	v_mfma_f32_16x16x32_bf16 v[118:121], v[182:185], v[208:211], v[118:121]
	v_mfma_f32_16x16x32_bf16 v[86:89], v[174:177], v[216:219], v[86:89]
	v_mfma_f32_16x16x32_bf16 v[94:97], v[182:185], v[216:219], v[94:97]
	s_setprio 2
	s_barrier
	v_mfma_f32_16x16x32_bf16 v[54:57], v[174:177], v[224:227], v[54:57]
	v_mfma_f32_16x16x32_bf16 v[70:73], v[182:185], v[224:227], v[70:73]
	s_setprio 0
	s_add_u32 s70, s90, 0x8000
	s_addc_u32 s71, s91, 0
	s_add_i32 s92, s49, s35
	s_mov_b32 m0, s92
	ds_read_b128 v[192:195], v150 offset:49152
	ds_read_b128 v[200:203], v150 offset:50176
	ds_read_b128 v[204:207], v150 offset:51200
	ds_read_b128 v[208:211], v150 offset:52224
	ds_read_b128 v[212:215], v150 offset:53248
	ds_read_b128 v[216:219], v150 offset:54272
	ds_read_b128 v[220:223], v150 offset:55296
	ds_read_b128 v[224:227], v150 offset:56320
	global_load_lds_dwordx4 v132, s[70:71] sc1
	s_add_i32 m0, s92, 0x2000
	s_nop 0
	global_load_lds_dwordx4 v136, s[70:71] sc1
	s_add_u32 s70, s90, 0xc000
	s_addc_u32 s71, s91, 0
	s_add_i32 s90, s50, s35
	s_mov_b32 m0, s90
	s_nop 0
	global_load_lds_dwordx4 v132, s[70:71] sc1
	s_add_i32 m0, s90, 0x2000
	s_nop 0
	global_load_lds_dwordx4 v136, s[70:71] sc1
	s_mov_b32 m0, s44
	s_nop 0
	global_load_lds_dwordx4 v130, s[82:83] sc1
	s_mov_b32 m0, s45
	s_nop 0
	global_load_lds_dwordx4 v134, s[82:83] sc1
	s_waitcnt vmcnt(8)
	s_waitcnt lgkmcnt(0)
	s_setprio 1
	s_barrier
	v_mfma_f32_16x16x32_bf16 v[58:61], v[152:155], v[192:195], v[58:61]
	v_mfma_f32_16x16x32_bf16 v[74:77], v[162:165], v[192:195], v[74:77]
	v_mfma_f32_16x16x32_bf16 v[30:33], v[152:155], v[204:207], v[30:33]
	v_mfma_f32_16x16x32_bf16 v[42:45], v[162:165], v[204:207], v[42:45]
	v_mfma_f32_16x16x32_bf16 v[10:13], v[152:155], v[212:215], v[10:13]
	v_mfma_f32_16x16x32_bf16 v[18:21], v[162:165], v[212:215], v[18:21]
	v_mfma_f32_16x16x32_bf16 v[2:5], v[152:155], v[220:223], v[2:5]
	v_mfma_f32_16x16x32_bf16 v[6:9], v[162:165], v[220:223], v[6:9]
	v_mfma_f32_16x16x32_bf16 v[58:61], v[156:159], v[200:203], v[58:61]
	v_mfma_f32_16x16x32_bf16 v[74:77], v[166:169], v[200:203], v[74:77]
	v_mfma_f32_16x16x32_bf16 v[30:33], v[156:159], v[208:211], v[30:33]
	v_mfma_f32_16x16x32_bf16 v[42:45], v[166:169], v[208:211], v[42:45]
	v_mfma_f32_16x16x32_bf16 v[10:13], v[156:159], v[216:219], v[10:13]
	v_mfma_f32_16x16x32_bf16 v[18:21], v[166:169], v[216:219], v[18:21]
	v_mfma_f32_16x16x32_bf16 v[2:5], v[156:159], v[224:227], v[2:5]
	v_mfma_f32_16x16x32_bf16 v[6:9], v[166:169], v[224:227], v[6:9]
	v_mfma_f32_16x16x32_bf16 v[106:109], v[170:173], v[192:195], v[106:109]
	v_mfma_f32_16x16x32_bf16 v[114:117], v[178:181], v[192:195], v[114:117]
	v_mfma_f32_16x16x32_bf16 v[82:85], v[170:173], v[204:207], v[82:85]
	v_mfma_f32_16x16x32_bf16 v[90:93], v[178:181], v[204:207], v[90:93]
	v_mfma_f32_16x16x32_bf16 v[50:53], v[170:173], v[212:215], v[50:53]
	v_mfma_f32_16x16x32_bf16 v[66:69], v[178:181], v[212:215], v[66:69]
	v_mfma_f32_16x16x32_bf16 v[26:29], v[170:173], v[220:223], v[26:29]
	v_mfma_f32_16x16x32_bf16 v[38:41], v[178:181], v[220:223], v[38:41]
	v_mfma_f32_16x16x32_bf16 v[106:109], v[174:177], v[200:203], v[106:109]
	v_mfma_f32_16x16x32_bf16 v[114:117], v[182:185], v[200:203], v[114:117]
	v_mfma_f32_16x16x32_bf16 v[82:85], v[174:177], v[208:211], v[82:85]
	v_mfma_f32_16x16x32_bf16 v[90:93], v[182:185], v[208:211], v[90:93]
	v_mfma_f32_16x16x32_bf16 v[50:53], v[174:177], v[216:219], v[50:53]
	v_mfma_f32_16x16x32_bf16 v[66:69], v[182:185], v[216:219], v[66:69]
	s_setprio 2
	s_barrier
	v_mfma_f32_16x16x32_bf16 v[26:29], v[174:177], v[224:227], v[26:29]
	v_mfma_f32_16x16x32_bf16 v[38:41], v[182:185], v[224:227], v[38:41]
	s_setprio 0
	s_add_i32 s94, s94, 2
	s_add_u32 s69, s69, 0x10000
	s_addc_u32 s77, s77, 0
	s_cmp_gt_u32 s94, 13
	s_mov_b64 s[70:71], s[78:79]
	s_cbranch_scc0 .LBB0_623
	s_and_b64 vcc, exec, s[8:9]
	s_cbranch_vccz .LBB0_626
	s_barrier

.LBB0_883:
	s_add_u32 s69, s30, 0x10000
	s_addc_u32 s80, s31, 0
	s_ashr_i32 s57, s56, 31
	v_readlane_b32 s64, v253, 0
	s_lshl_b64 s[30:31], s[56:57], 20
	v_readlane_b32 s66, v253, 2
	v_readlane_b32 s67, v253, 3
	s_add_u32 s62, s66, s30
	s_addc_u32 s63, s67, s31
	s_ashr_i32 s41, s40, 31
	s_lshl_b64 s[30:31], s[40:41], 19
	s_add_u32 s30, s28, s30
	v_readlane_b32 s65, v253, 1
	s_addc_u32 s31, s29, s31
	s_lshl_b32 s64, s10, 2
	s_ashr_i32 s19, s18, 31
	s_ashr_i32 s65, s64, 31
	s_lshl_b64 s[66:67], s[18:19], 19
	s_lshl_b64 s[64:65], s[64:65], 15
	s_add_u32 s19, s60, s64
	s_addc_u32 s41, s33, s65
	s_add_u32 s19, s19, s66
	s_addc_u32 s41, s41, s67
	s_add_u32 s66, s19, 0x10000
	s_addc_u32 s57, s41, 0
	s_and_b64 s[64:65], s[8:9], exec
	s_cselect_b32 s57, s63, s57
	s_cselect_b32 s81, s62, s66
	s_cselect_b32 s85, s31, s41
	s_cselect_b32 s86, s30, s19
	v_lshl_add_u64 v[144:145], s[38:39], 0, v[136:137]
	v_lshl_add_u64 v[146:147], s[38:39], 0, v[138:139]
	s_mov_b32 s87, -2
	s_mov_b64 s[64:65], 0
	v_add_u32_e32 v255, 0x10000, v151
	s_add_u32 s19, s38, s64
	s_addc_u32 s41, s39, s65
	s_add_u32 s19, s19, 0x10000
	ds_read_b128 v[156:159], v255 offset:256
	ds_read_b128 v[160:163], v255 offset:1280
	ds_read_b128 v[164:167], v255 offset:2304
	ds_read_b128 v[168:171], v255 offset:3328
	ds_read_b128 v[172:175], v255 offset:16640
	ds_read_b128 v[176:179], v255 offset:17664
	ds_read_b128 v[180:183], v255 offset:18688
	ds_read_b128 v[184:187], v255 offset:19712
	s_addc_u32 s41, s41, 0
	s_add_u32 s66, s69, s64
	s_addc_u32 s67, s80, s65
	s_cmp_eq_u32 s64, 0x70000
	s_cselect_b32 s78, s81, s19
	s_cselect_b32 s79, s57, s41
	s_cselect_b32 s70, s86, s66
	s_cselect_b32 s71, s85, s67
	s_add_u32 s66, s78, 0x8000
	s_addc_u32 s67, s79, 0
	s_add_i32 s19, s37, 0xc000
	s_add_u32 s98, s38, s64
	s_addc_u32 s99, s39, s65
	s_mov_b32 m0, s19
	s_add_i32 s41, s37, 0xe000
	ds_read_b128 v[192:195], v154
	ds_read_b128 v[200:203], v154 offset:1024
	ds_read_b128 v[204:207], v154 offset:2048
	ds_read_b128 v[208:211], v154 offset:3072
	ds_read_b128 v[212:215], v154 offset:4096
	ds_read_b128 v[216:219], v154 offset:5120
	ds_read_b128 v[220:223], v154 offset:6144
	ds_read_b128 v[224:227], v154 offset:7168
	global_load_lds_dwordx4 v136, s[98:99] sc1
	s_mov_b32 m0, s41
	s_nop 0
	global_load_lds_dwordx4 v138, s[98:99] sc1
	s_waitcnt vmcnt(8)
	s_waitcnt lgkmcnt(0)
	s_setprio 1
	s_barrier
	v_mfma_f32_16x16x32_bf16 v[112:115], v[156:159], v[192:195], 0
	v_mfma_f32_16x16x32_bf16 v[116:119], v[164:167], v[192:195], 0
	v_mfma_f32_16x16x32_bf16 v[96:99], v[156:159], v[204:207], 0
	v_mfma_f32_16x16x32_bf16 v[100:103], v[164:167], v[204:207], 0
	v_mfma_f32_16x16x32_bf16 v[80:83], v[156:159], v[212:215], 0
	v_mfma_f32_16x16x32_bf16 v[84:87], v[164:167], v[212:215], 0
	v_mfma_f32_16x16x32_bf16 v[64:67], v[156:159], v[220:223], 0
	v_mfma_f32_16x16x32_bf16 v[68:71], v[164:167], v[220:223], 0
	v_mfma_f32_16x16x32_bf16 v[112:115], v[160:163], v[200:203], v[112:115]
	v_mfma_f32_16x16x32_bf16 v[116:119], v[168:171], v[200:203], v[116:119]
	v_mfma_f32_16x16x32_bf16 v[96:99], v[160:163], v[208:211], v[96:99]
	v_mfma_f32_16x16x32_bf16 v[100:103], v[168:171], v[208:211], v[100:103]
	v_mfma_f32_16x16x32_bf16 v[80:83], v[160:163], v[216:219], v[80:83]
	v_mfma_f32_16x16x32_bf16 v[84:87], v[168:171], v[216:219], v[84:87]
	v_mfma_f32_16x16x32_bf16 v[64:67], v[160:163], v[224:227], v[64:67]
	v_mfma_f32_16x16x32_bf16 v[68:71], v[168:171], v[224:227], v[68:71]
	v_mfma_f32_16x16x32_bf16 v[120:123], v[172:175], v[192:195], 0
	v_mfma_f32_16x16x32_bf16 v[124:127], v[180:183], v[192:195], 0
	v_mfma_f32_16x16x32_bf16 v[104:107], v[172:175], v[204:207], 0
	v_mfma_f32_16x16x32_bf16 v[108:111], v[180:183], v[204:207], 0
	v_mfma_f32_16x16x32_bf16 v[88:91], v[172:175], v[212:215], 0
	v_mfma_f32_16x16x32_bf16 v[92:95], v[180:183], v[212:215], 0
	v_mfma_f32_16x16x32_bf16 v[72:75], v[172:175], v[220:223], 0
	v_mfma_f32_16x16x32_bf16 v[76:79], v[180:183], v[220:223], 0
	v_mfma_f32_16x16x32_bf16 v[120:123], v[176:179], v[200:203], v[120:123]
	v_mfma_f32_16x16x32_bf16 v[124:127], v[184:187], v[200:203], v[124:127]
	v_mfma_f32_16x16x32_bf16 v[104:107], v[176:179], v[208:211], v[104:107]
	v_mfma_f32_16x16x32_bf16 v[108:111], v[184:187], v[208:211], v[108:111]
	v_mfma_f32_16x16x32_bf16 v[88:91], v[176:179], v[216:219], v[88:91]
	v_mfma_f32_16x16x32_bf16 v[92:95], v[184:187], v[216:219], v[92:95]
	s_setprio 2
	s_barrier
	v_mfma_f32_16x16x32_bf16 v[72:75], v[176:179], v[224:227], v[72:75]
	v_mfma_f32_16x16x32_bf16 v[76:79], v[184:187], v[224:227], v[76:79]
	s_setprio 0
	s_add_i32 s88, s49, s35
	s_mov_b32 m0, s88
	ds_read_b128 v[192:195], v154 offset:16384
	ds_read_b128 v[200:203], v154 offset:17408
	ds_read_b128 v[204:207], v154 offset:18432
	ds_read_b128 v[208:211], v154 offset:19456
	ds_read_b128 v[212:215], v154 offset:20480
	ds_read_b128 v[216:219], v154 offset:21504
	ds_read_b128 v[220:223], v154 offset:22528
	ds_read_b128 v[224:227], v154 offset:23552
	global_load_lds_dwordx4 v130, s[70:71] sc1
	s_add_i32 m0, s88, 0x2000
	s_add_u32 s88, s70, 0x4000
	s_addc_u32 s89, s71, 0
	s_add_i32 s90, s51, s35
	global_load_lds_dwordx4 v134, s[70:71] sc1
	s_mov_b32 m0, s90
	s_nop 0
	global_load_lds_dwordx4 v130, s[88:89] sc1
	s_add_i32 m0, s90, 0x2000
	s_nop 0
	global_load_lds_dwordx4 v134, s[88:89] sc1
	s_mov_b32 m0, s37
	s_nop 0
	global_load_lds_dwordx4 v128, s[78:79] sc1
	s_mov_b32 m0, s43
	s_nop 0
	global_load_lds_dwordx4 v132, s[78:79] sc1
	s_waitcnt vmcnt(8)
	s_waitcnt lgkmcnt(0)
	s_setprio 1
	s_barrier
	v_mfma_f32_16x16x32_bf16 v[48:51], v[156:159], v[192:195], 0
	v_mfma_f32_16x16x32_bf16 v[52:55], v[164:167], v[192:195], 0
	v_mfma_f32_16x16x32_bf16 v[32:35], v[156:159], v[204:207], 0
	v_mfma_f32_16x16x32_bf16 v[36:39], v[164:167], v[204:207], 0
	v_mfma_f32_16x16x32_bf16 v[16:19], v[156:159], v[212:215], 0
	v_mfma_f32_16x16x32_bf16 v[20:23], v[164:167], v[212:215], 0
	v_mfma_f32_16x16x32_bf16 v[0:3], v[156:159], v[220:223], 0
	v_mfma_f32_16x16x32_bf16 v[4:7], v[164:167], v[220:223], 0
	v_mfma_f32_16x16x32_bf16 v[48:51], v[160:163], v[200:203], v[48:51]
	v_mfma_f32_16x16x32_bf16 v[52:55], v[168:171], v[200:203], v[52:55]
	v_mfma_f32_16x16x32_bf16 v[32:35], v[160:163], v[208:211], v[32:35]
	v_mfma_f32_16x16x32_bf16 v[36:39], v[168:171], v[208:211], v[36:39]
	v_mfma_f32_16x16x32_bf16 v[16:19], v[160:163], v[216:219], v[16:19]
	v_mfma_f32_16x16x32_bf16 v[20:23], v[168:171], v[216:219], v[20:23]
	v_mfma_f32_16x16x32_bf16 v[0:3], v[160:163], v[224:227], v[0:3]
	v_mfma_f32_16x16x32_bf16 v[4:7], v[168:171], v[224:227], v[4:7]
	v_mfma_f32_16x16x32_bf16 v[56:59], v[172:175], v[192:195], 0
	v_mfma_f32_16x16x32_bf16 v[60:63], v[180:183], v[192:195], 0
	v_mfma_f32_16x16x32_bf16 v[40:43], v[172:175], v[204:207], 0
	v_mfma_f32_16x16x32_bf16 v[44:47], v[180:183], v[204:207], 0
	v_mfma_f32_16x16x32_bf16 v[24:27], v[172:175], v[212:215], 0
	v_mfma_f32_16x16x32_bf16 v[28:31], v[180:183], v[212:215], 0
	v_mfma_f32_16x16x32_bf16 v[8:11], v[172:175], v[220:223], 0
	v_mfma_f32_16x16x32_bf16 v[12:15], v[180:183], v[220:223], 0
	v_mfma_f32_16x16x32_bf16 v[56:59], v[176:179], v[200:203], v[56:59]
	v_mfma_f32_16x16x32_bf16 v[60:63], v[184:187], v[200:203], v[60:63]
	v_mfma_f32_16x16x32_bf16 v[40:43], v[176:179], v[208:211], v[40:43]
	v_mfma_f32_16x16x32_bf16 v[44:47], v[184:187], v[208:211], v[44:47]
	v_mfma_f32_16x16x32_bf16 v[24:27], v[176:179], v[216:219], v[24:27]
	v_mfma_f32_16x16x32_bf16 v[28:31], v[184:187], v[216:219], v[28:31]
	s_setprio 2
	s_barrier
	v_mfma_f32_16x16x32_bf16 v[8:11], v[176:179], v[224:227], v[8:11]
	v_mfma_f32_16x16x32_bf16 v[12:15], v[184:187], v[224:227], v[12:15]
	s_setprio 0
	ds_read_b128 v[156:159], v255 offset:33024
	ds_read_b128 v[160:163], v255 offset:34048
	ds_read_b128 v[164:167], v255 offset:35072
	ds_read_b128 v[168:171], v255 offset:36096
	ds_read_b128 v[172:175], v255 offset:49408
	ds_read_b128 v[176:179], v255 offset:50432
	ds_read_b128 v[180:183], v255 offset:51456
	ds_read_b128 v[184:187], v255 offset:52480
	s_add_u32 s78, s78, 0x4000
	s_addc_u32 s79, s79, 0
	s_mov_b32 m0, s44
	ds_read_b128 v[192:195], v154 offset:32768
	ds_read_b128 v[200:203], v154 offset:33792
	ds_read_b128 v[204:207], v154 offset:34816
	ds_read_b128 v[208:211], v154 offset:35840
	ds_read_b128 v[212:215], v154 offset:36864
	ds_read_b128 v[216:219], v154 offset:37888
	ds_read_b128 v[220:223], v154 offset:38912
	ds_read_b128 v[224:227], v154 offset:39936
	global_load_lds_dwordx4 v128, s[78:79] sc1
	s_mov_b32 m0, s45
	s_nop 0
	global_load_lds_dwordx4 v132, s[78:79] sc1
	s_waitcnt vmcnt(8)
	s_waitcnt lgkmcnt(0)
	s_setprio 1
	s_barrier
	v_mfma_f32_16x16x32_bf16 v[112:115], v[156:159], v[192:195], v[112:115]
	v_mfma_f32_16x16x32_bf16 v[116:119], v[164:167], v[192:195], v[116:119]
	v_mfma_f32_16x16x32_bf16 v[96:99], v[156:159], v[204:207], v[96:99]
	v_mfma_f32_16x16x32_bf16 v[100:103], v[164:167], v[204:207], v[100:103]
	v_mfma_f32_16x16x32_bf16 v[80:83], v[156:159], v[212:215], v[80:83]
	v_mfma_f32_16x16x32_bf16 v[84:87], v[164:167], v[212:215], v[84:87]
	v_mfma_f32_16x16x32_bf16 v[64:67], v[156:159], v[220:223], v[64:67]
	v_mfma_f32_16x16x32_bf16 v[68:71], v[164:167], v[220:223], v[68:71]
	v_mfma_f32_16x16x32_bf16 v[112:115], v[160:163], v[200:203], v[112:115]
	v_mfma_f32_16x16x32_bf16 v[116:119], v[168:171], v[200:203], v[116:119]
	v_mfma_f32_16x16x32_bf16 v[96:99], v[160:163], v[208:211], v[96:99]
	v_mfma_f32_16x16x32_bf16 v[100:103], v[168:171], v[208:211], v[100:103]
	v_mfma_f32_16x16x32_bf16 v[80:83], v[160:163], v[216:219], v[80:83]
	v_mfma_f32_16x16x32_bf16 v[84:87], v[168:171], v[216:219], v[84:87]
	v_mfma_f32_16x16x32_bf16 v[64:67], v[160:163], v[224:227], v[64:67]
	v_mfma_f32_16x16x32_bf16 v[68:71], v[168:171], v[224:227], v[68:71]
	v_mfma_f32_16x16x32_bf16 v[120:123], v[172:175], v[192:195], v[120:123]
	v_mfma_f32_16x16x32_bf16 v[124:127], v[180:183], v[192:195], v[124:127]
	v_mfma_f32_16x16x32_bf16 v[104:107], v[172:175], v[204:207], v[104:107]
	v_mfma_f32_16x16x32_bf16 v[108:111], v[180:183], v[204:207], v[108:111]
	v_mfma_f32_16x16x32_bf16 v[88:91], v[172:175], v[212:215], v[88:91]
	v_mfma_f32_16x16x32_bf16 v[92:95], v[180:183], v[212:215], v[92:95]
	v_mfma_f32_16x16x32_bf16 v[72:75], v[172:175], v[220:223], v[72:75]
	v_mfma_f32_16x16x32_bf16 v[76:79], v[180:183], v[220:223], v[76:79]
	v_mfma_f32_16x16x32_bf16 v[120:123], v[176:179], v[200:203], v[120:123]
	v_mfma_f32_16x16x32_bf16 v[124:127], v[184:187], v[200:203], v[124:127]
	v_mfma_f32_16x16x32_bf16 v[104:107], v[176:179], v[208:211], v[104:107]
	v_mfma_f32_16x16x32_bf16 v[108:111], v[184:187], v[208:211], v[108:111]
	v_mfma_f32_16x16x32_bf16 v[88:91], v[176:179], v[216:219], v[88:91]
	v_mfma_f32_16x16x32_bf16 v[92:95], v[184:187], v[216:219], v[92:95]
	s_setprio 2
	s_barrier
	v_mfma_f32_16x16x32_bf16 v[72:75], v[176:179], v[224:227], v[72:75]
	v_mfma_f32_16x16x32_bf16 v[76:79], v[184:187], v[224:227], v[76:79]
	s_setprio 0
	s_add_u32 s78, s70, 0x8000
	s_addc_u32 s79, s71, 0
	s_add_i32 s88, s54, s35
	s_mov_b32 m0, s88
	ds_read_b128 v[192:195], v154 offset:49152
	ds_read_b128 v[200:203], v154 offset:50176
	ds_read_b128 v[204:207], v154 offset:51200
	ds_read_b128 v[208:211], v154 offset:52224
	ds_read_b128 v[212:215], v154 offset:53248
	ds_read_b128 v[216:219], v154 offset:54272
	ds_read_b128 v[220:223], v154 offset:55296
	ds_read_b128 v[224:227], v154 offset:56320
	global_load_lds_dwordx4 v130, s[78:79] sc1
	s_add_i32 m0, s88, 0x2000
	s_add_u32 s70, s70, 0xc000
	global_load_lds_dwordx4 v134, s[78:79] sc1
	s_addc_u32 s71, s71, 0
	s_add_i32 s78, s55, s35
	s_mov_b32 m0, s78
	s_nop 0
	global_load_lds_dwordx4 v130, s[70:71] sc1
	s_add_i32 m0, s78, 0x2000
	s_nop 0
	global_load_lds_dwordx4 v134, s[70:71] sc1
	s_mov_b32 m0, s47
	s_nop 0
	global_load_lds_dwordx4 v128, s[66:67] sc1
	s_mov_b32 m0, s48
	s_nop 0
	global_load_lds_dwordx4 v132, s[66:67] sc1
	s_waitcnt vmcnt(8)
	s_waitcnt lgkmcnt(0)
	s_setprio 1
	s_barrier
	v_mfma_f32_16x16x32_bf16 v[48:51], v[156:159], v[192:195], v[48:51]
	v_mfma_f32_16x16x32_bf16 v[52:55], v[164:167], v[192:195], v[52:55]
	v_mfma_f32_16x16x32_bf16 v[32:35], v[156:159], v[204:207], v[32:35]
	v_mfma_f32_16x16x32_bf16 v[36:39], v[164:167], v[204:207], v[36:39]
	v_mfma_f32_16x16x32_bf16 v[16:19], v[156:159], v[212:215], v[16:19]
	v_mfma_f32_16x16x32_bf16 v[20:23], v[164:167], v[212:215], v[20:23]
	v_mfma_f32_16x16x32_bf16 v[0:3], v[156:159], v[220:223], v[0:3]
	v_mfma_f32_16x16x32_bf16 v[4:7], v[164:167], v[220:223], v[4:7]
	v_mfma_f32_16x16x32_bf16 v[48:51], v[160:163], v[200:203], v[48:51]
	v_mfma_f32_16x16x32_bf16 v[52:55], v[168:171], v[200:203], v[52:55]
	v_mfma_f32_16x16x32_bf16 v[32:35], v[160:163], v[208:211], v[32:35]
	v_mfma_f32_16x16x32_bf16 v[36:39], v[168:171], v[208:211], v[36:39]
	v_mfma_f32_16x16x32_bf16 v[16:19], v[160:163], v[216:219], v[16:19]
	v_mfma_f32_16x16x32_bf16 v[20:23], v[168:171], v[216:219], v[20:23]
	v_mfma_f32_16x16x32_bf16 v[0:3], v[160:163], v[224:227], v[0:3]
	v_mfma_f32_16x16x32_bf16 v[4:7], v[168:171], v[224:227], v[4:7]
	v_mfma_f32_16x16x32_bf16 v[56:59], v[172:175], v[192:195], v[56:59]
	v_mfma_f32_16x16x32_bf16 v[60:63], v[180:183], v[192:195], v[60:63]
	v_mfma_f32_16x16x32_bf16 v[40:43], v[172:175], v[204:207], v[40:43]
	v_mfma_f32_16x16x32_bf16 v[44:47], v[180:183], v[204:207], v[44:47]
	v_mfma_f32_16x16x32_bf16 v[24:27], v[172:175], v[212:215], v[24:27]
	v_mfma_f32_16x16x32_bf16 v[28:31], v[180:183], v[212:215], v[28:31]
	v_mfma_f32_16x16x32_bf16 v[8:11], v[172:175], v[220:223], v[8:11]
	v_mfma_f32_16x16x32_bf16 v[12:15], v[180:183], v[220:223], v[12:15]
	v_mfma_f32_16x16x32_bf16 v[56:59], v[176:179], v[200:203], v[56:59]
	v_mfma_f32_16x16x32_bf16 v[60:63], v[184:187], v[200:203], v[60:63]
	v_mfma_f32_16x16x32_bf16 v[40:43], v[176:179], v[208:211], v[40:43]
	v_mfma_f32_16x16x32_bf16 v[44:47], v[184:187], v[208:211], v[44:47]
	v_mfma_f32_16x16x32_bf16 v[24:27], v[176:179], v[216:219], v[24:27]
	v_mfma_f32_16x16x32_bf16 v[28:31], v[184:187], v[216:219], v[28:31]
	s_setprio 2
	s_barrier
	v_mfma_f32_16x16x32_bf16 v[8:11], v[176:179], v[224:227], v[8:11]
	v_mfma_f32_16x16x32_bf16 v[12:15], v[184:187], v[224:227], v[12:15]
	s_setprio 0
	s_add_i32 s87, s87, 2
	s_add_u32 s64, s64, 0x10000
	s_addc_u32 s65, s65, 0
	s_cmp_gt_u32 s87, 13
.LBB0_884:
	s_add_u32 s19, s38, s64
	s_addc_u32 s41, s39, s65
	s_add_u32 s19, s19, 0x10000
	ds_read_b128 v[156:159], v255 offset:256
	ds_read_b128 v[160:163], v255 offset:1280
	ds_read_b128 v[164:167], v255 offset:2304
	ds_read_b128 v[168:171], v255 offset:3328
	ds_read_b128 v[172:175], v255 offset:16640
	ds_read_b128 v[176:179], v255 offset:17664
	ds_read_b128 v[180:183], v255 offset:18688
	ds_read_b128 v[184:187], v255 offset:19712
	s_addc_u32 s41, s41, 0
	s_add_u32 s66, s69, s64
	s_addc_u32 s67, s80, s65
	s_cmp_eq_u32 s64, 0x70000
	s_cselect_b32 s78, s81, s19
	s_cselect_b32 s79, s57, s41
	s_cselect_b32 s70, s86, s66
	s_cselect_b32 s71, s85, s67
	s_add_u32 s66, s78, 0x8000
	s_addc_u32 s67, s79, 0
	s_add_i32 s19, s37, 0xc000
	s_add_u32 s98, s38, s64
	s_addc_u32 s99, s39, s65
	s_mov_b32 m0, s19
	s_add_i32 s41, s37, 0xe000
	ds_read_b128 v[192:195], v154
	ds_read_b128 v[200:203], v154 offset:1024
	ds_read_b128 v[204:207], v154 offset:2048
	ds_read_b128 v[208:211], v154 offset:3072
	ds_read_b128 v[212:215], v154 offset:4096
	ds_read_b128 v[216:219], v154 offset:5120
	ds_read_b128 v[220:223], v154 offset:6144
	ds_read_b128 v[224:227], v154 offset:7168
	global_load_lds_dwordx4 v136, s[98:99] sc1
	s_mov_b32 m0, s41
	s_nop 0
	global_load_lds_dwordx4 v138, s[98:99] sc1
	s_waitcnt vmcnt(8)
	s_waitcnt lgkmcnt(0)
	s_setprio 1
	s_barrier
	v_mfma_f32_16x16x32_bf16 v[112:115], v[156:159], v[192:195], v[112:115]
	v_mfma_f32_16x16x32_bf16 v[116:119], v[164:167], v[192:195], v[116:119]
	v_mfma_f32_16x16x32_bf16 v[96:99], v[156:159], v[204:207], v[96:99]
	v_mfma_f32_16x16x32_bf16 v[100:103], v[164:167], v[204:207], v[100:103]
	v_mfma_f32_16x16x32_bf16 v[80:83], v[156:159], v[212:215], v[80:83]
	v_mfma_f32_16x16x32_bf16 v[84:87], v[164:167], v[212:215], v[84:87]
	v_mfma_f32_16x16x32_bf16 v[64:67], v[156:159], v[220:223], v[64:67]
	v_mfma_f32_16x16x32_bf16 v[68:71], v[164:167], v[220:223], v[68:71]
	v_mfma_f32_16x16x32_bf16 v[112:115], v[160:163], v[200:203], v[112:115]
	v_mfma_f32_16x16x32_bf16 v[116:119], v[168:171], v[200:203], v[116:119]
	v_mfma_f32_16x16x32_bf16 v[96:99], v[160:163], v[208:211], v[96:99]
	v_mfma_f32_16x16x32_bf16 v[100:103], v[168:171], v[208:211], v[100:103]
	v_mfma_f32_16x16x32_bf16 v[80:83], v[160:163], v[216:219], v[80:83]
	v_mfma_f32_16x16x32_bf16 v[84:87], v[168:171], v[216:219], v[84:87]
	v_mfma_f32_16x16x32_bf16 v[64:67], v[160:163], v[224:227], v[64:67]
	v_mfma_f32_16x16x32_bf16 v[68:71], v[168:171], v[224:227], v[68:71]
	v_mfma_f32_16x16x32_bf16 v[120:123], v[172:175], v[192:195], v[120:123]
	v_mfma_f32_16x16x32_bf16 v[124:127], v[180:183], v[192:195], v[124:127]
	v_mfma_f32_16x16x32_bf16 v[104:107], v[172:175], v[204:207], v[104:107]
	v_mfma_f32_16x16x32_bf16 v[108:111], v[180:183], v[204:207], v[108:111]
	v_mfma_f32_16x16x32_bf16 v[88:91], v[172:175], v[212:215], v[88:91]
	v_mfma_f32_16x16x32_bf16 v[92:95], v[180:183], v[212:215], v[92:95]
	v_mfma_f32_16x16x32_bf16 v[72:75], v[172:175], v[220:223], v[72:75]
	v_mfma_f32_16x16x32_bf16 v[76:79], v[180:183], v[220:223], v[76:79]
	v_mfma_f32_16x16x32_bf16 v[120:123], v[176:179], v[200:203], v[120:123]
	v_mfma_f32_16x16x32_bf16 v[124:127], v[184:187], v[200:203], v[124:127]
	v_mfma_f32_16x16x32_bf16 v[104:107], v[176:179], v[208:211], v[104:107]
	v_mfma_f32_16x16x32_bf16 v[108:111], v[184:187], v[208:211], v[108:111]
	v_mfma_f32_16x16x32_bf16 v[88:91], v[176:179], v[216:219], v[88:91]
	v_mfma_f32_16x16x32_bf16 v[92:95], v[184:187], v[216:219], v[92:95]
	s_setprio 2
	s_barrier
	v_mfma_f32_16x16x32_bf16 v[72:75], v[176:179], v[224:227], v[72:75]
	v_mfma_f32_16x16x32_bf16 v[76:79], v[184:187], v[224:227], v[76:79]
	s_setprio 0
	s_add_i32 s88, s49, s35
	s_mov_b32 m0, s88
	ds_read_b128 v[192:195], v154 offset:16384
	ds_read_b128 v[200:203], v154 offset:17408
	ds_read_b128 v[204:207], v154 offset:18432
	ds_read_b128 v[208:211], v154 offset:19456
	ds_read_b128 v[212:215], v154 offset:20480
	ds_read_b128 v[216:219], v154 offset:21504
	ds_read_b128 v[220:223], v154 offset:22528
	ds_read_b128 v[224:227], v154 offset:23552
	global_load_lds_dwordx4 v130, s[70:71] sc1
	s_add_i32 m0, s88, 0x2000
	s_add_u32 s88, s70, 0x4000
	s_addc_u32 s89, s71, 0
	s_add_i32 s90, s51, s35
	global_load_lds_dwordx4 v134, s[70:71] sc1
	s_mov_b32 m0, s90
	s_nop 0
	global_load_lds_dwordx4 v130, s[88:89] sc1
	s_add_i32 m0, s90, 0x2000
	s_nop 0
	global_load_lds_dwordx4 v134, s[88:89] sc1
	s_mov_b32 m0, s37
	s_nop 0
	global_load_lds_dwordx4 v128, s[78:79] sc1
	s_mov_b32 m0, s43
	s_nop 0
	global_load_lds_dwordx4 v132, s[78:79] sc1
	s_waitcnt vmcnt(8)
	s_waitcnt lgkmcnt(0)
	s_setprio 1
	s_barrier
	v_mfma_f32_16x16x32_bf16 v[48:51], v[156:159], v[192:195], v[48:51]
	v_mfma_f32_16x16x32_bf16 v[52:55], v[164:167], v[192:195], v[52:55]
	v_mfma_f32_16x16x32_bf16 v[32:35], v[156:159], v[204:207], v[32:35]
	v_mfma_f32_16x16x32_bf16 v[36:39], v[164:167], v[204:207], v[36:39]
	v_mfma_f32_16x16x32_bf16 v[16:19], v[156:159], v[212:215], v[16:19]
	v_mfma_f32_16x16x32_bf16 v[20:23], v[164:167], v[212:215], v[20:23]
	v_mfma_f32_16x16x32_bf16 v[0:3], v[156:159], v[220:223], v[0:3]
	v_mfma_f32_16x16x32_bf16 v[4:7], v[164:167], v[220:223], v[4:7]
	v_mfma_f32_16x16x32_bf16 v[48:51], v[160:163], v[200:203], v[48:51]
	v_mfma_f32_16x16x32_bf16 v[52:55], v[168:171], v[200:203], v[52:55]
	v_mfma_f32_16x16x32_bf16 v[32:35], v[160:163], v[208:211], v[32:35]
	v_mfma_f32_16x16x32_bf16 v[36:39], v[168:171], v[208:211], v[36:39]
	v_mfma_f32_16x16x32_bf16 v[16:19], v[160:163], v[216:219], v[16:19]
	v_mfma_f32_16x16x32_bf16 v[20:23], v[168:171], v[216:219], v[20:23]
	v_mfma_f32_16x16x32_bf16 v[0:3], v[160:163], v[224:227], v[0:3]
	v_mfma_f32_16x16x32_bf16 v[4:7], v[168:171], v[224:227], v[4:7]
	v_mfma_f32_16x16x32_bf16 v[56:59], v[172:175], v[192:195], v[56:59]
	v_mfma_f32_16x16x32_bf16 v[60:63], v[180:183], v[192:195], v[60:63]
	v_mfma_f32_16x16x32_bf16 v[40:43], v[172:175], v[204:207], v[40:43]
	v_mfma_f32_16x16x32_bf16 v[44:47], v[180:183], v[204:207], v[44:47]
	v_mfma_f32_16x16x32_bf16 v[24:27], v[172:175], v[212:215], v[24:27]
	v_mfma_f32_16x16x32_bf16 v[28:31], v[180:183], v[212:215], v[28:31]
	v_mfma_f32_16x16x32_bf16 v[8:11], v[172:175], v[220:223], v[8:11]
	v_mfma_f32_16x16x32_bf16 v[12:15], v[180:183], v[220:223], v[12:15]
	v_mfma_f32_16x16x32_bf16 v[56:59], v[176:179], v[200:203], v[56:59]
	v_mfma_f32_16x16x32_bf16 v[60:63], v[184:187], v[200:203], v[60:63]
	v_mfma_f32_16x16x32_bf16 v[40:43], v[176:179], v[208:211], v[40:43]
	v_mfma_f32_16x16x32_bf16 v[44:47], v[184:187], v[208:211], v[44:47]
	v_mfma_f32_16x16x32_bf16 v[24:27], v[176:179], v[216:219], v[24:27]
	v_mfma_f32_16x16x32_bf16 v[28:31], v[184:187], v[216:219], v[28:31]
	s_setprio 2
	s_barrier
	v_mfma_f32_16x16x32_bf16 v[8:11], v[176:179], v[224:227], v[8:11]
	v_mfma_f32_16x16x32_bf16 v[12:15], v[184:187], v[224:227], v[12:15]
	s_setprio 0
	ds_read_b128 v[156:159], v255 offset:33024
	ds_read_b128 v[160:163], v255 offset:34048
	ds_read_b128 v[164:167], v255 offset:35072
	ds_read_b128 v[168:171], v255 offset:36096
	ds_read_b128 v[172:175], v255 offset:49408
	ds_read_b128 v[176:179], v255 offset:50432
	ds_read_b128 v[180:183], v255 offset:51456
	ds_read_b128 v[184:187], v255 offset:52480
	s_add_u32 s78, s78, 0x4000
	s_addc_u32 s79, s79, 0
	s_mov_b32 m0, s44
	ds_read_b128 v[192:195], v154 offset:32768
	ds_read_b128 v[200:203], v154 offset:33792
	ds_read_b128 v[204:207], v154 offset:34816
	ds_read_b128 v[208:211], v154 offset:35840
	ds_read_b128 v[212:215], v154 offset:36864
	ds_read_b128 v[216:219], v154 offset:37888
	ds_read_b128 v[220:223], v154 offset:38912
	ds_read_b128 v[224:227], v154 offset:39936
	global_load_lds_dwordx4 v128, s[78:79] sc1
	s_mov_b32 m0, s45
	s_nop 0
	global_load_lds_dwordx4 v132, s[78:79] sc1
	s_waitcnt vmcnt(8)
	s_waitcnt lgkmcnt(0)
	s_setprio 1
	s_barrier
	v_mfma_f32_16x16x32_bf16 v[112:115], v[156:159], v[192:195], v[112:115]
	v_mfma_f32_16x16x32_bf16 v[116:119], v[164:167], v[192:195], v[116:119]
	v_mfma_f32_16x16x32_bf16 v[96:99], v[156:159], v[204:207], v[96:99]
	v_mfma_f32_16x16x32_bf16 v[100:103], v[164:167], v[204:207], v[100:103]
	v_mfma_f32_16x16x32_bf16 v[80:83], v[156:159], v[212:215], v[80:83]
	v_mfma_f32_16x16x32_bf16 v[84:87], v[164:167], v[212:215], v[84:87]
	v_mfma_f32_16x16x32_bf16 v[64:67], v[156:159], v[220:223], v[64:67]
	v_mfma_f32_16x16x32_bf16 v[68:71], v[164:167], v[220:223], v[68:71]
	v_mfma_f32_16x16x32_bf16 v[112:115], v[160:163], v[200:203], v[112:115]
	v_mfma_f32_16x16x32_bf16 v[116:119], v[168:171], v[200:203], v[116:119]
	v_mfma_f32_16x16x32_bf16 v[96:99], v[160:163], v[208:211], v[96:99]
	v_mfma_f32_16x16x32_bf16 v[100:103], v[168:171], v[208:211], v[100:103]
	v_mfma_f32_16x16x32_bf16 v[80:83], v[160:163], v[216:219], v[80:83]
	v_mfma_f32_16x16x32_bf16 v[84:87], v[168:171], v[216:219], v[84:87]
	v_mfma_f32_16x16x32_bf16 v[64:67], v[160:163], v[224:227], v[64:67]
	v_mfma_f32_16x16x32_bf16 v[68:71], v[168:171], v[224:227], v[68:71]
	v_mfma_f32_16x16x32_bf16 v[120:123], v[172:175], v[192:195], v[120:123]
	v_mfma_f32_16x16x32_bf16 v[124:127], v[180:183], v[192:195], v[124:127]
	v_mfma_f32_16x16x32_bf16 v[104:107], v[172:175], v[204:207], v[104:107]
	v_mfma_f32_16x16x32_bf16 v[108:111], v[180:183], v[204:207], v[108:111]
	v_mfma_f32_16x16x32_bf16 v[88:91], v[172:175], v[212:215], v[88:91]
	v_mfma_f32_16x16x32_bf16 v[92:95], v[180:183], v[212:215], v[92:95]
	v_mfma_f32_16x16x32_bf16 v[72:75], v[172:175], v[220:223], v[72:75]
	v_mfma_f32_16x16x32_bf16 v[76:79], v[180:183], v[220:223], v[76:79]
	v_mfma_f32_16x16x32_bf16 v[120:123], v[176:179], v[200:203], v[120:123]
	v_mfma_f32_16x16x32_bf16 v[124:127], v[184:187], v[200:203], v[124:127]
	v_mfma_f32_16x16x32_bf16 v[104:107], v[176:179], v[208:211], v[104:107]
	v_mfma_f32_16x16x32_bf16 v[108:111], v[184:187], v[208:211], v[108:111]
	v_mfma_f32_16x16x32_bf16 v[88:91], v[176:179], v[216:219], v[88:91]
	v_mfma_f32_16x16x32_bf16 v[92:95], v[184:187], v[216:219], v[92:95]
	s_setprio 2
	s_barrier
	v_mfma_f32_16x16x32_bf16 v[72:75], v[176:179], v[224:227], v[72:75]
	v_mfma_f32_16x16x32_bf16 v[76:79], v[184:187], v[224:227], v[76:79]
	s_setprio 0
	s_add_u32 s78, s70, 0x8000
	s_addc_u32 s79, s71, 0
	s_add_i32 s88, s54, s35
	s_mov_b32 m0, s88
	ds_read_b128 v[192:195], v154 offset:49152
	ds_read_b128 v[200:203], v154 offset:50176
	ds_read_b128 v[204:207], v154 offset:51200
	ds_read_b128 v[208:211], v154 offset:52224
	ds_read_b128 v[212:215], v154 offset:53248
	ds_read_b128 v[216:219], v154 offset:54272
	ds_read_b128 v[220:223], v154 offset:55296
	ds_read_b128 v[224:227], v154 offset:56320
	global_load_lds_dwordx4 v130, s[78:79] sc1
	s_add_i32 m0, s88, 0x2000
	s_add_u32 s70, s70, 0xc000
	global_load_lds_dwordx4 v134, s[78:79] sc1
	s_addc_u32 s71, s71, 0
	s_add_i32 s78, s55, s35
	s_mov_b32 m0, s78
	s_nop 0
	global_load_lds_dwordx4 v130, s[70:71] sc1
	s_add_i32 m0, s78, 0x2000
	s_nop 0
	global_load_lds_dwordx4 v134, s[70:71] sc1
	s_mov_b32 m0, s47
	s_nop 0
	global_load_lds_dwordx4 v128, s[66:67] sc1
	s_mov_b32 m0, s48
	s_nop 0
	global_load_lds_dwordx4 v132, s[66:67] sc1
	s_waitcnt vmcnt(8)
	s_waitcnt lgkmcnt(0)
	s_setprio 1
	s_barrier
	v_mfma_f32_16x16x32_bf16 v[48:51], v[156:159], v[192:195], v[48:51]
	v_mfma_f32_16x16x32_bf16 v[52:55], v[164:167], v[192:195], v[52:55]
	v_mfma_f32_16x16x32_bf16 v[32:35], v[156:159], v[204:207], v[32:35]
	v_mfma_f32_16x16x32_bf16 v[36:39], v[164:167], v[204:207], v[36:39]
	v_mfma_f32_16x16x32_bf16 v[16:19], v[156:159], v[212:215], v[16:19]
	v_mfma_f32_16x16x32_bf16 v[20:23], v[164:167], v[212:215], v[20:23]
	v_mfma_f32_16x16x32_bf16 v[0:3], v[156:159], v[220:223], v[0:3]
	v_mfma_f32_16x16x32_bf16 v[4:7], v[164:167], v[220:223], v[4:7]
	v_mfma_f32_16x16x32_bf16 v[48:51], v[160:163], v[200:203], v[48:51]
	v_mfma_f32_16x16x32_bf16 v[52:55], v[168:171], v[200:203], v[52:55]
	v_mfma_f32_16x16x32_bf16 v[32:35], v[160:163], v[208:211], v[32:35]
	v_mfma_f32_16x16x32_bf16 v[36:39], v[168:171], v[208:211], v[36:39]
	v_mfma_f32_16x16x32_bf16 v[16:19], v[160:163], v[216:219], v[16:19]
	v_mfma_f32_16x16x32_bf16 v[20:23], v[168:171], v[216:219], v[20:23]
	v_mfma_f32_16x16x32_bf16 v[0:3], v[160:163], v[224:227], v[0:3]
	v_mfma_f32_16x16x32_bf16 v[4:7], v[168:171], v[224:227], v[4:7]
	v_mfma_f32_16x16x32_bf16 v[56:59], v[172:175], v[192:195], v[56:59]
	v_mfma_f32_16x16x32_bf16 v[60:63], v[180:183], v[192:195], v[60:63]
	v_mfma_f32_16x16x32_bf16 v[40:43], v[172:175], v[204:207], v[40:43]
	v_mfma_f32_16x16x32_bf16 v[44:47], v[180:183], v[204:207], v[44:47]
	v_mfma_f32_16x16x32_bf16 v[24:27], v[172:175], v[212:215], v[24:27]
	v_mfma_f32_16x16x32_bf16 v[28:31], v[180:183], v[212:215], v[28:31]
	v_mfma_f32_16x16x32_bf16 v[8:11], v[172:175], v[220:223], v[8:11]
	v_mfma_f32_16x16x32_bf16 v[12:15], v[180:183], v[220:223], v[12:15]
	v_mfma_f32_16x16x32_bf16 v[56:59], v[176:179], v[200:203], v[56:59]
	v_mfma_f32_16x16x32_bf16 v[60:63], v[184:187], v[200:203], v[60:63]
	v_mfma_f32_16x16x32_bf16 v[40:43], v[176:179], v[208:211], v[40:43]
	v_mfma_f32_16x16x32_bf16 v[44:47], v[184:187], v[208:211], v[44:47]
	v_mfma_f32_16x16x32_bf16 v[24:27], v[176:179], v[216:219], v[24:27]
	v_mfma_f32_16x16x32_bf16 v[28:31], v[184:187], v[216:219], v[28:31]
	s_setprio 2
	s_barrier
	v_mfma_f32_16x16x32_bf16 v[8:11], v[176:179], v[224:227], v[8:11]
	v_mfma_f32_16x16x32_bf16 v[12:15], v[184:187], v[224:227], v[12:15]
	s_setprio 0
	s_add_i32 s87, s87, 2
	s_add_u32 s64, s64, 0x10000
	s_addc_u32 s65, s65, 0
	s_cmp_gt_u32 s87, 13
	s_cbranch_scc0 .LBB0_884
	s_add_u32 s64, s69, 0xffff0000
	s_addc_u32 s65, s80, -1
	s_andn2_b64 vcc, exec, s[8:9]
	s_cbranch_vccz .LBB0_876
	s_mov_b64 s[30:31], s[64:65]
	s_andn2_b64 vcc, exec, s[6:7]
	s_cbranch_vccnz .LBB0_877

.LBB0_975:
	s_add_u32 s55, s64, 0x10000
	s_addc_u32 s69, s65, 0
	s_ashr_i32 s41, s40, 31
	s_lshl_b64 s[56:57], s[40:41], 19
	s_add_u32 s62, s60, s56
	s_addc_u32 s63, s33, s57
	s_and_b64 s[56:57], s[8:9], exec
	s_cselect_b32 s41, s63, s19
	s_cselect_b32 s80, s62, s18
	s_ashr_i32 s39, s38, 31
	s_lshl_b64 s[56:57], s[38:39], 19
	s_add_u32 s56, s30, s56
	s_addc_u32 s57, s31, s57
	s_and_b64 s[66:67], s[8:9], exec
	s_cselect_b32 s39, s57, s65
	s_cselect_b32 s81, s56, s64
	v_lshl_add_u64 v[144:145], s[18:19], 0, v[136:137]
	v_lshl_add_u64 v[146:147], s[18:19], 0, v[138:139]
	s_mov_b32 s85, -2
	s_mov_b64 s[64:65], 0
	v_add_u32_e32 v255, 0x10000, v149
	s_add_u32 s66, s18, s64
	s_addc_u32 s67, s19, s65
	ds_read_b128 v[152:155], v255 offset:256
	ds_read_b128 v[156:159], v255 offset:1280
	ds_read_b128 v[160:163], v255 offset:2304
	ds_read_b128 v[164:167], v255 offset:3328
	s_add_u32 s66, s66, 0x10000
	ds_read_b128 v[168:171], v255 offset:16640
	ds_read_b128 v[172:175], v255 offset:17664
	ds_read_b128 v[176:179], v255 offset:18688
	ds_read_b128 v[180:183], v255 offset:19712
	s_addc_u32 s67, s67, 0
	s_add_u32 s70, s55, s64
	s_addc_u32 s71, s69, s65
	s_cmp_eq_u32 s64, 0x70000
	s_cselect_b32 s78, s80, s66
	s_cselect_b32 s79, s41, s67
	s_cselect_b32 s70, s81, s70
	s_cselect_b32 s71, s39, s71
	s_add_u32 s66, s78, 0x8000
	s_addc_u32 s67, s79, 0
	s_add_u32 s98, s18, s64
	s_addc_u32 s99, s19, s65
	s_add_i32 m0, s11, 0xc000
	ds_read_b128 v[184:187], v150
	ds_read_b128 v[192:195], v150 offset:1024
	ds_read_b128 v[200:203], v150 offset:2048
	ds_read_b128 v[204:207], v150 offset:3072
	ds_read_b128 v[208:211], v150 offset:4096
	ds_read_b128 v[212:215], v150 offset:5120
	ds_read_b128 v[216:219], v150 offset:6144
	ds_read_b128 v[220:223], v150 offset:7168
	global_load_lds_dwordx4 v136, s[98:99] sc1
	s_add_i32 m0, s11, 0xe000
	s_nop 0
	global_load_lds_dwordx4 v138, s[98:99] sc1
	s_waitcnt vmcnt(8)
	s_waitcnt lgkmcnt(0)
	s_setprio 1
	s_barrier
	v_mfma_f32_16x16x32_bf16 v[104:107], v[152:155], v[184:187], 0
	v_mfma_f32_16x16x32_bf16 v[108:111], v[160:163], v[184:187], 0
	v_mfma_f32_16x16x32_bf16 v[84:87], v[152:155], v[200:203], 0
	v_mfma_f32_16x16x32_bf16 v[92:95], v[160:163], v[200:203], 0
	v_mfma_f32_16x16x32_bf16 v[72:75], v[152:155], v[208:211], 0
	v_mfma_f32_16x16x32_bf16 v[76:79], v[160:163], v[208:211], 0
	v_mfma_f32_16x16x32_bf16 v[64:67], v[152:155], v[216:219], 0
	v_mfma_f32_16x16x32_bf16 v[68:71], v[160:163], v[216:219], 0
	v_mfma_f32_16x16x32_bf16 v[104:107], v[156:159], v[192:195], v[104:107]
	v_mfma_f32_16x16x32_bf16 v[108:111], v[164:167], v[192:195], v[108:111]
	v_mfma_f32_16x16x32_bf16 v[84:87], v[156:159], v[204:207], v[84:87]
	v_mfma_f32_16x16x32_bf16 v[92:95], v[164:167], v[204:207], v[92:95]
	v_mfma_f32_16x16x32_bf16 v[72:75], v[156:159], v[212:215], v[72:75]
	v_mfma_f32_16x16x32_bf16 v[76:79], v[164:167], v[212:215], v[76:79]
	v_mfma_f32_16x16x32_bf16 v[64:67], v[156:159], v[220:223], v[64:67]
	v_mfma_f32_16x16x32_bf16 v[68:71], v[164:167], v[220:223], v[68:71]
	v_mfma_f32_16x16x32_bf16 v[120:123], v[168:171], v[184:187], 0
	v_mfma_f32_16x16x32_bf16 v[124:127], v[176:179], v[184:187], 0
	v_mfma_f32_16x16x32_bf16 v[112:115], v[168:171], v[200:203], 0
	v_mfma_f32_16x16x32_bf16 v[116:119], v[176:179], v[200:203], 0
	v_mfma_f32_16x16x32_bf16 v[96:99], v[168:171], v[208:211], 0
	v_mfma_f32_16x16x32_bf16 v[100:103], v[176:179], v[208:211], 0
	v_mfma_f32_16x16x32_bf16 v[80:83], v[168:171], v[216:219], 0
	v_mfma_f32_16x16x32_bf16 v[88:91], v[176:179], v[216:219], 0
	v_mfma_f32_16x16x32_bf16 v[120:123], v[172:175], v[192:195], v[120:123]
	v_mfma_f32_16x16x32_bf16 v[124:127], v[180:183], v[192:195], v[124:127]
	v_mfma_f32_16x16x32_bf16 v[112:115], v[172:175], v[204:207], v[112:115]
	v_mfma_f32_16x16x32_bf16 v[116:119], v[180:183], v[204:207], v[116:119]
	v_mfma_f32_16x16x32_bf16 v[96:99], v[172:175], v[212:215], v[96:99]
	v_mfma_f32_16x16x32_bf16 v[100:103], v[180:183], v[212:215], v[100:103]
	s_setprio 2
	s_barrier
	v_mfma_f32_16x16x32_bf16 v[80:83], v[172:175], v[220:223], v[80:83]
	v_mfma_f32_16x16x32_bf16 v[88:91], v[180:183], v[220:223], v[88:91]
	s_setprio 0
	s_add_i32 s86, s48, s37
	s_mov_b32 m0, s86
	ds_read_b128 v[184:187], v150 offset:16384
	ds_read_b128 v[192:195], v150 offset:17408
	ds_read_b128 v[200:203], v150 offset:18432
	ds_read_b128 v[204:207], v150 offset:19456
	ds_read_b128 v[208:211], v150 offset:20480
	ds_read_b128 v[212:215], v150 offset:21504
	ds_read_b128 v[216:219], v150 offset:22528
	ds_read_b128 v[220:223], v150 offset:23552
	global_load_lds_dwordx4 v132, s[70:71] sc1
	s_add_i32 m0, s86, 0x2000
	s_add_u32 s86, s70, 0x4000
	s_addc_u32 s87, s71, 0
	s_add_i32 s88, s49, s37
	global_load_lds_dwordx4 v134, s[70:71] sc1
	s_mov_b32 m0, s88
	s_nop 0
	global_load_lds_dwordx4 v132, s[86:87] sc1
	s_add_i32 m0, s88, 0x2000
	s_nop 0
	global_load_lds_dwordx4 v134, s[86:87] sc1
	s_mov_b32 m0, s11
	s_nop 0
	global_load_lds_dwordx4 v128, s[78:79] sc1
	s_mov_b32 m0, s42
	s_nop 0
	global_load_lds_dwordx4 v130, s[78:79] sc1
	s_waitcnt vmcnt(8)
	s_waitcnt lgkmcnt(0)
	s_setprio 1
	s_barrier
	v_mfma_f32_16x16x32_bf16 v[36:39], v[152:155], v[184:187], 0
	v_mfma_f32_16x16x32_bf16 v[44:47], v[160:163], v[184:187], 0
	v_mfma_f32_16x16x32_bf16 v[20:23], v[152:155], v[200:203], 0
	v_mfma_f32_16x16x32_bf16 v[28:31], v[160:163], v[200:203], 0
	v_mfma_f32_16x16x32_bf16 v[8:11], v[152:155], v[208:211], 0
	v_mfma_f32_16x16x32_bf16 v[12:15], v[160:163], v[208:211], 0
	v_mfma_f32_16x16x32_bf16 v[0:3], v[152:155], v[216:219], 0
	v_mfma_f32_16x16x32_bf16 v[4:7], v[160:163], v[216:219], 0
	v_mfma_f32_16x16x32_bf16 v[36:39], v[156:159], v[192:195], v[36:39]
	v_mfma_f32_16x16x32_bf16 v[44:47], v[164:167], v[192:195], v[44:47]
	v_mfma_f32_16x16x32_bf16 v[20:23], v[156:159], v[204:207], v[20:23]
	v_mfma_f32_16x16x32_bf16 v[28:31], v[164:167], v[204:207], v[28:31]
	v_mfma_f32_16x16x32_bf16 v[8:11], v[156:159], v[212:215], v[8:11]
	v_mfma_f32_16x16x32_bf16 v[12:15], v[164:167], v[212:215], v[12:15]
	v_mfma_f32_16x16x32_bf16 v[0:3], v[156:159], v[220:223], v[0:3]
	v_mfma_f32_16x16x32_bf16 v[4:7], v[164:167], v[220:223], v[4:7]
	v_mfma_f32_16x16x32_bf16 v[56:59], v[168:171], v[184:187], 0
	v_mfma_f32_16x16x32_bf16 v[60:63], v[176:179], v[184:187], 0
	v_mfma_f32_16x16x32_bf16 v[48:51], v[168:171], v[200:203], 0
	v_mfma_f32_16x16x32_bf16 v[52:55], v[176:179], v[200:203], 0
	v_mfma_f32_16x16x32_bf16 v[32:35], v[168:171], v[208:211], 0
	v_mfma_f32_16x16x32_bf16 v[40:43], v[176:179], v[208:211], 0
	v_mfma_f32_16x16x32_bf16 v[16:19], v[168:171], v[216:219], 0
	v_mfma_f32_16x16x32_bf16 v[24:27], v[176:179], v[216:219], 0
	v_mfma_f32_16x16x32_bf16 v[56:59], v[172:175], v[192:195], v[56:59]
	v_mfma_f32_16x16x32_bf16 v[60:63], v[180:183], v[192:195], v[60:63]
	v_mfma_f32_16x16x32_bf16 v[48:51], v[172:175], v[204:207], v[48:51]
	v_mfma_f32_16x16x32_bf16 v[52:55], v[180:183], v[204:207], v[52:55]
	v_mfma_f32_16x16x32_bf16 v[32:35], v[172:175], v[212:215], v[32:35]
	v_mfma_f32_16x16x32_bf16 v[40:43], v[180:183], v[212:215], v[40:43]
	s_setprio 2
	s_barrier
	v_mfma_f32_16x16x32_bf16 v[16:19], v[172:175], v[220:223], v[16:19]
	v_mfma_f32_16x16x32_bf16 v[24:27], v[180:183], v[220:223], v[24:27]
	s_setprio 0
	ds_read_b128 v[152:155], v255 offset:33024
	ds_read_b128 v[156:159], v255 offset:34048
	ds_read_b128 v[160:163], v255 offset:35072
	ds_read_b128 v[164:167], v255 offset:36096
	ds_read_b128 v[168:171], v255 offset:49408
	ds_read_b128 v[172:175], v255 offset:50432
	ds_read_b128 v[176:179], v255 offset:51456
	ds_read_b128 v[180:183], v255 offset:52480
	s_add_u32 s78, s78, 0x4000
	s_addc_u32 s79, s79, 0
	s_mov_b32 m0, s43
	ds_read_b128 v[184:187], v150 offset:32768
	ds_read_b128 v[192:195], v150 offset:33792
	ds_read_b128 v[200:203], v150 offset:34816
	ds_read_b128 v[204:207], v150 offset:35840
	ds_read_b128 v[208:211], v150 offset:36864
	ds_read_b128 v[212:215], v150 offset:37888
	ds_read_b128 v[216:219], v150 offset:38912
	ds_read_b128 v[220:223], v150 offset:39936
	global_load_lds_dwordx4 v128, s[78:79] sc1
	s_mov_b32 m0, s44
	s_nop 0
	global_load_lds_dwordx4 v130, s[78:79] sc1
	s_waitcnt vmcnt(8)
	s_waitcnt lgkmcnt(0)
	s_setprio 1
	s_barrier
	v_mfma_f32_16x16x32_bf16 v[104:107], v[152:155], v[184:187], v[104:107]
	v_mfma_f32_16x16x32_bf16 v[108:111], v[160:163], v[184:187], v[108:111]
	v_mfma_f32_16x16x32_bf16 v[84:87], v[152:155], v[200:203], v[84:87]
	v_mfma_f32_16x16x32_bf16 v[92:95], v[160:163], v[200:203], v[92:95]
	v_mfma_f32_16x16x32_bf16 v[72:75], v[152:155], v[208:211], v[72:75]
	v_mfma_f32_16x16x32_bf16 v[76:79], v[160:163], v[208:211], v[76:79]
	v_mfma_f32_16x16x32_bf16 v[64:67], v[152:155], v[216:219], v[64:67]
	v_mfma_f32_16x16x32_bf16 v[68:71], v[160:163], v[216:219], v[68:71]
	v_mfma_f32_16x16x32_bf16 v[104:107], v[156:159], v[192:195], v[104:107]
	v_mfma_f32_16x16x32_bf16 v[108:111], v[164:167], v[192:195], v[108:111]
	v_mfma_f32_16x16x32_bf16 v[84:87], v[156:159], v[204:207], v[84:87]
	v_mfma_f32_16x16x32_bf16 v[92:95], v[164:167], v[204:207], v[92:95]
	v_mfma_f32_16x16x32_bf16 v[72:75], v[156:159], v[212:215], v[72:75]
	v_mfma_f32_16x16x32_bf16 v[76:79], v[164:167], v[212:215], v[76:79]
	v_mfma_f32_16x16x32_bf16 v[64:67], v[156:159], v[220:223], v[64:67]
	v_mfma_f32_16x16x32_bf16 v[68:71], v[164:167], v[220:223], v[68:71]
	v_mfma_f32_16x16x32_bf16 v[120:123], v[168:171], v[184:187], v[120:123]
	v_mfma_f32_16x16x32_bf16 v[124:127], v[176:179], v[184:187], v[124:127]
	v_mfma_f32_16x16x32_bf16 v[112:115], v[168:171], v[200:203], v[112:115]
	v_mfma_f32_16x16x32_bf16 v[116:119], v[176:179], v[200:203], v[116:119]
	v_mfma_f32_16x16x32_bf16 v[96:99], v[168:171], v[208:211], v[96:99]
	v_mfma_f32_16x16x32_bf16 v[100:103], v[176:179], v[208:211], v[100:103]
	v_mfma_f32_16x16x32_bf16 v[80:83], v[168:171], v[216:219], v[80:83]
	v_mfma_f32_16x16x32_bf16 v[88:91], v[176:179], v[216:219], v[88:91]
	v_mfma_f32_16x16x32_bf16 v[120:123], v[172:175], v[192:195], v[120:123]
	v_mfma_f32_16x16x32_bf16 v[124:127], v[180:183], v[192:195], v[124:127]
	v_mfma_f32_16x16x32_bf16 v[112:115], v[172:175], v[204:207], v[112:115]
	v_mfma_f32_16x16x32_bf16 v[116:119], v[180:183], v[204:207], v[116:119]
	v_mfma_f32_16x16x32_bf16 v[96:99], v[172:175], v[212:215], v[96:99]
	v_mfma_f32_16x16x32_bf16 v[100:103], v[180:183], v[212:215], v[100:103]
	s_setprio 2
	s_barrier
	v_mfma_f32_16x16x32_bf16 v[80:83], v[172:175], v[220:223], v[80:83]
	v_mfma_f32_16x16x32_bf16 v[88:91], v[180:183], v[220:223], v[88:91]
	s_setprio 0
	s_add_u32 s78, s70, 0x8000
	s_addc_u32 s79, s71, 0
	s_add_i32 s86, s50, s37
	s_mov_b32 m0, s86
	ds_read_b128 v[184:187], v150 offset:49152
	ds_read_b128 v[192:195], v150 offset:50176
	ds_read_b128 v[200:203], v150 offset:51200
	ds_read_b128 v[204:207], v150 offset:52224
	ds_read_b128 v[208:211], v150 offset:53248
	ds_read_b128 v[212:215], v150 offset:54272
	ds_read_b128 v[216:219], v150 offset:55296
	ds_read_b128 v[220:223], v150 offset:56320
	global_load_lds_dwordx4 v132, s[78:79] sc1
	s_add_i32 m0, s86, 0x2000
	s_add_u32 s70, s70, 0xc000
	global_load_lds_dwordx4 v134, s[78:79] sc1
	s_addc_u32 s71, s71, 0
	s_add_i32 s78, s51, s37
	s_mov_b32 m0, s78
	s_nop 0
	global_load_lds_dwordx4 v132, s[70:71] sc1
	s_add_i32 m0, s78, 0x2000
	s_nop 0
	global_load_lds_dwordx4 v134, s[70:71] sc1
	s_mov_b32 m0, s17
	s_nop 0
	global_load_lds_dwordx4 v128, s[66:67] sc1
	s_mov_b32 m0, s46
	s_nop 0
	global_load_lds_dwordx4 v130, s[66:67] sc1
	s_waitcnt vmcnt(8)
	s_waitcnt lgkmcnt(0)
	s_setprio 1
	s_barrier
	v_mfma_f32_16x16x32_bf16 v[36:39], v[152:155], v[184:187], v[36:39]
	v_mfma_f32_16x16x32_bf16 v[44:47], v[160:163], v[184:187], v[44:47]
	v_mfma_f32_16x16x32_bf16 v[20:23], v[152:155], v[200:203], v[20:23]
	v_mfma_f32_16x16x32_bf16 v[28:31], v[160:163], v[200:203], v[28:31]
	v_mfma_f32_16x16x32_bf16 v[8:11], v[152:155], v[208:211], v[8:11]
	v_mfma_f32_16x16x32_bf16 v[12:15], v[160:163], v[208:211], v[12:15]
	v_mfma_f32_16x16x32_bf16 v[0:3], v[152:155], v[216:219], v[0:3]
	v_mfma_f32_16x16x32_bf16 v[4:7], v[160:163], v[216:219], v[4:7]
	v_mfma_f32_16x16x32_bf16 v[36:39], v[156:159], v[192:195], v[36:39]
	v_mfma_f32_16x16x32_bf16 v[44:47], v[164:167], v[192:195], v[44:47]
	v_mfma_f32_16x16x32_bf16 v[20:23], v[156:159], v[204:207], v[20:23]
	v_mfma_f32_16x16x32_bf16 v[28:31], v[164:167], v[204:207], v[28:31]
	v_mfma_f32_16x16x32_bf16 v[8:11], v[156:159], v[212:215], v[8:11]
	v_mfma_f32_16x16x32_bf16 v[12:15], v[164:167], v[212:215], v[12:15]
	v_mfma_f32_16x16x32_bf16 v[0:3], v[156:159], v[220:223], v[0:3]
	v_mfma_f32_16x16x32_bf16 v[4:7], v[164:167], v[220:223], v[4:7]
	v_mfma_f32_16x16x32_bf16 v[56:59], v[168:171], v[184:187], v[56:59]
	v_mfma_f32_16x16x32_bf16 v[60:63], v[176:179], v[184:187], v[60:63]
	v_mfma_f32_16x16x32_bf16 v[48:51], v[168:171], v[200:203], v[48:51]
	v_mfma_f32_16x16x32_bf16 v[52:55], v[176:179], v[200:203], v[52:55]
	v_mfma_f32_16x16x32_bf16 v[32:35], v[168:171], v[208:211], v[32:35]
	v_mfma_f32_16x16x32_bf16 v[40:43], v[176:179], v[208:211], v[40:43]
	v_mfma_f32_16x16x32_bf16 v[16:19], v[168:171], v[216:219], v[16:19]
	v_mfma_f32_16x16x32_bf16 v[24:27], v[176:179], v[216:219], v[24:27]
	v_mfma_f32_16x16x32_bf16 v[56:59], v[172:175], v[192:195], v[56:59]
	v_mfma_f32_16x16x32_bf16 v[60:63], v[180:183], v[192:195], v[60:63]
	v_mfma_f32_16x16x32_bf16 v[48:51], v[172:175], v[204:207], v[48:51]
	v_mfma_f32_16x16x32_bf16 v[52:55], v[180:183], v[204:207], v[52:55]
	v_mfma_f32_16x16x32_bf16 v[32:35], v[172:175], v[212:215], v[32:35]
	v_mfma_f32_16x16x32_bf16 v[40:43], v[180:183], v[212:215], v[40:43]
	s_setprio 2
	s_barrier
	v_mfma_f32_16x16x32_bf16 v[16:19], v[172:175], v[220:223], v[16:19]
	v_mfma_f32_16x16x32_bf16 v[24:27], v[180:183], v[220:223], v[24:27]
	s_setprio 0
	s_add_i32 s85, s85, 2
	s_add_u32 s64, s64, 0x10000
	s_addc_u32 s65, s65, 0
	s_cmp_gt_u32 s85, 13
.LBB0_976:
	s_add_u32 s66, s18, s64
	s_addc_u32 s67, s19, s65
	ds_read_b128 v[152:155], v255 offset:256
	ds_read_b128 v[156:159], v255 offset:1280
	ds_read_b128 v[160:163], v255 offset:2304
	ds_read_b128 v[164:167], v255 offset:3328
	s_add_u32 s66, s66, 0x10000
	ds_read_b128 v[168:171], v255 offset:16640
	ds_read_b128 v[172:175], v255 offset:17664
	ds_read_b128 v[176:179], v255 offset:18688
	ds_read_b128 v[180:183], v255 offset:19712
	s_addc_u32 s67, s67, 0
	s_add_u32 s70, s55, s64
	s_addc_u32 s71, s69, s65
	s_cmp_eq_u32 s64, 0x70000
	s_cselect_b32 s78, s80, s66
	s_cselect_b32 s79, s41, s67
	s_cselect_b32 s70, s81, s70
	s_cselect_b32 s71, s39, s71
	s_add_u32 s66, s78, 0x8000
	s_addc_u32 s67, s79, 0
	s_add_u32 s98, s18, s64
	s_addc_u32 s99, s19, s65
	s_add_i32 m0, s11, 0xc000
	ds_read_b128 v[184:187], v150
	ds_read_b128 v[192:195], v150 offset:1024
	ds_read_b128 v[200:203], v150 offset:2048
	ds_read_b128 v[204:207], v150 offset:3072
	ds_read_b128 v[208:211], v150 offset:4096
	ds_read_b128 v[212:215], v150 offset:5120
	ds_read_b128 v[216:219], v150 offset:6144
	ds_read_b128 v[220:223], v150 offset:7168
	global_load_lds_dwordx4 v136, s[98:99] sc1
	s_add_i32 m0, s11, 0xe000
	s_nop 0
	global_load_lds_dwordx4 v138, s[98:99] sc1
	s_waitcnt vmcnt(8)
	s_waitcnt lgkmcnt(0)
	s_setprio 1
	s_barrier
	v_mfma_f32_16x16x32_bf16 v[104:107], v[152:155], v[184:187], v[104:107]
	v_mfma_f32_16x16x32_bf16 v[108:111], v[160:163], v[184:187], v[108:111]
	v_mfma_f32_16x16x32_bf16 v[84:87], v[152:155], v[200:203], v[84:87]
	v_mfma_f32_16x16x32_bf16 v[92:95], v[160:163], v[200:203], v[92:95]
	v_mfma_f32_16x16x32_bf16 v[72:75], v[152:155], v[208:211], v[72:75]
	v_mfma_f32_16x16x32_bf16 v[76:79], v[160:163], v[208:211], v[76:79]
	v_mfma_f32_16x16x32_bf16 v[64:67], v[152:155], v[216:219], v[64:67]
	v_mfma_f32_16x16x32_bf16 v[68:71], v[160:163], v[216:219], v[68:71]
	v_mfma_f32_16x16x32_bf16 v[104:107], v[156:159], v[192:195], v[104:107]
	v_mfma_f32_16x16x32_bf16 v[108:111], v[164:167], v[192:195], v[108:111]
	v_mfma_f32_16x16x32_bf16 v[84:87], v[156:159], v[204:207], v[84:87]
	v_mfma_f32_16x16x32_bf16 v[92:95], v[164:167], v[204:207], v[92:95]
	v_mfma_f32_16x16x32_bf16 v[72:75], v[156:159], v[212:215], v[72:75]
	v_mfma_f32_16x16x32_bf16 v[76:79], v[164:167], v[212:215], v[76:79]
	v_mfma_f32_16x16x32_bf16 v[64:67], v[156:159], v[220:223], v[64:67]
	v_mfma_f32_16x16x32_bf16 v[68:71], v[164:167], v[220:223], v[68:71]
	v_mfma_f32_16x16x32_bf16 v[120:123], v[168:171], v[184:187], v[120:123]
	v_mfma_f32_16x16x32_bf16 v[124:127], v[176:179], v[184:187], v[124:127]
	v_mfma_f32_16x16x32_bf16 v[112:115], v[168:171], v[200:203], v[112:115]
	v_mfma_f32_16x16x32_bf16 v[116:119], v[176:179], v[200:203], v[116:119]
	v_mfma_f32_16x16x32_bf16 v[96:99], v[168:171], v[208:211], v[96:99]
	v_mfma_f32_16x16x32_bf16 v[100:103], v[176:179], v[208:211], v[100:103]
	v_mfma_f32_16x16x32_bf16 v[80:83], v[168:171], v[216:219], v[80:83]
	v_mfma_f32_16x16x32_bf16 v[88:91], v[176:179], v[216:219], v[88:91]
	v_mfma_f32_16x16x32_bf16 v[120:123], v[172:175], v[192:195], v[120:123]
	v_mfma_f32_16x16x32_bf16 v[124:127], v[180:183], v[192:195], v[124:127]
	v_mfma_f32_16x16x32_bf16 v[112:115], v[172:175], v[204:207], v[112:115]
	v_mfma_f32_16x16x32_bf16 v[116:119], v[180:183], v[204:207], v[116:119]
	v_mfma_f32_16x16x32_bf16 v[96:99], v[172:175], v[212:215], v[96:99]
	v_mfma_f32_16x16x32_bf16 v[100:103], v[180:183], v[212:215], v[100:103]
	s_setprio 2
	s_barrier
	v_mfma_f32_16x16x32_bf16 v[80:83], v[172:175], v[220:223], v[80:83]
	v_mfma_f32_16x16x32_bf16 v[88:91], v[180:183], v[220:223], v[88:91]
	s_setprio 0
	s_add_i32 s86, s48, s37
	s_mov_b32 m0, s86
	ds_read_b128 v[184:187], v150 offset:16384
	ds_read_b128 v[192:195], v150 offset:17408
	ds_read_b128 v[200:203], v150 offset:18432
	ds_read_b128 v[204:207], v150 offset:19456
	ds_read_b128 v[208:211], v150 offset:20480
	ds_read_b128 v[212:215], v150 offset:21504
	ds_read_b128 v[216:219], v150 offset:22528
	ds_read_b128 v[220:223], v150 offset:23552
	global_load_lds_dwordx4 v132, s[70:71] sc1
	s_add_i32 m0, s86, 0x2000
	s_add_u32 s86, s70, 0x4000
	s_addc_u32 s87, s71, 0
	s_add_i32 s88, s49, s37
	global_load_lds_dwordx4 v134, s[70:71] sc1
	s_mov_b32 m0, s88
	s_nop 0
	global_load_lds_dwordx4 v132, s[86:87] sc1
	s_add_i32 m0, s88, 0x2000
	s_nop 0
	global_load_lds_dwordx4 v134, s[86:87] sc1
	s_mov_b32 m0, s11
	s_nop 0
	global_load_lds_dwordx4 v128, s[78:79] sc1
	s_mov_b32 m0, s42
	s_nop 0
	global_load_lds_dwordx4 v130, s[78:79] sc1
	s_waitcnt vmcnt(8)
	s_waitcnt lgkmcnt(0)
	s_setprio 1
	s_barrier
	v_mfma_f32_16x16x32_bf16 v[36:39], v[152:155], v[184:187], v[36:39]
	v_mfma_f32_16x16x32_bf16 v[44:47], v[160:163], v[184:187], v[44:47]
	v_mfma_f32_16x16x32_bf16 v[20:23], v[152:155], v[200:203], v[20:23]
	v_mfma_f32_16x16x32_bf16 v[28:31], v[160:163], v[200:203], v[28:31]
	v_mfma_f32_16x16x32_bf16 v[8:11], v[152:155], v[208:211], v[8:11]
	v_mfma_f32_16x16x32_bf16 v[12:15], v[160:163], v[208:211], v[12:15]
	v_mfma_f32_16x16x32_bf16 v[0:3], v[152:155], v[216:219], v[0:3]
	v_mfma_f32_16x16x32_bf16 v[4:7], v[160:163], v[216:219], v[4:7]
	v_mfma_f32_16x16x32_bf16 v[36:39], v[156:159], v[192:195], v[36:39]
	v_mfma_f32_16x16x32_bf16 v[44:47], v[164:167], v[192:195], v[44:47]
	v_mfma_f32_16x16x32_bf16 v[20:23], v[156:159], v[204:207], v[20:23]
	v_mfma_f32_16x16x32_bf16 v[28:31], v[164:167], v[204:207], v[28:31]
	v_mfma_f32_16x16x32_bf16 v[8:11], v[156:159], v[212:215], v[8:11]
	v_mfma_f32_16x16x32_bf16 v[12:15], v[164:167], v[212:215], v[12:15]
	v_mfma_f32_16x16x32_bf16 v[0:3], v[156:159], v[220:223], v[0:3]
	v_mfma_f32_16x16x32_bf16 v[4:7], v[164:167], v[220:223], v[4:7]
	v_mfma_f32_16x16x32_bf16 v[56:59], v[168:171], v[184:187], v[56:59]
	v_mfma_f32_16x16x32_bf16 v[60:63], v[176:179], v[184:187], v[60:63]
	v_mfma_f32_16x16x32_bf16 v[48:51], v[168:171], v[200:203], v[48:51]
	v_mfma_f32_16x16x32_bf16 v[52:55], v[176:179], v[200:203], v[52:55]
	v_mfma_f32_16x16x32_bf16 v[32:35], v[168:171], v[208:211], v[32:35]
	v_mfma_f32_16x16x32_bf16 v[40:43], v[176:179], v[208:211], v[40:43]
	v_mfma_f32_16x16x32_bf16 v[16:19], v[168:171], v[216:219], v[16:19]
	v_mfma_f32_16x16x32_bf16 v[24:27], v[176:179], v[216:219], v[24:27]
	v_mfma_f32_16x16x32_bf16 v[56:59], v[172:175], v[192:195], v[56:59]
	v_mfma_f32_16x16x32_bf16 v[60:63], v[180:183], v[192:195], v[60:63]
	v_mfma_f32_16x16x32_bf16 v[48:51], v[172:175], v[204:207], v[48:51]
	v_mfma_f32_16x16x32_bf16 v[52:55], v[180:183], v[204:207], v[52:55]
	v_mfma_f32_16x16x32_bf16 v[32:35], v[172:175], v[212:215], v[32:35]
	v_mfma_f32_16x16x32_bf16 v[40:43], v[180:183], v[212:215], v[40:43]
	s_setprio 2
	s_barrier
	v_mfma_f32_16x16x32_bf16 v[16:19], v[172:175], v[220:223], v[16:19]
	v_mfma_f32_16x16x32_bf16 v[24:27], v[180:183], v[220:223], v[24:27]
	s_setprio 0
	ds_read_b128 v[152:155], v255 offset:33024
	ds_read_b128 v[156:159], v255 offset:34048
	ds_read_b128 v[160:163], v255 offset:35072
	ds_read_b128 v[164:167], v255 offset:36096
	ds_read_b128 v[168:171], v255 offset:49408
	ds_read_b128 v[172:175], v255 offset:50432
	ds_read_b128 v[176:179], v255 offset:51456
	ds_read_b128 v[180:183], v255 offset:52480
	s_add_u32 s78, s78, 0x4000
	s_addc_u32 s79, s79, 0
	s_mov_b32 m0, s43
	ds_read_b128 v[184:187], v150 offset:32768
	ds_read_b128 v[192:195], v150 offset:33792
	ds_read_b128 v[200:203], v150 offset:34816
	ds_read_b128 v[204:207], v150 offset:35840
	ds_read_b128 v[208:211], v150 offset:36864
	ds_read_b128 v[212:215], v150 offset:37888
	ds_read_b128 v[216:219], v150 offset:38912
	ds_read_b128 v[220:223], v150 offset:39936
	global_load_lds_dwordx4 v128, s[78:79] sc1
	s_mov_b32 m0, s44
	s_nop 0
	global_load_lds_dwordx4 v130, s[78:79] sc1
	s_waitcnt vmcnt(8)
	s_waitcnt lgkmcnt(0)
	s_setprio 1
	s_barrier
	v_mfma_f32_16x16x32_bf16 v[104:107], v[152:155], v[184:187], v[104:107]
	v_mfma_f32_16x16x32_bf16 v[108:111], v[160:163], v[184:187], v[108:111]
	v_mfma_f32_16x16x32_bf16 v[84:87], v[152:155], v[200:203], v[84:87]
	v_mfma_f32_16x16x32_bf16 v[92:95], v[160:163], v[200:203], v[92:95]
	v_mfma_f32_16x16x32_bf16 v[72:75], v[152:155], v[208:211], v[72:75]
	v_mfma_f32_16x16x32_bf16 v[76:79], v[160:163], v[208:211], v[76:79]
	v_mfma_f32_16x16x32_bf16 v[64:67], v[152:155], v[216:219], v[64:67]
	v_mfma_f32_16x16x32_bf16 v[68:71], v[160:163], v[216:219], v[68:71]
	v_mfma_f32_16x16x32_bf16 v[104:107], v[156:159], v[192:195], v[104:107]
	v_mfma_f32_16x16x32_bf16 v[108:111], v[164:167], v[192:195], v[108:111]
	v_mfma_f32_16x16x32_bf16 v[84:87], v[156:159], v[204:207], v[84:87]
	v_mfma_f32_16x16x32_bf16 v[92:95], v[164:167], v[204:207], v[92:95]
	v_mfma_f32_16x16x32_bf16 v[72:75], v[156:159], v[212:215], v[72:75]
	v_mfma_f32_16x16x32_bf16 v[76:79], v[164:167], v[212:215], v[76:79]
	v_mfma_f32_16x16x32_bf16 v[64:67], v[156:159], v[220:223], v[64:67]
	v_mfma_f32_16x16x32_bf16 v[68:71], v[164:167], v[220:223], v[68:71]
	v_mfma_f32_16x16x32_bf16 v[120:123], v[168:171], v[184:187], v[120:123]
	v_mfma_f32_16x16x32_bf16 v[124:127], v[176:179], v[184:187], v[124:127]
	v_mfma_f32_16x16x32_bf16 v[112:115], v[168:171], v[200:203], v[112:115]
	v_mfma_f32_16x16x32_bf16 v[116:119], v[176:179], v[200:203], v[116:119]
	v_mfma_f32_16x16x32_bf16 v[96:99], v[168:171], v[208:211], v[96:99]
	v_mfma_f32_16x16x32_bf16 v[100:103], v[176:179], v[208:211], v[100:103]
	v_mfma_f32_16x16x32_bf16 v[80:83], v[168:171], v[216:219], v[80:83]
	v_mfma_f32_16x16x32_bf16 v[88:91], v[176:179], v[216:219], v[88:91]
	v_mfma_f32_16x16x32_bf16 v[120:123], v[172:175], v[192:195], v[120:123]
	v_mfma_f32_16x16x32_bf16 v[124:127], v[180:183], v[192:195], v[124:127]
	v_mfma_f32_16x16x32_bf16 v[112:115], v[172:175], v[204:207], v[112:115]
	v_mfma_f32_16x16x32_bf16 v[116:119], v[180:183], v[204:207], v[116:119]
	v_mfma_f32_16x16x32_bf16 v[96:99], v[172:175], v[212:215], v[96:99]
	v_mfma_f32_16x16x32_bf16 v[100:103], v[180:183], v[212:215], v[100:103]
	s_setprio 2
	s_barrier
	v_mfma_f32_16x16x32_bf16 v[80:83], v[172:175], v[220:223], v[80:83]
	v_mfma_f32_16x16x32_bf16 v[88:91], v[180:183], v[220:223], v[88:91]
	s_setprio 0
	s_add_u32 s78, s70, 0x8000
	s_addc_u32 s79, s71, 0
	s_add_i32 s86, s50, s37
	s_mov_b32 m0, s86
	ds_read_b128 v[184:187], v150 offset:49152
	ds_read_b128 v[192:195], v150 offset:50176
	ds_read_b128 v[200:203], v150 offset:51200
	ds_read_b128 v[204:207], v150 offset:52224
	ds_read_b128 v[208:211], v150 offset:53248
	ds_read_b128 v[212:215], v150 offset:54272
	ds_read_b128 v[216:219], v150 offset:55296
	ds_read_b128 v[220:223], v150 offset:56320
	global_load_lds_dwordx4 v132, s[78:79] sc1
	s_add_i32 m0, s86, 0x2000
	s_add_u32 s70, s70, 0xc000
	global_load_lds_dwordx4 v134, s[78:79] sc1
	s_addc_u32 s71, s71, 0
	s_add_i32 s78, s51, s37
	s_mov_b32 m0, s78
	s_nop 0
	global_load_lds_dwordx4 v132, s[70:71] sc1
	s_add_i32 m0, s78, 0x2000
	s_nop 0
	global_load_lds_dwordx4 v134, s[70:71] sc1
	s_mov_b32 m0, s17
	s_nop 0
	global_load_lds_dwordx4 v128, s[66:67] sc1
	s_mov_b32 m0, s46
	s_nop 0
	global_load_lds_dwordx4 v130, s[66:67] sc1
	s_waitcnt vmcnt(8)
	s_waitcnt lgkmcnt(0)
	s_setprio 1
	s_barrier
	v_mfma_f32_16x16x32_bf16 v[36:39], v[152:155], v[184:187], v[36:39]
	v_mfma_f32_16x16x32_bf16 v[44:47], v[160:163], v[184:187], v[44:47]
	v_mfma_f32_16x16x32_bf16 v[20:23], v[152:155], v[200:203], v[20:23]
	v_mfma_f32_16x16x32_bf16 v[28:31], v[160:163], v[200:203], v[28:31]
	v_mfma_f32_16x16x32_bf16 v[8:11], v[152:155], v[208:211], v[8:11]
	v_mfma_f32_16x16x32_bf16 v[12:15], v[160:163], v[208:211], v[12:15]
	v_mfma_f32_16x16x32_bf16 v[0:3], v[152:155], v[216:219], v[0:3]
	v_mfma_f32_16x16x32_bf16 v[4:7], v[160:163], v[216:219], v[4:7]
	v_mfma_f32_16x16x32_bf16 v[36:39], v[156:159], v[192:195], v[36:39]
	v_mfma_f32_16x16x32_bf16 v[44:47], v[164:167], v[192:195], v[44:47]
	v_mfma_f32_16x16x32_bf16 v[20:23], v[156:159], v[204:207], v[20:23]
	v_mfma_f32_16x16x32_bf16 v[28:31], v[164:167], v[204:207], v[28:31]
	v_mfma_f32_16x16x32_bf16 v[8:11], v[156:159], v[212:215], v[8:11]
	v_mfma_f32_16x16x32_bf16 v[12:15], v[164:167], v[212:215], v[12:15]
	v_mfma_f32_16x16x32_bf16 v[0:3], v[156:159], v[220:223], v[0:3]
	v_mfma_f32_16x16x32_bf16 v[4:7], v[164:167], v[220:223], v[4:7]
	v_mfma_f32_16x16x32_bf16 v[56:59], v[168:171], v[184:187], v[56:59]
	v_mfma_f32_16x16x32_bf16 v[60:63], v[176:179], v[184:187], v[60:63]
	v_mfma_f32_16x16x32_bf16 v[48:51], v[168:171], v[200:203], v[48:51]
	v_mfma_f32_16x16x32_bf16 v[52:55], v[176:179], v[200:203], v[52:55]
	v_mfma_f32_16x16x32_bf16 v[32:35], v[168:171], v[208:211], v[32:35]
	v_mfma_f32_16x16x32_bf16 v[40:43], v[176:179], v[208:211], v[40:43]
	v_mfma_f32_16x16x32_bf16 v[16:19], v[168:171], v[216:219], v[16:19]
	v_mfma_f32_16x16x32_bf16 v[24:27], v[176:179], v[216:219], v[24:27]
	v_mfma_f32_16x16x32_bf16 v[56:59], v[172:175], v[192:195], v[56:59]
	v_mfma_f32_16x16x32_bf16 v[60:63], v[180:183], v[192:195], v[60:63]
	v_mfma_f32_16x16x32_bf16 v[48:51], v[172:175], v[204:207], v[48:51]
	v_mfma_f32_16x16x32_bf16 v[52:55], v[180:183], v[204:207], v[52:55]
	v_mfma_f32_16x16x32_bf16 v[32:35], v[172:175], v[212:215], v[32:35]
	v_mfma_f32_16x16x32_bf16 v[40:43], v[180:183], v[212:215], v[40:43]
	s_setprio 2
	s_barrier
	v_mfma_f32_16x16x32_bf16 v[16:19], v[172:175], v[220:223], v[16:19]
	v_mfma_f32_16x16x32_bf16 v[24:27], v[180:183], v[220:223], v[24:27]
	s_setprio 0
	s_add_i32 s85, s85, 2
	s_add_u32 s64, s64, 0x10000
	s_addc_u32 s65, s65, 0
	s_cmp_gt_u32 s85, 13
	s_cbranch_scc0 .LBB0_976
	s_add_u32 s64, s55, 0xffff0000
	s_addc_u32 s65, s69, -1
	s_andn2_b64 vcc, exec, s[8:9]
	s_cbranch_vccnz .LBB0_967
	s_mov_b32 s16, s38
	s_mov_b32 s10, s40
	s_mov_b64 s[18:19], s[62:63]
	s_mov_b32 s47, s54
	s_andn2_b64 vcc, exec, s[6:7]
	s_cbranch_vccnz .LBB0_968

.LBB0_1028:
	s_add_u32 s77, s62, 0x10000
	s_addc_u32 s82, s63, 0
	s_ashr_i32 s65, s64, 31
	s_lshl_b64 s[62:63], s[64:65], 19
	s_add_u32 s62, s38, s62
	s_addc_u32 s63, s39, s63
	s_lshl_b32 s70, s18, 2
	s_ashr_i32 s41, s40, 31
	s_ashr_i32 s71, s70, 31
	s_lshl_b64 s[78:79], s[40:41], 19
	s_lshl_b64 s[70:71], s[70:71], 15
	s_add_u32 s41, s60, s70
	s_addc_u32 s65, s33, s71
	s_add_u32 s41, s41, s78
	s_addc_u32 s65, s65, s79
	s_add_u32 s70, s41, 0x10000
	s_addc_u32 s71, s65, 0
	s_and_b64 s[10:11], s[10:11], exec
	s_cselect_b32 s83, s67, s71
	s_cselect_b32 s84, s66, s70
	s_cselect_b32 s85, s63, s65
	s_cselect_b32 s86, s62, s41
	v_lshl_add_u64 v[144:145], s[56:57], 0, v[136:137]
	v_lshl_add_u64 v[146:147], s[56:57], 0, v[138:139]
	s_mov_b32 s87, -2
	s_mov_b64 s[10:11], 0
	v_add_u32_e32 v255, 0x10000, v151
	s_add_u32 s41, s56, s10
	s_addc_u32 s65, s57, s11
	s_add_u32 s41, s41, 0x10000
	ds_read_b128 v[156:159], v255 offset:256
	ds_read_b128 v[160:163], v255 offset:1280
	ds_read_b128 v[164:167], v255 offset:2304
	ds_read_b128 v[168:171], v255 offset:3328
	ds_read_b128 v[172:175], v255 offset:16640
	ds_read_b128 v[176:179], v255 offset:17664
	ds_read_b128 v[180:183], v255 offset:18688
	ds_read_b128 v[184:187], v255 offset:19712
	s_addc_u32 s65, s65, 0
	s_add_u32 s70, s77, s10
	s_addc_u32 s71, s82, s11
	s_cmp_eq_u32 s10, 0x70000
	s_cselect_b32 s80, s84, s41
	s_cselect_b32 s81, s83, s65
	s_cselect_b32 s78, s86, s70
	s_cselect_b32 s79, s85, s71
	s_add_u32 s70, s80, 0x8000
	s_addc_u32 s71, s81, 0
	s_add_i32 s41, s42, 0xc000
	s_add_u32 s98, s56, s10
	s_addc_u32 s99, s57, s11
	s_mov_b32 m0, s41
	s_add_i32 s65, s42, 0xe000
	ds_read_b128 v[192:195], v154
	ds_read_b128 v[200:203], v154 offset:1024
	ds_read_b128 v[204:207], v154 offset:2048
	ds_read_b128 v[208:211], v154 offset:3072
	ds_read_b128 v[212:215], v154 offset:4096
	ds_read_b128 v[216:219], v154 offset:5120
	ds_read_b128 v[220:223], v154 offset:6144
	ds_read_b128 v[224:227], v154 offset:7168
	global_load_lds_dwordx4 v136, s[98:99] sc1
	s_mov_b32 m0, s65
	s_nop 0
	global_load_lds_dwordx4 v138, s[98:99] sc1
	s_waitcnt vmcnt(8)
	s_waitcnt lgkmcnt(0)
	s_setprio 1
	s_barrier
	v_mfma_f32_16x16x32_bf16 v[112:115], v[156:159], v[192:195], 0
	v_mfma_f32_16x16x32_bf16 v[116:119], v[164:167], v[192:195], 0
	v_mfma_f32_16x16x32_bf16 v[96:99], v[156:159], v[204:207], 0
	v_mfma_f32_16x16x32_bf16 v[100:103], v[164:167], v[204:207], 0
	v_mfma_f32_16x16x32_bf16 v[80:83], v[156:159], v[212:215], 0
	v_mfma_f32_16x16x32_bf16 v[84:87], v[164:167], v[212:215], 0
	v_mfma_f32_16x16x32_bf16 v[64:67], v[156:159], v[220:223], 0
	v_mfma_f32_16x16x32_bf16 v[68:71], v[164:167], v[220:223], 0
	v_mfma_f32_16x16x32_bf16 v[112:115], v[160:163], v[200:203], v[112:115]
	v_mfma_f32_16x16x32_bf16 v[116:119], v[168:171], v[200:203], v[116:119]
	v_mfma_f32_16x16x32_bf16 v[96:99], v[160:163], v[208:211], v[96:99]
	v_mfma_f32_16x16x32_bf16 v[100:103], v[168:171], v[208:211], v[100:103]
	v_mfma_f32_16x16x32_bf16 v[80:83], v[160:163], v[216:219], v[80:83]
	v_mfma_f32_16x16x32_bf16 v[84:87], v[168:171], v[216:219], v[84:87]
	v_mfma_f32_16x16x32_bf16 v[64:67], v[160:163], v[224:227], v[64:67]
	v_mfma_f32_16x16x32_bf16 v[68:71], v[168:171], v[224:227], v[68:71]
	v_mfma_f32_16x16x32_bf16 v[120:123], v[172:175], v[192:195], 0
	v_mfma_f32_16x16x32_bf16 v[124:127], v[180:183], v[192:195], 0
	v_mfma_f32_16x16x32_bf16 v[104:107], v[172:175], v[204:207], 0
	v_mfma_f32_16x16x32_bf16 v[108:111], v[180:183], v[204:207], 0
	v_mfma_f32_16x16x32_bf16 v[88:91], v[172:175], v[212:215], 0
	v_mfma_f32_16x16x32_bf16 v[92:95], v[180:183], v[212:215], 0
	v_mfma_f32_16x16x32_bf16 v[72:75], v[172:175], v[220:223], 0
	v_mfma_f32_16x16x32_bf16 v[76:79], v[180:183], v[220:223], 0
	v_mfma_f32_16x16x32_bf16 v[120:123], v[176:179], v[200:203], v[120:123]
	v_mfma_f32_16x16x32_bf16 v[124:127], v[184:187], v[200:203], v[124:127]
	v_mfma_f32_16x16x32_bf16 v[104:107], v[176:179], v[208:211], v[104:107]
	v_mfma_f32_16x16x32_bf16 v[108:111], v[184:187], v[208:211], v[108:111]
	v_mfma_f32_16x16x32_bf16 v[88:91], v[176:179], v[216:219], v[88:91]
	v_mfma_f32_16x16x32_bf16 v[92:95], v[184:187], v[216:219], v[92:95]
	s_setprio 2
	s_barrier
	v_mfma_f32_16x16x32_bf16 v[72:75], v[176:179], v[224:227], v[72:75]
	v_mfma_f32_16x16x32_bf16 v[76:79], v[184:187], v[224:227], v[76:79]
	s_setprio 0
	s_add_i32 s88, s50, s35
	s_mov_b32 m0, s88
	ds_read_b128 v[192:195], v154 offset:16384
	ds_read_b128 v[200:203], v154 offset:17408
	ds_read_b128 v[204:207], v154 offset:18432
	ds_read_b128 v[208:211], v154 offset:19456
	ds_read_b128 v[212:215], v154 offset:20480
	ds_read_b128 v[216:219], v154 offset:21504
	ds_read_b128 v[220:223], v154 offset:22528
	ds_read_b128 v[224:227], v154 offset:23552
	global_load_lds_dwordx4 v132, s[78:79] sc1
	s_add_i32 m0, s88, 0x2000
	s_add_u32 s88, s78, 0x4000
	s_addc_u32 s89, s79, 0
	s_add_i32 s90, s51, s35
	global_load_lds_dwordx4 v134, s[78:79] sc1
	s_mov_b32 m0, s90
	s_nop 0
	global_load_lds_dwordx4 v132, s[88:89] sc1
	s_add_i32 m0, s90, 0x2000
	s_nop 0
	global_load_lds_dwordx4 v134, s[88:89] sc1
	s_mov_b32 m0, s42
	s_nop 0
	global_load_lds_dwordx4 v128, s[80:81] sc1
	s_mov_b32 m0, s43
	s_nop 0
	global_load_lds_dwordx4 v130, s[80:81] sc1
	s_waitcnt vmcnt(8)
	s_waitcnt lgkmcnt(0)
	s_setprio 1
	s_barrier
	v_mfma_f32_16x16x32_bf16 v[48:51], v[156:159], v[192:195], 0
	v_mfma_f32_16x16x32_bf16 v[52:55], v[164:167], v[192:195], 0
	v_mfma_f32_16x16x32_bf16 v[32:35], v[156:159], v[204:207], 0
	v_mfma_f32_16x16x32_bf16 v[36:39], v[164:167], v[204:207], 0
	v_mfma_f32_16x16x32_bf16 v[16:19], v[156:159], v[212:215], 0
	v_mfma_f32_16x16x32_bf16 v[20:23], v[164:167], v[212:215], 0
	v_mfma_f32_16x16x32_bf16 v[0:3], v[156:159], v[220:223], 0
	v_mfma_f32_16x16x32_bf16 v[4:7], v[164:167], v[220:223], 0
	v_mfma_f32_16x16x32_bf16 v[48:51], v[160:163], v[200:203], v[48:51]
	v_mfma_f32_16x16x32_bf16 v[52:55], v[168:171], v[200:203], v[52:55]
	v_mfma_f32_16x16x32_bf16 v[32:35], v[160:163], v[208:211], v[32:35]
	v_mfma_f32_16x16x32_bf16 v[36:39], v[168:171], v[208:211], v[36:39]
	v_mfma_f32_16x16x32_bf16 v[16:19], v[160:163], v[216:219], v[16:19]
	v_mfma_f32_16x16x32_bf16 v[20:23], v[168:171], v[216:219], v[20:23]
	v_mfma_f32_16x16x32_bf16 v[0:3], v[160:163], v[224:227], v[0:3]
	v_mfma_f32_16x16x32_bf16 v[4:7], v[168:171], v[224:227], v[4:7]
	v_mfma_f32_16x16x32_bf16 v[56:59], v[172:175], v[192:195], 0
	v_mfma_f32_16x16x32_bf16 v[60:63], v[180:183], v[192:195], 0
	v_mfma_f32_16x16x32_bf16 v[40:43], v[172:175], v[204:207], 0
	v_mfma_f32_16x16x32_bf16 v[44:47], v[180:183], v[204:207], 0
	v_mfma_f32_16x16x32_bf16 v[24:27], v[172:175], v[212:215], 0
	v_mfma_f32_16x16x32_bf16 v[28:31], v[180:183], v[212:215], 0
	v_mfma_f32_16x16x32_bf16 v[8:11], v[172:175], v[220:223], 0
	v_mfma_f32_16x16x32_bf16 v[12:15], v[180:183], v[220:223], 0
	v_mfma_f32_16x16x32_bf16 v[56:59], v[176:179], v[200:203], v[56:59]
	v_mfma_f32_16x16x32_bf16 v[60:63], v[184:187], v[200:203], v[60:63]
	v_mfma_f32_16x16x32_bf16 v[40:43], v[176:179], v[208:211], v[40:43]
	v_mfma_f32_16x16x32_bf16 v[44:47], v[184:187], v[208:211], v[44:47]
	v_mfma_f32_16x16x32_bf16 v[24:27], v[176:179], v[216:219], v[24:27]
	v_mfma_f32_16x16x32_bf16 v[28:31], v[184:187], v[216:219], v[28:31]
	s_setprio 2
	s_barrier
	v_mfma_f32_16x16x32_bf16 v[8:11], v[176:179], v[224:227], v[8:11]
	v_mfma_f32_16x16x32_bf16 v[12:15], v[184:187], v[224:227], v[12:15]
	s_setprio 0
	ds_read_b128 v[156:159], v255 offset:33024
	ds_read_b128 v[160:163], v255 offset:34048
	ds_read_b128 v[164:167], v255 offset:35072
	ds_read_b128 v[168:171], v255 offset:36096
	ds_read_b128 v[172:175], v255 offset:49408
	ds_read_b128 v[176:179], v255 offset:50432
	ds_read_b128 v[180:183], v255 offset:51456
	ds_read_b128 v[184:187], v255 offset:52480
	s_add_u32 s80, s80, 0x4000
	s_addc_u32 s81, s81, 0
	s_mov_b32 m0, s44
	ds_read_b128 v[192:195], v154 offset:32768
	ds_read_b128 v[200:203], v154 offset:33792
	ds_read_b128 v[204:207], v154 offset:34816
	ds_read_b128 v[208:211], v154 offset:35840
	ds_read_b128 v[212:215], v154 offset:36864
	ds_read_b128 v[216:219], v154 offset:37888
	ds_read_b128 v[220:223], v154 offset:38912
	ds_read_b128 v[224:227], v154 offset:39936
	global_load_lds_dwordx4 v128, s[80:81] sc1
	s_mov_b32 m0, s45
	s_nop 0
	global_load_lds_dwordx4 v130, s[80:81] sc1
	s_waitcnt vmcnt(8)
	s_waitcnt lgkmcnt(0)
	s_setprio 1
	s_barrier
	v_mfma_f32_16x16x32_bf16 v[112:115], v[156:159], v[192:195], v[112:115]
	v_mfma_f32_16x16x32_bf16 v[116:119], v[164:167], v[192:195], v[116:119]
	v_mfma_f32_16x16x32_bf16 v[96:99], v[156:159], v[204:207], v[96:99]
	v_mfma_f32_16x16x32_bf16 v[100:103], v[164:167], v[204:207], v[100:103]
	v_mfma_f32_16x16x32_bf16 v[80:83], v[156:159], v[212:215], v[80:83]
	v_mfma_f32_16x16x32_bf16 v[84:87], v[164:167], v[212:215], v[84:87]
	v_mfma_f32_16x16x32_bf16 v[64:67], v[156:159], v[220:223], v[64:67]
	v_mfma_f32_16x16x32_bf16 v[68:71], v[164:167], v[220:223], v[68:71]
	v_mfma_f32_16x16x32_bf16 v[112:115], v[160:163], v[200:203], v[112:115]
	v_mfma_f32_16x16x32_bf16 v[116:119], v[168:171], v[200:203], v[116:119]
	v_mfma_f32_16x16x32_bf16 v[96:99], v[160:163], v[208:211], v[96:99]
	v_mfma_f32_16x16x32_bf16 v[100:103], v[168:171], v[208:211], v[100:103]
	v_mfma_f32_16x16x32_bf16 v[80:83], v[160:163], v[216:219], v[80:83]
	v_mfma_f32_16x16x32_bf16 v[84:87], v[168:171], v[216:219], v[84:87]
	v_mfma_f32_16x16x32_bf16 v[64:67], v[160:163], v[224:227], v[64:67]
	v_mfma_f32_16x16x32_bf16 v[68:71], v[168:171], v[224:227], v[68:71]
	v_mfma_f32_16x16x32_bf16 v[120:123], v[172:175], v[192:195], v[120:123]
	v_mfma_f32_16x16x32_bf16 v[124:127], v[180:183], v[192:195], v[124:127]
	v_mfma_f32_16x16x32_bf16 v[104:107], v[172:175], v[204:207], v[104:107]
	v_mfma_f32_16x16x32_bf16 v[108:111], v[180:183], v[204:207], v[108:111]
	v_mfma_f32_16x16x32_bf16 v[88:91], v[172:175], v[212:215], v[88:91]
	v_mfma_f32_16x16x32_bf16 v[92:95], v[180:183], v[212:215], v[92:95]
	v_mfma_f32_16x16x32_bf16 v[72:75], v[172:175], v[220:223], v[72:75]
	v_mfma_f32_16x16x32_bf16 v[76:79], v[180:183], v[220:223], v[76:79]
	v_mfma_f32_16x16x32_bf16 v[120:123], v[176:179], v[200:203], v[120:123]
	v_mfma_f32_16x16x32_bf16 v[124:127], v[184:187], v[200:203], v[124:127]
	v_mfma_f32_16x16x32_bf16 v[104:107], v[176:179], v[208:211], v[104:107]
	v_mfma_f32_16x16x32_bf16 v[108:111], v[184:187], v[208:211], v[108:111]
	v_mfma_f32_16x16x32_bf16 v[88:91], v[176:179], v[216:219], v[88:91]
	v_mfma_f32_16x16x32_bf16 v[92:95], v[184:187], v[216:219], v[92:95]
	s_setprio 2
	s_barrier
	v_mfma_f32_16x16x32_bf16 v[72:75], v[176:179], v[224:227], v[72:75]
	v_mfma_f32_16x16x32_bf16 v[76:79], v[184:187], v[224:227], v[76:79]
	s_setprio 0
	s_add_u32 s80, s78, 0x8000
	s_addc_u32 s81, s79, 0
	s_add_i32 s88, s54, s35
	s_mov_b32 m0, s88
	ds_read_b128 v[192:195], v154 offset:49152
	ds_read_b128 v[200:203], v154 offset:50176
	ds_read_b128 v[204:207], v154 offset:51200
	ds_read_b128 v[208:211], v154 offset:52224
	ds_read_b128 v[212:215], v154 offset:53248
	ds_read_b128 v[216:219], v154 offset:54272
	ds_read_b128 v[220:223], v154 offset:55296
	ds_read_b128 v[224:227], v154 offset:56320
	global_load_lds_dwordx4 v132, s[80:81] sc1
	s_add_i32 m0, s88, 0x2000
	s_add_u32 s78, s78, 0xc000
	global_load_lds_dwordx4 v134, s[80:81] sc1
	s_addc_u32 s79, s79, 0
	s_add_i32 s80, s55, s35
	s_mov_b32 m0, s80
	s_nop 0
	global_load_lds_dwordx4 v132, s[78:79] sc1
	s_add_i32 m0, s80, 0x2000
	s_nop 0
	global_load_lds_dwordx4 v134, s[78:79] sc1
	s_mov_b32 m0, s47
	s_nop 0
	global_load_lds_dwordx4 v128, s[70:71] sc1
	s_mov_b32 m0, s48
	s_nop 0
	global_load_lds_dwordx4 v130, s[70:71] sc1
	s_waitcnt vmcnt(8)
	s_waitcnt lgkmcnt(0)
	s_setprio 1
	s_barrier
	v_mfma_f32_16x16x32_bf16 v[48:51], v[156:159], v[192:195], v[48:51]
	v_mfma_f32_16x16x32_bf16 v[52:55], v[164:167], v[192:195], v[52:55]
	v_mfma_f32_16x16x32_bf16 v[32:35], v[156:159], v[204:207], v[32:35]
	v_mfma_f32_16x16x32_bf16 v[36:39], v[164:167], v[204:207], v[36:39]
	v_mfma_f32_16x16x32_bf16 v[16:19], v[156:159], v[212:215], v[16:19]
	v_mfma_f32_16x16x32_bf16 v[20:23], v[164:167], v[212:215], v[20:23]
	v_mfma_f32_16x16x32_bf16 v[0:3], v[156:159], v[220:223], v[0:3]
	v_mfma_f32_16x16x32_bf16 v[4:7], v[164:167], v[220:223], v[4:7]
	v_mfma_f32_16x16x32_bf16 v[48:51], v[160:163], v[200:203], v[48:51]
	v_mfma_f32_16x16x32_bf16 v[52:55], v[168:171], v[200:203], v[52:55]
	v_mfma_f32_16x16x32_bf16 v[32:35], v[160:163], v[208:211], v[32:35]
	v_mfma_f32_16x16x32_bf16 v[36:39], v[168:171], v[208:211], v[36:39]
	v_mfma_f32_16x16x32_bf16 v[16:19], v[160:163], v[216:219], v[16:19]
	v_mfma_f32_16x16x32_bf16 v[20:23], v[168:171], v[216:219], v[20:23]
	v_mfma_f32_16x16x32_bf16 v[0:3], v[160:163], v[224:227], v[0:3]
	v_mfma_f32_16x16x32_bf16 v[4:7], v[168:171], v[224:227], v[4:7]
	v_mfma_f32_16x16x32_bf16 v[56:59], v[172:175], v[192:195], v[56:59]
	v_mfma_f32_16x16x32_bf16 v[60:63], v[180:183], v[192:195], v[60:63]
	v_mfma_f32_16x16x32_bf16 v[40:43], v[172:175], v[204:207], v[40:43]
	v_mfma_f32_16x16x32_bf16 v[44:47], v[180:183], v[204:207], v[44:47]
	v_mfma_f32_16x16x32_bf16 v[24:27], v[172:175], v[212:215], v[24:27]
	v_mfma_f32_16x16x32_bf16 v[28:31], v[180:183], v[212:215], v[28:31]
	v_mfma_f32_16x16x32_bf16 v[8:11], v[172:175], v[220:223], v[8:11]
	v_mfma_f32_16x16x32_bf16 v[12:15], v[180:183], v[220:223], v[12:15]
	v_mfma_f32_16x16x32_bf16 v[56:59], v[176:179], v[200:203], v[56:59]
	v_mfma_f32_16x16x32_bf16 v[60:63], v[184:187], v[200:203], v[60:63]
	v_mfma_f32_16x16x32_bf16 v[40:43], v[176:179], v[208:211], v[40:43]
	v_mfma_f32_16x16x32_bf16 v[44:47], v[184:187], v[208:211], v[44:47]
	v_mfma_f32_16x16x32_bf16 v[24:27], v[176:179], v[216:219], v[24:27]
	v_mfma_f32_16x16x32_bf16 v[28:31], v[184:187], v[216:219], v[28:31]
	s_setprio 2
	s_barrier
	v_mfma_f32_16x16x32_bf16 v[8:11], v[176:179], v[224:227], v[8:11]
	v_mfma_f32_16x16x32_bf16 v[12:15], v[184:187], v[224:227], v[12:15]
	s_setprio 0
	s_add_i32 s87, s87, 2
	s_add_u32 s10, s10, 0x10000
	s_addc_u32 s11, s11, 0
	s_cmp_gt_u32 s87, 13
.LBB0_1029:
	s_add_u32 s41, s56, s10
	s_addc_u32 s65, s57, s11
	s_add_u32 s41, s41, 0x10000
	ds_read_b128 v[156:159], v255 offset:256
	ds_read_b128 v[160:163], v255 offset:1280
	ds_read_b128 v[164:167], v255 offset:2304
	ds_read_b128 v[168:171], v255 offset:3328
	ds_read_b128 v[172:175], v255 offset:16640
	ds_read_b128 v[176:179], v255 offset:17664
	ds_read_b128 v[180:183], v255 offset:18688
	ds_read_b128 v[184:187], v255 offset:19712
	s_addc_u32 s65, s65, 0
	s_add_u32 s70, s77, s10
	s_addc_u32 s71, s82, s11
	s_cmp_eq_u32 s10, 0x70000
	s_cselect_b32 s80, s84, s41
	s_cselect_b32 s81, s83, s65
	s_cselect_b32 s78, s86, s70
	s_cselect_b32 s79, s85, s71
	s_add_u32 s70, s80, 0x8000
	s_addc_u32 s71, s81, 0
	s_add_i32 s41, s42, 0xc000
	s_add_u32 s98, s56, s10
	s_addc_u32 s99, s57, s11
	s_mov_b32 m0, s41
	s_add_i32 s65, s42, 0xe000
	ds_read_b128 v[192:195], v154
	ds_read_b128 v[200:203], v154 offset:1024
	ds_read_b128 v[204:207], v154 offset:2048
	ds_read_b128 v[208:211], v154 offset:3072
	ds_read_b128 v[212:215], v154 offset:4096
	ds_read_b128 v[216:219], v154 offset:5120
	ds_read_b128 v[220:223], v154 offset:6144
	ds_read_b128 v[224:227], v154 offset:7168
	global_load_lds_dwordx4 v136, s[98:99] sc1
	s_mov_b32 m0, s65
	s_nop 0
	global_load_lds_dwordx4 v138, s[98:99] sc1
	s_waitcnt vmcnt(8)
	s_waitcnt lgkmcnt(0)
	s_setprio 1
	s_barrier
	v_mfma_f32_16x16x32_bf16 v[112:115], v[156:159], v[192:195], v[112:115]
	v_mfma_f32_16x16x32_bf16 v[116:119], v[164:167], v[192:195], v[116:119]
	v_mfma_f32_16x16x32_bf16 v[96:99], v[156:159], v[204:207], v[96:99]
	v_mfma_f32_16x16x32_bf16 v[100:103], v[164:167], v[204:207], v[100:103]
	v_mfma_f32_16x16x32_bf16 v[80:83], v[156:159], v[212:215], v[80:83]
	v_mfma_f32_16x16x32_bf16 v[84:87], v[164:167], v[212:215], v[84:87]
	v_mfma_f32_16x16x32_bf16 v[64:67], v[156:159], v[220:223], v[64:67]
	v_mfma_f32_16x16x32_bf16 v[68:71], v[164:167], v[220:223], v[68:71]
	v_mfma_f32_16x16x32_bf16 v[112:115], v[160:163], v[200:203], v[112:115]
	v_mfma_f32_16x16x32_bf16 v[116:119], v[168:171], v[200:203], v[116:119]
	v_mfma_f32_16x16x32_bf16 v[96:99], v[160:163], v[208:211], v[96:99]
	v_mfma_f32_16x16x32_bf16 v[100:103], v[168:171], v[208:211], v[100:103]
	v_mfma_f32_16x16x32_bf16 v[80:83], v[160:163], v[216:219], v[80:83]
	v_mfma_f32_16x16x32_bf16 v[84:87], v[168:171], v[216:219], v[84:87]
	v_mfma_f32_16x16x32_bf16 v[64:67], v[160:163], v[224:227], v[64:67]
	v_mfma_f32_16x16x32_bf16 v[68:71], v[168:171], v[224:227], v[68:71]
	v_mfma_f32_16x16x32_bf16 v[120:123], v[172:175], v[192:195], v[120:123]
	v_mfma_f32_16x16x32_bf16 v[124:127], v[180:183], v[192:195], v[124:127]
	v_mfma_f32_16x16x32_bf16 v[104:107], v[172:175], v[204:207], v[104:107]
	v_mfma_f32_16x16x32_bf16 v[108:111], v[180:183], v[204:207], v[108:111]
	v_mfma_f32_16x16x32_bf16 v[88:91], v[172:175], v[212:215], v[88:91]
	v_mfma_f32_16x16x32_bf16 v[92:95], v[180:183], v[212:215], v[92:95]
	v_mfma_f32_16x16x32_bf16 v[72:75], v[172:175], v[220:223], v[72:75]
	v_mfma_f32_16x16x32_bf16 v[76:79], v[180:183], v[220:223], v[76:79]
	v_mfma_f32_16x16x32_bf16 v[120:123], v[176:179], v[200:203], v[120:123]
	v_mfma_f32_16x16x32_bf16 v[124:127], v[184:187], v[200:203], v[124:127]
	v_mfma_f32_16x16x32_bf16 v[104:107], v[176:179], v[208:211], v[104:107]
	v_mfma_f32_16x16x32_bf16 v[108:111], v[184:187], v[208:211], v[108:111]
	v_mfma_f32_16x16x32_bf16 v[88:91], v[176:179], v[216:219], v[88:91]
	v_mfma_f32_16x16x32_bf16 v[92:95], v[184:187], v[216:219], v[92:95]
	s_setprio 2
	s_barrier
	v_mfma_f32_16x16x32_bf16 v[72:75], v[176:179], v[224:227], v[72:75]
	v_mfma_f32_16x16x32_bf16 v[76:79], v[184:187], v[224:227], v[76:79]
	s_setprio 0
	s_add_i32 s88, s50, s35
	s_mov_b32 m0, s88
	ds_read_b128 v[192:195], v154 offset:16384
	ds_read_b128 v[200:203], v154 offset:17408
	ds_read_b128 v[204:207], v154 offset:18432
	ds_read_b128 v[208:211], v154 offset:19456
	ds_read_b128 v[212:215], v154 offset:20480
	ds_read_b128 v[216:219], v154 offset:21504
	ds_read_b128 v[220:223], v154 offset:22528
	ds_read_b128 v[224:227], v154 offset:23552
	global_load_lds_dwordx4 v132, s[78:79] sc1
	s_add_i32 m0, s88, 0x2000
	s_add_u32 s88, s78, 0x4000
	s_addc_u32 s89, s79, 0
	s_add_i32 s90, s51, s35
	global_load_lds_dwordx4 v134, s[78:79] sc1
	s_mov_b32 m0, s90
	s_nop 0
	global_load_lds_dwordx4 v132, s[88:89] sc1
	s_add_i32 m0, s90, 0x2000
	s_nop 0
	global_load_lds_dwordx4 v134, s[88:89] sc1
	s_mov_b32 m0, s42
	s_nop 0
	global_load_lds_dwordx4 v128, s[80:81] sc1
	s_mov_b32 m0, s43
	s_nop 0
	global_load_lds_dwordx4 v130, s[80:81] sc1
	s_waitcnt vmcnt(8)
	s_waitcnt lgkmcnt(0)
	s_setprio 1
	s_barrier
	v_mfma_f32_16x16x32_bf16 v[48:51], v[156:159], v[192:195], v[48:51]
	v_mfma_f32_16x16x32_bf16 v[52:55], v[164:167], v[192:195], v[52:55]
	v_mfma_f32_16x16x32_bf16 v[32:35], v[156:159], v[204:207], v[32:35]
	v_mfma_f32_16x16x32_bf16 v[36:39], v[164:167], v[204:207], v[36:39]
	v_mfma_f32_16x16x32_bf16 v[16:19], v[156:159], v[212:215], v[16:19]
	v_mfma_f32_16x16x32_bf16 v[20:23], v[164:167], v[212:215], v[20:23]
	v_mfma_f32_16x16x32_bf16 v[0:3], v[156:159], v[220:223], v[0:3]
	v_mfma_f32_16x16x32_bf16 v[4:7], v[164:167], v[220:223], v[4:7]
	v_mfma_f32_16x16x32_bf16 v[48:51], v[160:163], v[200:203], v[48:51]
	v_mfma_f32_16x16x32_bf16 v[52:55], v[168:171], v[200:203], v[52:55]
	v_mfma_f32_16x16x32_bf16 v[32:35], v[160:163], v[208:211], v[32:35]
	v_mfma_f32_16x16x32_bf16 v[36:39], v[168:171], v[208:211], v[36:39]
	v_mfma_f32_16x16x32_bf16 v[16:19], v[160:163], v[216:219], v[16:19]
	v_mfma_f32_16x16x32_bf16 v[20:23], v[168:171], v[216:219], v[20:23]
	v_mfma_f32_16x16x32_bf16 v[0:3], v[160:163], v[224:227], v[0:3]
	v_mfma_f32_16x16x32_bf16 v[4:7], v[168:171], v[224:227], v[4:7]
	v_mfma_f32_16x16x32_bf16 v[56:59], v[172:175], v[192:195], v[56:59]
	v_mfma_f32_16x16x32_bf16 v[60:63], v[180:183], v[192:195], v[60:63]
	v_mfma_f32_16x16x32_bf16 v[40:43], v[172:175], v[204:207], v[40:43]
	v_mfma_f32_16x16x32_bf16 v[44:47], v[180:183], v[204:207], v[44:47]
	v_mfma_f32_16x16x32_bf16 v[24:27], v[172:175], v[212:215], v[24:27]
	v_mfma_f32_16x16x32_bf16 v[28:31], v[180:183], v[212:215], v[28:31]
	v_mfma_f32_16x16x32_bf16 v[8:11], v[172:175], v[220:223], v[8:11]
	v_mfma_f32_16x16x32_bf16 v[12:15], v[180:183], v[220:223], v[12:15]
	v_mfma_f32_16x16x32_bf16 v[56:59], v[176:179], v[200:203], v[56:59]
	v_mfma_f32_16x16x32_bf16 v[60:63], v[184:187], v[200:203], v[60:63]
	v_mfma_f32_16x16x32_bf16 v[40:43], v[176:179], v[208:211], v[40:43]
	v_mfma_f32_16x16x32_bf16 v[44:47], v[184:187], v[208:211], v[44:47]
	v_mfma_f32_16x16x32_bf16 v[24:27], v[176:179], v[216:219], v[24:27]
	v_mfma_f32_16x16x32_bf16 v[28:31], v[184:187], v[216:219], v[28:31]
	s_setprio 2
	s_barrier
	v_mfma_f32_16x16x32_bf16 v[8:11], v[176:179], v[224:227], v[8:11]
	v_mfma_f32_16x16x32_bf16 v[12:15], v[184:187], v[224:227], v[12:15]
	s_setprio 0
	ds_read_b128 v[156:159], v255 offset:33024
	ds_read_b128 v[160:163], v255 offset:34048
	ds_read_b128 v[164:167], v255 offset:35072
	ds_read_b128 v[168:171], v255 offset:36096
	ds_read_b128 v[172:175], v255 offset:49408
	ds_read_b128 v[176:179], v255 offset:50432
	ds_read_b128 v[180:183], v255 offset:51456
	ds_read_b128 v[184:187], v255 offset:52480
	s_add_u32 s80, s80, 0x4000
	s_addc_u32 s81, s81, 0
	s_mov_b32 m0, s44
	ds_read_b128 v[192:195], v154 offset:32768
	ds_read_b128 v[200:203], v154 offset:33792
	ds_read_b128 v[204:207], v154 offset:34816
	ds_read_b128 v[208:211], v154 offset:35840
	ds_read_b128 v[212:215], v154 offset:36864
	ds_read_b128 v[216:219], v154 offset:37888
	ds_read_b128 v[220:223], v154 offset:38912
	ds_read_b128 v[224:227], v154 offset:39936
	global_load_lds_dwordx4 v128, s[80:81] sc1
	s_mov_b32 m0, s45
	s_nop 0
	global_load_lds_dwordx4 v130, s[80:81] sc1
	s_waitcnt vmcnt(8)
	s_waitcnt lgkmcnt(0)
	s_setprio 1
	s_barrier
	v_mfma_f32_16x16x32_bf16 v[112:115], v[156:159], v[192:195], v[112:115]
	v_mfma_f32_16x16x32_bf16 v[116:119], v[164:167], v[192:195], v[116:119]
	v_mfma_f32_16x16x32_bf16 v[96:99], v[156:159], v[204:207], v[96:99]
	v_mfma_f32_16x16x32_bf16 v[100:103], v[164:167], v[204:207], v[100:103]
	v_mfma_f32_16x16x32_bf16 v[80:83], v[156:159], v[212:215], v[80:83]
	v_mfma_f32_16x16x32_bf16 v[84:87], v[164:167], v[212:215], v[84:87]
	v_mfma_f32_16x16x32_bf16 v[64:67], v[156:159], v[220:223], v[64:67]
	v_mfma_f32_16x16x32_bf16 v[68:71], v[164:167], v[220:223], v[68:71]
	v_mfma_f32_16x16x32_bf16 v[112:115], v[160:163], v[200:203], v[112:115]
	v_mfma_f32_16x16x32_bf16 v[116:119], v[168:171], v[200:203], v[116:119]
	v_mfma_f32_16x16x32_bf16 v[96:99], v[160:163], v[208:211], v[96:99]
	v_mfma_f32_16x16x32_bf16 v[100:103], v[168:171], v[208:211], v[100:103]
	v_mfma_f32_16x16x32_bf16 v[80:83], v[160:163], v[216:219], v[80:83]
	v_mfma_f32_16x16x32_bf16 v[84:87], v[168:171], v[216:219], v[84:87]
	v_mfma_f32_16x16x32_bf16 v[64:67], v[160:163], v[224:227], v[64:67]
	v_mfma_f32_16x16x32_bf16 v[68:71], v[168:171], v[224:227], v[68:71]
	v_mfma_f32_16x16x32_bf16 v[120:123], v[172:175], v[192:195], v[120:123]
	v_mfma_f32_16x16x32_bf16 v[124:127], v[180:183], v[192:195], v[124:127]
	v_mfma_f32_16x16x32_bf16 v[104:107], v[172:175], v[204:207], v[104:107]
	v_mfma_f32_16x16x32_bf16 v[108:111], v[180:183], v[204:207], v[108:111]
	v_mfma_f32_16x16x32_bf16 v[88:91], v[172:175], v[212:215], v[88:91]
	v_mfma_f32_16x16x32_bf16 v[92:95], v[180:183], v[212:215], v[92:95]
	v_mfma_f32_16x16x32_bf16 v[72:75], v[172:175], v[220:223], v[72:75]
	v_mfma_f32_16x16x32_bf16 v[76:79], v[180:183], v[220:223], v[76:79]
	v_mfma_f32_16x16x32_bf16 v[120:123], v[176:179], v[200:203], v[120:123]
	v_mfma_f32_16x16x32_bf16 v[124:127], v[184:187], v[200:203], v[124:127]
	v_mfma_f32_16x16x32_bf16 v[104:107], v[176:179], v[208:211], v[104:107]
	v_mfma_f32_16x16x32_bf16 v[108:111], v[184:187], v[208:211], v[108:111]
	v_mfma_f32_16x16x32_bf16 v[88:91], v[176:179], v[216:219], v[88:91]
	v_mfma_f32_16x16x32_bf16 v[92:95], v[184:187], v[216:219], v[92:95]
	s_setprio 2
	s_barrier
	v_mfma_f32_16x16x32_bf16 v[72:75], v[176:179], v[224:227], v[72:75]
	v_mfma_f32_16x16x32_bf16 v[76:79], v[184:187], v[224:227], v[76:79]
	s_setprio 0
	s_add_u32 s80, s78, 0x8000
	s_addc_u32 s81, s79, 0
	s_add_i32 s88, s54, s35
	s_mov_b32 m0, s88
	ds_read_b128 v[192:195], v154 offset:49152
	ds_read_b128 v[200:203], v154 offset:50176
	ds_read_b128 v[204:207], v154 offset:51200
	ds_read_b128 v[208:211], v154 offset:52224
	ds_read_b128 v[212:215], v154 offset:53248
	ds_read_b128 v[216:219], v154 offset:54272
	ds_read_b128 v[220:223], v154 offset:55296
	ds_read_b128 v[224:227], v154 offset:56320
	global_load_lds_dwordx4 v132, s[80:81] sc1
	s_add_i32 m0, s88, 0x2000
	s_add_u32 s78, s78, 0xc000
	global_load_lds_dwordx4 v134, s[80:81] sc1
	s_addc_u32 s79, s79, 0
	s_add_i32 s80, s55, s35
	s_mov_b32 m0, s80
	s_nop 0
	global_load_lds_dwordx4 v132, s[78:79] sc1
	s_add_i32 m0, s80, 0x2000
	s_nop 0
	global_load_lds_dwordx4 v134, s[78:79] sc1
	s_mov_b32 m0, s47
	s_nop 0
	global_load_lds_dwordx4 v128, s[70:71] sc1
	s_mov_b32 m0, s48
	s_nop 0
	global_load_lds_dwordx4 v130, s[70:71] sc1
	s_waitcnt vmcnt(8)
	s_waitcnt lgkmcnt(0)
	s_setprio 1
	s_barrier
	v_mfma_f32_16x16x32_bf16 v[48:51], v[156:159], v[192:195], v[48:51]
	v_mfma_f32_16x16x32_bf16 v[52:55], v[164:167], v[192:195], v[52:55]
	v_mfma_f32_16x16x32_bf16 v[32:35], v[156:159], v[204:207], v[32:35]
	v_mfma_f32_16x16x32_bf16 v[36:39], v[164:167], v[204:207], v[36:39]
	v_mfma_f32_16x16x32_bf16 v[16:19], v[156:159], v[212:215], v[16:19]
	v_mfma_f32_16x16x32_bf16 v[20:23], v[164:167], v[212:215], v[20:23]
	v_mfma_f32_16x16x32_bf16 v[0:3], v[156:159], v[220:223], v[0:3]
	v_mfma_f32_16x16x32_bf16 v[4:7], v[164:167], v[220:223], v[4:7]
	v_mfma_f32_16x16x32_bf16 v[48:51], v[160:163], v[200:203], v[48:51]
	v_mfma_f32_16x16x32_bf16 v[52:55], v[168:171], v[200:203], v[52:55]
	v_mfma_f32_16x16x32_bf16 v[32:35], v[160:163], v[208:211], v[32:35]
	v_mfma_f32_16x16x32_bf16 v[36:39], v[168:171], v[208:211], v[36:39]
	v_mfma_f32_16x16x32_bf16 v[16:19], v[160:163], v[216:219], v[16:19]
	v_mfma_f32_16x16x32_bf16 v[20:23], v[168:171], v[216:219], v[20:23]
	v_mfma_f32_16x16x32_bf16 v[0:3], v[160:163], v[224:227], v[0:3]
	v_mfma_f32_16x16x32_bf16 v[4:7], v[168:171], v[224:227], v[4:7]
	v_mfma_f32_16x16x32_bf16 v[56:59], v[172:175], v[192:195], v[56:59]
	v_mfma_f32_16x16x32_bf16 v[60:63], v[180:183], v[192:195], v[60:63]
	v_mfma_f32_16x16x32_bf16 v[40:43], v[172:175], v[204:207], v[40:43]
	v_mfma_f32_16x16x32_bf16 v[44:47], v[180:183], v[204:207], v[44:47]
	v_mfma_f32_16x16x32_bf16 v[24:27], v[172:175], v[212:215], v[24:27]
	v_mfma_f32_16x16x32_bf16 v[28:31], v[180:183], v[212:215], v[28:31]
	v_mfma_f32_16x16x32_bf16 v[8:11], v[172:175], v[220:223], v[8:11]
	v_mfma_f32_16x16x32_bf16 v[12:15], v[180:183], v[220:223], v[12:15]
	v_mfma_f32_16x16x32_bf16 v[56:59], v[176:179], v[200:203], v[56:59]
	v_mfma_f32_16x16x32_bf16 v[60:63], v[184:187], v[200:203], v[60:63]
	v_mfma_f32_16x16x32_bf16 v[40:43], v[176:179], v[208:211], v[40:43]
	v_mfma_f32_16x16x32_bf16 v[44:47], v[184:187], v[208:211], v[44:47]
	v_mfma_f32_16x16x32_bf16 v[24:27], v[176:179], v[216:219], v[24:27]
	v_mfma_f32_16x16x32_bf16 v[28:31], v[184:187], v[216:219], v[28:31]
	s_setprio 2
	s_barrier
	v_mfma_f32_16x16x32_bf16 v[8:11], v[176:179], v[224:227], v[8:11]
	v_mfma_f32_16x16x32_bf16 v[12:15], v[184:187], v[224:227], v[12:15]
	s_setprio 0
	s_add_i32 s87, s87, 2
	s_add_u32 s10, s10, 0x10000
	s_addc_u32 s11, s11, 0
	s_cmp_gt_u32 s87, 13
	s_cbranch_scc0 .LBB0_1029
	s_add_u32 s10, s77, 0xffff0000
	s_addc_u32 s11, s82, -1
	s_and_b64 vcc, exec, s[8:9]
	s_cbranch_vccz .LBB0_1019
	s_mov_b64 s[62:63], s[10:11]
	s_andn2_b64 vcc, exec, s[6:7]
	s_cbranch_vccnz .LBB0_1020

.LBB0_1092:
	s_mov_b32 s54, s35
	s_add_i32 s35, s35, 1
	s_cmp_lt_u32 s35, s12
	s_mov_b64 s[40:41], s[16:17]
	s_mov_b32 s16, s61
	s_cselect_b64 s[56:57], -1, 0
	s_add_i32 s61, s35, s6
	s_mov_b64 s[18:19], s[0:1]
	s_and_b64 s[0:1], s[56:57], exec
	s_cselect_b32 s0, s58, s58
	s_cselect_b32 s16, s61, s16
	s_ashr_i32 s1, s0, 31
	s_lshl_b64 s[0:1], s[0:1], 19
	s_add_u32 s0, s60, s0
	s_addc_u32 s1, s33, s1
	s_and_b64 s[62:63], s[56:57], exec
	s_cselect_b32 s55, s1, s19
	s_cselect_b32 s69, s0, s18
	s_ashr_i32 s17, s16, 31
	s_lshl_b64 s[16:17], s[16:17], 19
	s_add_u32 s16, s66, s16
	s_addc_u32 s17, s67, s17
	s_and_b64 s[56:57], s[56:57], exec
	s_cselect_b32 s70, s17, s41
	s_cselect_b32 s71, s16, s40
	s_add_u32 s76, s40, 0x10000
	s_addc_u32 s77, s41, 0
	s_mov_b32 s78, -2
	v_add_u32_e32 v255, 0x10000, v148
	ds_read_b128 v[156:159], v255 offset:256
	ds_read_b128 v[160:163], v255 offset:1280
	ds_read_b128 v[164:167], v255 offset:2304
	ds_read_b128 v[168:171], v255 offset:3328
	ds_read_b128 v[172:175], v255 offset:16640
	ds_read_b128 v[176:179], v255 offset:17664
	ds_read_b128 v[180:183], v255 offset:18688
	ds_read_b128 v[184:187], v255 offset:19712
	s_add_u32 s40, s18, 0x10000
	s_addc_u32 s41, s19, 0
	s_cmp_eq_u32 s78, 12
	s_cselect_b32 s64, s69, s40
	s_cselect_b32 s65, s55, s41
	s_cselect_b32 s62, s71, s76
	s_cselect_b32 s63, s70, s77
	s_add_u32 s56, s64, 0x8000
	s_addc_u32 s57, s65, 0
	s_add_i32 m0, s37, 0xc000
	ds_read_b128 v[192:195], v154
	ds_read_b128 v[200:203], v154 offset:1024
	ds_read_b128 v[204:207], v154 offset:2048
	ds_read_b128 v[208:211], v154 offset:3072
	ds_read_b128 v[212:215], v154 offset:4096
	ds_read_b128 v[216:219], v154 offset:5120
	ds_read_b128 v[220:223], v154 offset:6144
	ds_read_b128 v[224:227], v154 offset:7168
	global_load_lds_dwordx4 v144, s[18:19] sc1
	s_add_i32 m0, s37, 0xe000
	s_nop 0
	global_load_lds_dwordx4 v146, s[18:19] sc1
	s_waitcnt vmcnt(8)
	s_waitcnt lgkmcnt(0)
	s_setprio 1
	s_barrier
	v_mfma_f32_16x16x32_bf16 v[116:119], v[156:159], v[192:195], 0
	v_mfma_f32_16x16x32_bf16 v[108:111], v[164:167], v[192:195], 0
	v_mfma_f32_16x16x32_bf16 v[100:103], v[156:159], v[204:207], 0
	v_mfma_f32_16x16x32_bf16 v[92:95], v[164:167], v[204:207], 0
	v_mfma_f32_16x16x32_bf16 v[84:87], v[156:159], v[212:215], 0
	v_mfma_f32_16x16x32_bf16 v[76:79], v[164:167], v[212:215], 0
	v_mfma_f32_16x16x32_bf16 v[60:63], v[156:159], v[220:223], 0
	v_mfma_f32_16x16x32_bf16 v[52:55], v[164:167], v[220:223], 0
	v_mfma_f32_16x16x32_bf16 v[116:119], v[160:163], v[200:203], v[116:119]
	v_mfma_f32_16x16x32_bf16 v[108:111], v[168:171], v[200:203], v[108:111]
	v_mfma_f32_16x16x32_bf16 v[100:103], v[160:163], v[208:211], v[100:103]
	v_mfma_f32_16x16x32_bf16 v[92:95], v[168:171], v[208:211], v[92:95]
	v_mfma_f32_16x16x32_bf16 v[84:87], v[160:163], v[216:219], v[84:87]
	v_mfma_f32_16x16x32_bf16 v[76:79], v[168:171], v[216:219], v[76:79]
	v_mfma_f32_16x16x32_bf16 v[60:63], v[160:163], v[224:227], v[60:63]
	v_mfma_f32_16x16x32_bf16 v[52:55], v[168:171], v[224:227], v[52:55]
	v_mfma_f32_16x16x32_bf16 v[124:127], v[172:175], v[192:195], 0
	v_mfma_f32_16x16x32_bf16 v[120:123], v[180:183], v[192:195], 0
	v_mfma_f32_16x16x32_bf16 v[112:115], v[172:175], v[204:207], 0
	v_mfma_f32_16x16x32_bf16 v[104:107], v[180:183], v[204:207], 0
	v_mfma_f32_16x16x32_bf16 v[96:99], v[172:175], v[212:215], 0
	v_mfma_f32_16x16x32_bf16 v[88:91], v[180:183], v[212:215], 0
	v_mfma_f32_16x16x32_bf16 v[80:83], v[172:175], v[220:223], 0
	v_mfma_f32_16x16x32_bf16 v[68:71], v[180:183], v[220:223], 0
	v_mfma_f32_16x16x32_bf16 v[124:127], v[176:179], v[200:203], v[124:127]
	v_mfma_f32_16x16x32_bf16 v[120:123], v[184:187], v[200:203], v[120:123]
	v_mfma_f32_16x16x32_bf16 v[112:115], v[176:179], v[208:211], v[112:115]
	v_mfma_f32_16x16x32_bf16 v[104:107], v[184:187], v[208:211], v[104:107]
	v_mfma_f32_16x16x32_bf16 v[96:99], v[176:179], v[216:219], v[96:99]
	v_mfma_f32_16x16x32_bf16 v[88:91], v[184:187], v[216:219], v[88:91]
	s_setprio 2
	s_barrier
	v_mfma_f32_16x16x32_bf16 v[80:83], v[176:179], v[224:227], v[80:83]
	v_mfma_f32_16x16x32_bf16 v[68:71], v[184:187], v[224:227], v[68:71]
	s_setprio 0
	s_add_i32 s18, s47, s36
	s_mov_b32 m0, s18
	ds_read_b128 v[192:195], v154 offset:16384
	ds_read_b128 v[200:203], v154 offset:17408
	ds_read_b128 v[204:207], v154 offset:18432
	ds_read_b128 v[208:211], v154 offset:19456
	ds_read_b128 v[212:215], v154 offset:20480
	ds_read_b128 v[216:219], v154 offset:21504
	ds_read_b128 v[220:223], v154 offset:22528
	ds_read_b128 v[224:227], v154 offset:23552
	global_load_lds_dwordx4 v132, s[62:63] sc1
	s_add_i32 m0, s18, 0x2000
	s_add_u32 s18, s62, 0x4000
	s_addc_u32 s19, s63, 0
	s_add_i32 s79, s48, s36
	global_load_lds_dwordx4 v134, s[62:63] sc1
	s_mov_b32 m0, s79
	s_nop 0
	global_load_lds_dwordx4 v132, s[18:19] sc1
	s_add_i32 m0, s79, 0x2000
	s_nop 0
	global_load_lds_dwordx4 v134, s[18:19] sc1
	s_mov_b32 m0, s37
	s_nop 0
	global_load_lds_dwordx4 v130, s[64:65] sc1
	s_mov_b32 m0, s42
	s_nop 0
	global_load_lds_dwordx4 v128, s[64:65] sc1
	s_waitcnt vmcnt(8)
	s_waitcnt lgkmcnt(0)
	s_setprio 1
	s_barrier
	v_mfma_f32_16x16x32_bf16 v[56:59], v[156:159], v[192:195], 0
	v_mfma_f32_16x16x32_bf16 v[44:47], v[164:167], v[192:195], 0
	v_mfma_f32_16x16x32_bf16 v[36:39], v[156:159], v[204:207], 0
	v_mfma_f32_16x16x32_bf16 v[28:31], v[164:167], v[204:207], 0
	v_mfma_f32_16x16x32_bf16 v[20:23], v[156:159], v[212:215], 0
	v_mfma_f32_16x16x32_bf16 v[12:15], v[164:167], v[212:215], 0
	v_mfma_f32_16x16x32_bf16 v[4:7], v[156:159], v[220:223], 0
	v_mfma_f32_16x16x32_bf16 v[0:3], v[164:167], v[220:223], 0
	v_mfma_f32_16x16x32_bf16 v[56:59], v[160:163], v[200:203], v[56:59]
	v_mfma_f32_16x16x32_bf16 v[44:47], v[168:171], v[200:203], v[44:47]
	v_mfma_f32_16x16x32_bf16 v[36:39], v[160:163], v[208:211], v[36:39]
	v_mfma_f32_16x16x32_bf16 v[28:31], v[168:171], v[208:211], v[28:31]
	v_mfma_f32_16x16x32_bf16 v[20:23], v[160:163], v[216:219], v[20:23]
	v_mfma_f32_16x16x32_bf16 v[12:15], v[168:171], v[216:219], v[12:15]
	v_mfma_f32_16x16x32_bf16 v[4:7], v[160:163], v[224:227], v[4:7]
	v_mfma_f32_16x16x32_bf16 v[0:3], v[168:171], v[224:227], v[0:3]
	v_mfma_f32_16x16x32_bf16 v[72:75], v[172:175], v[192:195], 0
	v_mfma_f32_16x16x32_bf16 v[64:67], v[180:183], v[192:195], 0
	v_mfma_f32_16x16x32_bf16 v[48:51], v[172:175], v[204:207], 0
	v_mfma_f32_16x16x32_bf16 v[40:43], v[180:183], v[204:207], 0
	v_mfma_f32_16x16x32_bf16 v[32:35], v[172:175], v[212:215], 0
	v_mfma_f32_16x16x32_bf16 v[24:27], v[180:183], v[212:215], 0
	v_mfma_f32_16x16x32_bf16 v[16:19], v[172:175], v[220:223], 0
	v_mfma_f32_16x16x32_bf16 v[8:11], v[180:183], v[220:223], 0
	v_mfma_f32_16x16x32_bf16 v[72:75], v[176:179], v[200:203], v[72:75]
	v_mfma_f32_16x16x32_bf16 v[64:67], v[184:187], v[200:203], v[64:67]
	v_mfma_f32_16x16x32_bf16 v[48:51], v[176:179], v[208:211], v[48:51]
	v_mfma_f32_16x16x32_bf16 v[40:43], v[184:187], v[208:211], v[40:43]
	v_mfma_f32_16x16x32_bf16 v[32:35], v[176:179], v[216:219], v[32:35]
	v_mfma_f32_16x16x32_bf16 v[24:27], v[184:187], v[216:219], v[24:27]
	s_setprio 2
	s_barrier
	v_mfma_f32_16x16x32_bf16 v[16:19], v[176:179], v[224:227], v[16:19]
	v_mfma_f32_16x16x32_bf16 v[8:11], v[184:187], v[224:227], v[8:11]
	s_setprio 0
	ds_read_b128 v[156:159], v255 offset:33024
	ds_read_b128 v[160:163], v255 offset:34048
	ds_read_b128 v[164:167], v255 offset:35072
	ds_read_b128 v[168:171], v255 offset:36096
	ds_read_b128 v[172:175], v255 offset:49408
	ds_read_b128 v[176:179], v255 offset:50432
	ds_read_b128 v[180:183], v255 offset:51456
	ds_read_b128 v[184:187], v255 offset:52480
	s_add_u32 s18, s64, 0x4000
	s_addc_u32 s19, s65, 0
	s_mov_b32 m0, s43
	ds_read_b128 v[192:195], v154 offset:32768
	ds_read_b128 v[200:203], v154 offset:33792
	ds_read_b128 v[204:207], v154 offset:34816
	ds_read_b128 v[208:211], v154 offset:35840
	ds_read_b128 v[212:215], v154 offset:36864
	ds_read_b128 v[216:219], v154 offset:37888
	ds_read_b128 v[220:223], v154 offset:38912
	ds_read_b128 v[224:227], v154 offset:39936
	global_load_lds_dwordx4 v130, s[18:19] sc1
	s_mov_b32 m0, s44
	s_nop 0
	global_load_lds_dwordx4 v128, s[18:19] sc1
	s_waitcnt vmcnt(8)
	s_waitcnt lgkmcnt(0)
	s_setprio 1
	s_barrier
	v_mfma_f32_16x16x32_bf16 v[116:119], v[156:159], v[192:195], v[116:119]
	v_mfma_f32_16x16x32_bf16 v[108:111], v[164:167], v[192:195], v[108:111]
	v_mfma_f32_16x16x32_bf16 v[100:103], v[156:159], v[204:207], v[100:103]
	v_mfma_f32_16x16x32_bf16 v[92:95], v[164:167], v[204:207], v[92:95]
	v_mfma_f32_16x16x32_bf16 v[84:87], v[156:159], v[212:215], v[84:87]
	v_mfma_f32_16x16x32_bf16 v[76:79], v[164:167], v[212:215], v[76:79]
	v_mfma_f32_16x16x32_bf16 v[60:63], v[156:159], v[220:223], v[60:63]
	v_mfma_f32_16x16x32_bf16 v[52:55], v[164:167], v[220:223], v[52:55]
	v_mfma_f32_16x16x32_bf16 v[116:119], v[160:163], v[200:203], v[116:119]
	v_mfma_f32_16x16x32_bf16 v[108:111], v[168:171], v[200:203], v[108:111]
	v_mfma_f32_16x16x32_bf16 v[100:103], v[160:163], v[208:211], v[100:103]
	v_mfma_f32_16x16x32_bf16 v[92:95], v[168:171], v[208:211], v[92:95]
	v_mfma_f32_16x16x32_bf16 v[84:87], v[160:163], v[216:219], v[84:87]
	v_mfma_f32_16x16x32_bf16 v[76:79], v[168:171], v[216:219], v[76:79]
	v_mfma_f32_16x16x32_bf16 v[60:63], v[160:163], v[224:227], v[60:63]
	v_mfma_f32_16x16x32_bf16 v[52:55], v[168:171], v[224:227], v[52:55]
	v_mfma_f32_16x16x32_bf16 v[124:127], v[172:175], v[192:195], v[124:127]
	v_mfma_f32_16x16x32_bf16 v[120:123], v[180:183], v[192:195], v[120:123]
	v_mfma_f32_16x16x32_bf16 v[112:115], v[172:175], v[204:207], v[112:115]
	v_mfma_f32_16x16x32_bf16 v[104:107], v[180:183], v[204:207], v[104:107]
	v_mfma_f32_16x16x32_bf16 v[96:99], v[172:175], v[212:215], v[96:99]
	v_mfma_f32_16x16x32_bf16 v[88:91], v[180:183], v[212:215], v[88:91]
	v_mfma_f32_16x16x32_bf16 v[80:83], v[172:175], v[220:223], v[80:83]
	v_mfma_f32_16x16x32_bf16 v[68:71], v[180:183], v[220:223], v[68:71]
	v_mfma_f32_16x16x32_bf16 v[124:127], v[176:179], v[200:203], v[124:127]
	v_mfma_f32_16x16x32_bf16 v[120:123], v[184:187], v[200:203], v[120:123]
	v_mfma_f32_16x16x32_bf16 v[112:115], v[176:179], v[208:211], v[112:115]
	v_mfma_f32_16x16x32_bf16 v[104:107], v[184:187], v[208:211], v[104:107]
	v_mfma_f32_16x16x32_bf16 v[96:99], v[176:179], v[216:219], v[96:99]
	v_mfma_f32_16x16x32_bf16 v[88:91], v[184:187], v[216:219], v[88:91]
	s_setprio 2
	s_barrier
	v_mfma_f32_16x16x32_bf16 v[80:83], v[176:179], v[224:227], v[80:83]
	v_mfma_f32_16x16x32_bf16 v[68:71], v[184:187], v[224:227], v[68:71]
	s_setprio 0
	s_add_u32 s18, s62, 0x8000
	s_addc_u32 s19, s63, 0
	s_add_i32 s64, s49, s36
	s_mov_b32 m0, s64
	ds_read_b128 v[192:195], v154 offset:49152
	ds_read_b128 v[200:203], v154 offset:50176
	ds_read_b128 v[204:207], v154 offset:51200
	ds_read_b128 v[208:211], v154 offset:52224
	ds_read_b128 v[212:215], v154 offset:53248
	ds_read_b128 v[216:219], v154 offset:54272
	ds_read_b128 v[220:223], v154 offset:55296
	ds_read_b128 v[224:227], v154 offset:56320
	global_load_lds_dwordx4 v132, s[18:19] sc1
	s_add_i32 m0, s64, 0x2000
	s_nop 0
	global_load_lds_dwordx4 v134, s[18:19] sc1
	s_add_u32 s18, s62, 0xc000
	s_addc_u32 s19, s63, 0
	s_add_i32 s62, s50, s36
	s_mov_b32 m0, s62
	s_nop 0
	global_load_lds_dwordx4 v132, s[18:19] sc1
	s_add_i32 m0, s62, 0x2000
	s_nop 0
	global_load_lds_dwordx4 v134, s[18:19] sc1
	s_mov_b32 m0, s7
	s_nop 0
	global_load_lds_dwordx4 v130, s[56:57] sc1
	s_mov_b32 m0, s45
	s_nop 0
	global_load_lds_dwordx4 v128, s[56:57] sc1
	s_waitcnt vmcnt(8)
	s_waitcnt lgkmcnt(0)
	s_setprio 1
	s_barrier
	v_mfma_f32_16x16x32_bf16 v[56:59], v[156:159], v[192:195], v[56:59]
	v_mfma_f32_16x16x32_bf16 v[44:47], v[164:167], v[192:195], v[44:47]
	v_mfma_f32_16x16x32_bf16 v[36:39], v[156:159], v[204:207], v[36:39]
	v_mfma_f32_16x16x32_bf16 v[28:31], v[164:167], v[204:207], v[28:31]
	v_mfma_f32_16x16x32_bf16 v[20:23], v[156:159], v[212:215], v[20:23]
	v_mfma_f32_16x16x32_bf16 v[12:15], v[164:167], v[212:215], v[12:15]
	v_mfma_f32_16x16x32_bf16 v[4:7], v[156:159], v[220:223], v[4:7]
	v_mfma_f32_16x16x32_bf16 v[0:3], v[164:167], v[220:223], v[0:3]
	v_mfma_f32_16x16x32_bf16 v[56:59], v[160:163], v[200:203], v[56:59]
	v_mfma_f32_16x16x32_bf16 v[44:47], v[168:171], v[200:203], v[44:47]
	v_mfma_f32_16x16x32_bf16 v[36:39], v[160:163], v[208:211], v[36:39]
	v_mfma_f32_16x16x32_bf16 v[28:31], v[168:171], v[208:211], v[28:31]
	v_mfma_f32_16x16x32_bf16 v[20:23], v[160:163], v[216:219], v[20:23]
	v_mfma_f32_16x16x32_bf16 v[12:15], v[168:171], v[216:219], v[12:15]
	v_mfma_f32_16x16x32_bf16 v[4:7], v[160:163], v[224:227], v[4:7]
	v_mfma_f32_16x16x32_bf16 v[0:3], v[168:171], v[224:227], v[0:3]
	v_mfma_f32_16x16x32_bf16 v[72:75], v[172:175], v[192:195], v[72:75]
	v_mfma_f32_16x16x32_bf16 v[64:67], v[180:183], v[192:195], v[64:67]
	v_mfma_f32_16x16x32_bf16 v[48:51], v[172:175], v[204:207], v[48:51]
	v_mfma_f32_16x16x32_bf16 v[40:43], v[180:183], v[204:207], v[40:43]
	v_mfma_f32_16x16x32_bf16 v[32:35], v[172:175], v[212:215], v[32:35]
	v_mfma_f32_16x16x32_bf16 v[24:27], v[180:183], v[212:215], v[24:27]
	v_mfma_f32_16x16x32_bf16 v[16:19], v[172:175], v[220:223], v[16:19]
	v_mfma_f32_16x16x32_bf16 v[8:11], v[180:183], v[220:223], v[8:11]
	v_mfma_f32_16x16x32_bf16 v[72:75], v[176:179], v[200:203], v[72:75]
	v_mfma_f32_16x16x32_bf16 v[64:67], v[184:187], v[200:203], v[64:67]
	v_mfma_f32_16x16x32_bf16 v[48:51], v[176:179], v[208:211], v[48:51]
	v_mfma_f32_16x16x32_bf16 v[40:43], v[184:187], v[208:211], v[40:43]
	v_mfma_f32_16x16x32_bf16 v[32:35], v[176:179], v[216:219], v[32:35]
	v_mfma_f32_16x16x32_bf16 v[24:27], v[184:187], v[216:219], v[24:27]
	s_setprio 2
	s_barrier
	v_mfma_f32_16x16x32_bf16 v[16:19], v[176:179], v[224:227], v[16:19]
	v_mfma_f32_16x16x32_bf16 v[8:11], v[184:187], v[224:227], v[8:11]
	s_setprio 0
	s_add_i32 s78, s78, 2
	s_add_u32 s76, s76, 0x10000
	s_addc_u32 s77, s77, 0
	s_cmp_gt_u32 s78, 13
	s_mov_b64 s[18:19], s[40:41]
.LBB0_1093:
	ds_read_b128 v[156:159], v255 offset:256
	ds_read_b128 v[160:163], v255 offset:1280
	ds_read_b128 v[164:167], v255 offset:2304
	ds_read_b128 v[168:171], v255 offset:3328
	ds_read_b128 v[172:175], v255 offset:16640
	ds_read_b128 v[176:179], v255 offset:17664
	ds_read_b128 v[180:183], v255 offset:18688
	ds_read_b128 v[184:187], v255 offset:19712
	s_add_u32 s40, s18, 0x10000
	s_addc_u32 s41, s19, 0
	s_cmp_eq_u32 s78, 12
	s_cselect_b32 s64, s69, s40
	s_cselect_b32 s65, s55, s41
	s_cselect_b32 s62, s71, s76
	s_cselect_b32 s63, s70, s77
	s_add_u32 s56, s64, 0x8000
	s_addc_u32 s57, s65, 0
	s_add_i32 m0, s37, 0xc000
	ds_read_b128 v[192:195], v154
	ds_read_b128 v[200:203], v154 offset:1024
	ds_read_b128 v[204:207], v154 offset:2048
	ds_read_b128 v[208:211], v154 offset:3072
	ds_read_b128 v[212:215], v154 offset:4096
	ds_read_b128 v[216:219], v154 offset:5120
	ds_read_b128 v[220:223], v154 offset:6144
	ds_read_b128 v[224:227], v154 offset:7168
	global_load_lds_dwordx4 v144, s[18:19] sc1
	s_add_i32 m0, s37, 0xe000
	s_nop 0
	global_load_lds_dwordx4 v146, s[18:19] sc1
	s_waitcnt vmcnt(8)
	s_waitcnt lgkmcnt(0)
	s_setprio 1
	s_barrier
	v_mfma_f32_16x16x32_bf16 v[116:119], v[156:159], v[192:195], v[116:119]
	v_mfma_f32_16x16x32_bf16 v[108:111], v[164:167], v[192:195], v[108:111]
	v_mfma_f32_16x16x32_bf16 v[100:103], v[156:159], v[204:207], v[100:103]
	v_mfma_f32_16x16x32_bf16 v[92:95], v[164:167], v[204:207], v[92:95]
	v_mfma_f32_16x16x32_bf16 v[84:87], v[156:159], v[212:215], v[84:87]
	v_mfma_f32_16x16x32_bf16 v[76:79], v[164:167], v[212:215], v[76:79]
	v_mfma_f32_16x16x32_bf16 v[60:63], v[156:159], v[220:223], v[60:63]
	v_mfma_f32_16x16x32_bf16 v[52:55], v[164:167], v[220:223], v[52:55]
	v_mfma_f32_16x16x32_bf16 v[116:119], v[160:163], v[200:203], v[116:119]
	v_mfma_f32_16x16x32_bf16 v[108:111], v[168:171], v[200:203], v[108:111]
	v_mfma_f32_16x16x32_bf16 v[100:103], v[160:163], v[208:211], v[100:103]
	v_mfma_f32_16x16x32_bf16 v[92:95], v[168:171], v[208:211], v[92:95]
	v_mfma_f32_16x16x32_bf16 v[84:87], v[160:163], v[216:219], v[84:87]
	v_mfma_f32_16x16x32_bf16 v[76:79], v[168:171], v[216:219], v[76:79]
	v_mfma_f32_16x16x32_bf16 v[60:63], v[160:163], v[224:227], v[60:63]
	v_mfma_f32_16x16x32_bf16 v[52:55], v[168:171], v[224:227], v[52:55]
	v_mfma_f32_16x16x32_bf16 v[124:127], v[172:175], v[192:195], v[124:127]
	v_mfma_f32_16x16x32_bf16 v[120:123], v[180:183], v[192:195], v[120:123]
	v_mfma_f32_16x16x32_bf16 v[112:115], v[172:175], v[204:207], v[112:115]
	v_mfma_f32_16x16x32_bf16 v[104:107], v[180:183], v[204:207], v[104:107]
	v_mfma_f32_16x16x32_bf16 v[96:99], v[172:175], v[212:215], v[96:99]
	v_mfma_f32_16x16x32_bf16 v[88:91], v[180:183], v[212:215], v[88:91]
	v_mfma_f32_16x16x32_bf16 v[80:83], v[172:175], v[220:223], v[80:83]
	v_mfma_f32_16x16x32_bf16 v[68:71], v[180:183], v[220:223], v[68:71]
	v_mfma_f32_16x16x32_bf16 v[124:127], v[176:179], v[200:203], v[124:127]
	v_mfma_f32_16x16x32_bf16 v[120:123], v[184:187], v[200:203], v[120:123]
	v_mfma_f32_16x16x32_bf16 v[112:115], v[176:179], v[208:211], v[112:115]
	v_mfma_f32_16x16x32_bf16 v[104:107], v[184:187], v[208:211], v[104:107]
	v_mfma_f32_16x16x32_bf16 v[96:99], v[176:179], v[216:219], v[96:99]
	v_mfma_f32_16x16x32_bf16 v[88:91], v[184:187], v[216:219], v[88:91]
	s_setprio 2
	s_barrier
	v_mfma_f32_16x16x32_bf16 v[80:83], v[176:179], v[224:227], v[80:83]
	v_mfma_f32_16x16x32_bf16 v[68:71], v[184:187], v[224:227], v[68:71]
	s_setprio 0
	s_add_i32 s18, s47, s36
	s_mov_b32 m0, s18
	ds_read_b128 v[192:195], v154 offset:16384
	ds_read_b128 v[200:203], v154 offset:17408
	ds_read_b128 v[204:207], v154 offset:18432
	ds_read_b128 v[208:211], v154 offset:19456
	ds_read_b128 v[212:215], v154 offset:20480
	ds_read_b128 v[216:219], v154 offset:21504
	ds_read_b128 v[220:223], v154 offset:22528
	ds_read_b128 v[224:227], v154 offset:23552
	global_load_lds_dwordx4 v132, s[62:63] sc1
	s_add_i32 m0, s18, 0x2000
	s_add_u32 s18, s62, 0x4000
	s_addc_u32 s19, s63, 0
	s_add_i32 s79, s48, s36
	global_load_lds_dwordx4 v134, s[62:63] sc1
	s_mov_b32 m0, s79
	s_nop 0
	global_load_lds_dwordx4 v132, s[18:19] sc1
	s_add_i32 m0, s79, 0x2000
	s_nop 0
	global_load_lds_dwordx4 v134, s[18:19] sc1
	s_mov_b32 m0, s37
	s_nop 0
	global_load_lds_dwordx4 v130, s[64:65] sc1
	s_mov_b32 m0, s42
	s_nop 0
	global_load_lds_dwordx4 v128, s[64:65] sc1
	s_waitcnt vmcnt(8)
	s_waitcnt lgkmcnt(0)
	s_setprio 1
	s_barrier
	v_mfma_f32_16x16x32_bf16 v[56:59], v[156:159], v[192:195], v[56:59]
	v_mfma_f32_16x16x32_bf16 v[44:47], v[164:167], v[192:195], v[44:47]
	v_mfma_f32_16x16x32_bf16 v[36:39], v[156:159], v[204:207], v[36:39]
	v_mfma_f32_16x16x32_bf16 v[28:31], v[164:167], v[204:207], v[28:31]
	v_mfma_f32_16x16x32_bf16 v[20:23], v[156:159], v[212:215], v[20:23]
	v_mfma_f32_16x16x32_bf16 v[12:15], v[164:167], v[212:215], v[12:15]
	v_mfma_f32_16x16x32_bf16 v[4:7], v[156:159], v[220:223], v[4:7]
	v_mfma_f32_16x16x32_bf16 v[0:3], v[164:167], v[220:223], v[0:3]
	v_mfma_f32_16x16x32_bf16 v[56:59], v[160:163], v[200:203], v[56:59]
	v_mfma_f32_16x16x32_bf16 v[44:47], v[168:171], v[200:203], v[44:47]
	v_mfma_f32_16x16x32_bf16 v[36:39], v[160:163], v[208:211], v[36:39]
	v_mfma_f32_16x16x32_bf16 v[28:31], v[168:171], v[208:211], v[28:31]
	v_mfma_f32_16x16x32_bf16 v[20:23], v[160:163], v[216:219], v[20:23]
	v_mfma_f32_16x16x32_bf16 v[12:15], v[168:171], v[216:219], v[12:15]
	v_mfma_f32_16x16x32_bf16 v[4:7], v[160:163], v[224:227], v[4:7]
	v_mfma_f32_16x16x32_bf16 v[0:3], v[168:171], v[224:227], v[0:3]
	v_mfma_f32_16x16x32_bf16 v[72:75], v[172:175], v[192:195], v[72:75]
	v_mfma_f32_16x16x32_bf16 v[64:67], v[180:183], v[192:195], v[64:67]
	v_mfma_f32_16x16x32_bf16 v[48:51], v[172:175], v[204:207], v[48:51]
	v_mfma_f32_16x16x32_bf16 v[40:43], v[180:183], v[204:207], v[40:43]
	v_mfma_f32_16x16x32_bf16 v[32:35], v[172:175], v[212:215], v[32:35]
	v_mfma_f32_16x16x32_bf16 v[24:27], v[180:183], v[212:215], v[24:27]
	v_mfma_f32_16x16x32_bf16 v[16:19], v[172:175], v[220:223], v[16:19]
	v_mfma_f32_16x16x32_bf16 v[8:11], v[180:183], v[220:223], v[8:11]
	v_mfma_f32_16x16x32_bf16 v[72:75], v[176:179], v[200:203], v[72:75]
	v_mfma_f32_16x16x32_bf16 v[64:67], v[184:187], v[200:203], v[64:67]
	v_mfma_f32_16x16x32_bf16 v[48:51], v[176:179], v[208:211], v[48:51]
	v_mfma_f32_16x16x32_bf16 v[40:43], v[184:187], v[208:211], v[40:43]
	v_mfma_f32_16x16x32_bf16 v[32:35], v[176:179], v[216:219], v[32:35]
	v_mfma_f32_16x16x32_bf16 v[24:27], v[184:187], v[216:219], v[24:27]
	s_setprio 2
	s_barrier
	v_mfma_f32_16x16x32_bf16 v[16:19], v[176:179], v[224:227], v[16:19]
	v_mfma_f32_16x16x32_bf16 v[8:11], v[184:187], v[224:227], v[8:11]
	s_setprio 0
	ds_read_b128 v[156:159], v255 offset:33024
	ds_read_b128 v[160:163], v255 offset:34048
	ds_read_b128 v[164:167], v255 offset:35072
	ds_read_b128 v[168:171], v255 offset:36096
	ds_read_b128 v[172:175], v255 offset:49408
	ds_read_b128 v[176:179], v255 offset:50432
	ds_read_b128 v[180:183], v255 offset:51456
	ds_read_b128 v[184:187], v255 offset:52480
	s_add_u32 s18, s64, 0x4000
	s_addc_u32 s19, s65, 0
	s_mov_b32 m0, s43
	ds_read_b128 v[192:195], v154 offset:32768
	ds_read_b128 v[200:203], v154 offset:33792
	ds_read_b128 v[204:207], v154 offset:34816
	ds_read_b128 v[208:211], v154 offset:35840
	ds_read_b128 v[212:215], v154 offset:36864
	ds_read_b128 v[216:219], v154 offset:37888
	ds_read_b128 v[220:223], v154 offset:38912
	ds_read_b128 v[224:227], v154 offset:39936
	global_load_lds_dwordx4 v130, s[18:19] sc1
	s_mov_b32 m0, s44
	s_nop 0
	global_load_lds_dwordx4 v128, s[18:19] sc1
	s_waitcnt vmcnt(8)
	s_waitcnt lgkmcnt(0)
	s_setprio 1
	s_barrier
	v_mfma_f32_16x16x32_bf16 v[116:119], v[156:159], v[192:195], v[116:119]
	v_mfma_f32_16x16x32_bf16 v[108:111], v[164:167], v[192:195], v[108:111]
	v_mfma_f32_16x16x32_bf16 v[100:103], v[156:159], v[204:207], v[100:103]
	v_mfma_f32_16x16x32_bf16 v[92:95], v[164:167], v[204:207], v[92:95]
	v_mfma_f32_16x16x32_bf16 v[84:87], v[156:159], v[212:215], v[84:87]
	v_mfma_f32_16x16x32_bf16 v[76:79], v[164:167], v[212:215], v[76:79]
	v_mfma_f32_16x16x32_bf16 v[60:63], v[156:159], v[220:223], v[60:63]
	v_mfma_f32_16x16x32_bf16 v[52:55], v[164:167], v[220:223], v[52:55]
	v_mfma_f32_16x16x32_bf16 v[116:119], v[160:163], v[200:203], v[116:119]
	v_mfma_f32_16x16x32_bf16 v[108:111], v[168:171], v[200:203], v[108:111]
	v_mfma_f32_16x16x32_bf16 v[100:103], v[160:163], v[208:211], v[100:103]
	v_mfma_f32_16x16x32_bf16 v[92:95], v[168:171], v[208:211], v[92:95]
	v_mfma_f32_16x16x32_bf16 v[84:87], v[160:163], v[216:219], v[84:87]
	v_mfma_f32_16x16x32_bf16 v[76:79], v[168:171], v[216:219], v[76:79]
	v_mfma_f32_16x16x32_bf16 v[60:63], v[160:163], v[224:227], v[60:63]
	v_mfma_f32_16x16x32_bf16 v[52:55], v[168:171], v[224:227], v[52:55]
	v_mfma_f32_16x16x32_bf16 v[124:127], v[172:175], v[192:195], v[124:127]
	v_mfma_f32_16x16x32_bf16 v[120:123], v[180:183], v[192:195], v[120:123]
	v_mfma_f32_16x16x32_bf16 v[112:115], v[172:175], v[204:207], v[112:115]
	v_mfma_f32_16x16x32_bf16 v[104:107], v[180:183], v[204:207], v[104:107]
	v_mfma_f32_16x16x32_bf16 v[96:99], v[172:175], v[212:215], v[96:99]
	v_mfma_f32_16x16x32_bf16 v[88:91], v[180:183], v[212:215], v[88:91]
	v_mfma_f32_16x16x32_bf16 v[80:83], v[172:175], v[220:223], v[80:83]
	v_mfma_f32_16x16x32_bf16 v[68:71], v[180:183], v[220:223], v[68:71]
	v_mfma_f32_16x16x32_bf16 v[124:127], v[176:179], v[200:203], v[124:127]
	v_mfma_f32_16x16x32_bf16 v[120:123], v[184:187], v[200:203], v[120:123]
	v_mfma_f32_16x16x32_bf16 v[112:115], v[176:179], v[208:211], v[112:115]
	v_mfma_f32_16x16x32_bf16 v[104:107], v[184:187], v[208:211], v[104:107]
	v_mfma_f32_16x16x32_bf16 v[96:99], v[176:179], v[216:219], v[96:99]
	v_mfma_f32_16x16x32_bf16 v[88:91], v[184:187], v[216:219], v[88:91]
	s_setprio 2
	s_barrier
	v_mfma_f32_16x16x32_bf16 v[80:83], v[176:179], v[224:227], v[80:83]
	v_mfma_f32_16x16x32_bf16 v[68:71], v[184:187], v[224:227], v[68:71]
	s_setprio 0
	s_add_u32 s18, s62, 0x8000
	s_addc_u32 s19, s63, 0
	s_add_i32 s64, s49, s36
	s_mov_b32 m0, s64
	ds_read_b128 v[192:195], v154 offset:49152
	ds_read_b128 v[200:203], v154 offset:50176
	ds_read_b128 v[204:207], v154 offset:51200
	ds_read_b128 v[208:211], v154 offset:52224
	ds_read_b128 v[212:215], v154 offset:53248
	ds_read_b128 v[216:219], v154 offset:54272
	ds_read_b128 v[220:223], v154 offset:55296
	ds_read_b128 v[224:227], v154 offset:56320
	global_load_lds_dwordx4 v132, s[18:19] sc1
	s_add_i32 m0, s64, 0x2000
	s_nop 0
	global_load_lds_dwordx4 v134, s[18:19] sc1
	s_add_u32 s18, s62, 0xc000
	s_addc_u32 s19, s63, 0
	s_add_i32 s62, s50, s36
	s_mov_b32 m0, s62
	s_nop 0
	global_load_lds_dwordx4 v132, s[18:19] sc1
	s_add_i32 m0, s62, 0x2000
	s_nop 0
	global_load_lds_dwordx4 v134, s[18:19] sc1
	s_mov_b32 m0, s7
	s_nop 0
	global_load_lds_dwordx4 v130, s[56:57] sc1
	s_mov_b32 m0, s45
	s_nop 0
	global_load_lds_dwordx4 v128, s[56:57] sc1
	s_waitcnt vmcnt(8)
	s_waitcnt lgkmcnt(0)
	s_setprio 1
	s_barrier
	v_mfma_f32_16x16x32_bf16 v[56:59], v[156:159], v[192:195], v[56:59]
	v_mfma_f32_16x16x32_bf16 v[44:47], v[164:167], v[192:195], v[44:47]
	v_mfma_f32_16x16x32_bf16 v[36:39], v[156:159], v[204:207], v[36:39]
	v_mfma_f32_16x16x32_bf16 v[28:31], v[164:167], v[204:207], v[28:31]
	v_mfma_f32_16x16x32_bf16 v[20:23], v[156:159], v[212:215], v[20:23]
	v_mfma_f32_16x16x32_bf16 v[12:15], v[164:167], v[212:215], v[12:15]
	v_mfma_f32_16x16x32_bf16 v[4:7], v[156:159], v[220:223], v[4:7]
	v_mfma_f32_16x16x32_bf16 v[0:3], v[164:167], v[220:223], v[0:3]
	v_mfma_f32_16x16x32_bf16 v[56:59], v[160:163], v[200:203], v[56:59]
	v_mfma_f32_16x16x32_bf16 v[44:47], v[168:171], v[200:203], v[44:47]
	v_mfma_f32_16x16x32_bf16 v[36:39], v[160:163], v[208:211], v[36:39]
	v_mfma_f32_16x16x32_bf16 v[28:31], v[168:171], v[208:211], v[28:31]
	v_mfma_f32_16x16x32_bf16 v[20:23], v[160:163], v[216:219], v[20:23]
	v_mfma_f32_16x16x32_bf16 v[12:15], v[168:171], v[216:219], v[12:15]
	v_mfma_f32_16x16x32_bf16 v[4:7], v[160:163], v[224:227], v[4:7]
	v_mfma_f32_16x16x32_bf16 v[0:3], v[168:171], v[224:227], v[0:3]
	v_mfma_f32_16x16x32_bf16 v[72:75], v[172:175], v[192:195], v[72:75]
	v_mfma_f32_16x16x32_bf16 v[64:67], v[180:183], v[192:195], v[64:67]
	v_mfma_f32_16x16x32_bf16 v[48:51], v[172:175], v[204:207], v[48:51]
	v_mfma_f32_16x16x32_bf16 v[40:43], v[180:183], v[204:207], v[40:43]
	v_mfma_f32_16x16x32_bf16 v[32:35], v[172:175], v[212:215], v[32:35]
	v_mfma_f32_16x16x32_bf16 v[24:27], v[180:183], v[212:215], v[24:27]
	v_mfma_f32_16x16x32_bf16 v[16:19], v[172:175], v[220:223], v[16:19]
	v_mfma_f32_16x16x32_bf16 v[8:11], v[180:183], v[220:223], v[8:11]
	v_mfma_f32_16x16x32_bf16 v[72:75], v[176:179], v[200:203], v[72:75]
	v_mfma_f32_16x16x32_bf16 v[64:67], v[184:187], v[200:203], v[64:67]
	v_mfma_f32_16x16x32_bf16 v[48:51], v[176:179], v[208:211], v[48:51]
	v_mfma_f32_16x16x32_bf16 v[40:43], v[184:187], v[208:211], v[40:43]
	v_mfma_f32_16x16x32_bf16 v[32:35], v[176:179], v[216:219], v[32:35]
	v_mfma_f32_16x16x32_bf16 v[24:27], v[184:187], v[216:219], v[24:27]
	s_setprio 2
	s_barrier
	v_mfma_f32_16x16x32_bf16 v[16:19], v[176:179], v[224:227], v[16:19]
	v_mfma_f32_16x16x32_bf16 v[8:11], v[184:187], v[224:227], v[8:11]
	s_setprio 0
	s_add_i32 s78, s78, 2
	s_add_u32 s76, s76, 0x10000
	s_addc_u32 s77, s77, 0
	s_cmp_gt_u32 s78, 13
	s_mov_b64 s[18:19], s[40:41]
	s_cbranch_scc0 .LBB0_1093
	s_and_b64 vcc, exec, s[10:11]
	s_cbranch_vccz .LBB0_1096
	s_barrier

.LBB0_1248:
	s_add_u32 s49, s18, 0x10000
	s_addc_u32 s50, s19, 0
	s_lshl_b32 s18, s8, 2
	s_ashr_i32 s11, s10, 31
	s_ashr_i32 s19, s18, 31
	s_lshl_b64 s[20:21], s[10:11], 19
	s_lshl_b64 s[18:19], s[18:19], 15
	s_add_u32 s11, s60, s18
	s_addc_u32 s18, s33, s19
	s_add_u32 s11, s11, s20
	s_addc_u32 s18, s18, s21
	s_add_u32 s19, s11, 0x10000
	s_addc_u32 s20, s18, 0
	s_and_b64 s[6:7], s[6:7], exec
	s_cselect_b32 s51, s17, s20
	s_cselect_b32 s52, s16, s19
	s_cselect_b32 s53, s15, s18
	s_cselect_b32 s54, s14, s11
	v_lshl_add_u64 v[144:145], s[12:13], 0, v[8:9]
	v_lshl_add_u64 v[146:147], s[12:13], 0, v[10:11]
	s_mov_b32 s55, -2
	s_mov_b64 s[6:7], 0
	v_add_u32_e32 v255, 0x10000, v150
	s_add_u32 s11, s12, s6
	s_addc_u32 s18, s13, s7
	ds_read_b128 v[152:155], v255 offset:256
	ds_read_b128 v[156:159], v255 offset:1280
	ds_read_b128 v[164:167], v255 offset:2304
	ds_read_b128 v[168:171], v255 offset:3328
	s_add_u32 s11, s11, 0x10000
	ds_read_b128 v[172:175], v255 offset:16640
	ds_read_b128 v[182:185], v255 offset:17664
	ds_read_b128 v[190:193], v255 offset:18688
	ds_read_b128 v[194:197], v255 offset:19712
	s_addc_u32 s18, s18, 0
	s_add_u32 s19, s49, s6
	s_addc_u32 s21, s50, s7
	s_cmp_eq_u32 s6, 0x150000
	s_cselect_b32 s22, s52, s11
	s_cselect_b32 s23, s51, s18
	s_cselect_b32 s20, s54, s19
	s_cselect_b32 s21, s53, s21
	s_add_u32 s18, s22, 0x8000
	s_addc_u32 s19, s23, 0
	s_add_i32 s11, s29, 0xc000
	s_add_u32 s98, s12, s6
	s_addc_u32 s99, s13, s7
	s_mov_b32 m0, s11
	s_add_i32 s48, s29, 0xe000
	ds_read_b128 v[198:201], v151
	ds_read_b128 v[202:205], v151 offset:1024
	ds_read_b128 v[206:209], v151 offset:2048
	ds_read_b128 v[210:213], v151 offset:3072
	ds_read_b128 v[214:217], v151 offset:4096
	ds_read_b128 v[218:221], v151 offset:5120
	ds_read_b128 v[222:225], v151 offset:6144
	ds_read_b128 v[226:229], v151 offset:7168
	global_load_lds_dwordx4 v8, s[98:99] sc1
	s_mov_b32 m0, s48
	s_nop 0
	global_load_lds_dwordx4 v10, s[98:99] sc1
	s_waitcnt vmcnt(8)
	s_waitcnt lgkmcnt(0)
	s_setprio 1
	s_barrier
	v_mfma_f32_16x16x32_bf16 v[128:131], v[152:155], v[198:201], 0
	v_mfma_f32_16x16x32_bf16 v[132:135], v[164:167], v[198:201], 0
	v_mfma_f32_16x16x32_bf16 v[112:115], v[152:155], v[206:209], 0
	v_mfma_f32_16x16x32_bf16 v[116:119], v[164:167], v[206:209], 0
	v_mfma_f32_16x16x32_bf16 v[96:99], v[152:155], v[214:217], 0
	v_mfma_f32_16x16x32_bf16 v[100:103], v[164:167], v[214:217], 0
	v_mfma_f32_16x16x32_bf16 v[72:75], v[152:155], v[222:225], 0
	v_mfma_f32_16x16x32_bf16 v[76:79], v[164:167], v[222:225], 0
	v_mfma_f32_16x16x32_bf16 v[128:131], v[156:159], v[202:205], v[128:131]
	v_mfma_f32_16x16x32_bf16 v[132:135], v[168:171], v[202:205], v[132:135]
	v_mfma_f32_16x16x32_bf16 v[112:115], v[156:159], v[210:213], v[112:115]
	v_mfma_f32_16x16x32_bf16 v[116:119], v[168:171], v[210:213], v[116:119]
	v_mfma_f32_16x16x32_bf16 v[96:99], v[156:159], v[218:221], v[96:99]
	v_mfma_f32_16x16x32_bf16 v[100:103], v[168:171], v[218:221], v[100:103]
	v_mfma_f32_16x16x32_bf16 v[72:75], v[156:159], v[226:229], v[72:75]
	v_mfma_f32_16x16x32_bf16 v[76:79], v[168:171], v[226:229], v[76:79]
	v_mfma_f32_16x16x32_bf16 v[136:139], v[172:175], v[198:201], 0
	v_mfma_f32_16x16x32_bf16 v[140:143], v[190:193], v[198:201], 0
	v_mfma_f32_16x16x32_bf16 v[120:123], v[172:175], v[206:209], 0
	v_mfma_f32_16x16x32_bf16 v[124:127], v[190:193], v[206:209], 0
	v_mfma_f32_16x16x32_bf16 v[104:107], v[172:175], v[214:217], 0
	v_mfma_f32_16x16x32_bf16 v[108:111], v[190:193], v[214:217], 0
	v_mfma_f32_16x16x32_bf16 v[88:91], v[172:175], v[222:225], 0
	v_mfma_f32_16x16x32_bf16 v[92:95], v[190:193], v[222:225], 0
	v_mfma_f32_16x16x32_bf16 v[136:139], v[182:185], v[202:205], v[136:139]
	v_mfma_f32_16x16x32_bf16 v[140:143], v[194:197], v[202:205], v[140:143]
	v_mfma_f32_16x16x32_bf16 v[120:123], v[182:185], v[210:213], v[120:123]
	v_mfma_f32_16x16x32_bf16 v[124:127], v[194:197], v[210:213], v[124:127]
	v_mfma_f32_16x16x32_bf16 v[104:107], v[182:185], v[218:221], v[104:107]
	v_mfma_f32_16x16x32_bf16 v[108:111], v[194:197], v[218:221], v[108:111]
	s_setprio 2
	s_barrier
	v_mfma_f32_16x16x32_bf16 v[88:91], v[182:185], v[226:229], v[88:91]
	v_mfma_f32_16x16x32_bf16 v[92:95], v[194:197], v[226:229], v[92:95]
	s_setprio 0
	s_add_i32 s56, s40, s27
	s_mov_b32 m0, s56
	ds_read_b128 v[198:201], v151 offset:16384
	ds_read_b128 v[202:205], v151 offset:17408
	ds_read_b128 v[206:209], v151 offset:18432
	ds_read_b128 v[210:213], v151 offset:19456
	ds_read_b128 v[214:217], v151 offset:20480
	ds_read_b128 v[218:221], v151 offset:21504
	ds_read_b128 v[222:225], v151 offset:22528
	ds_read_b128 v[226:229], v151 offset:23552
	global_load_lds_dwordx4 v2, s[20:21] sc1
	s_add_i32 m0, s56, 0x2000
	s_add_u32 s56, s20, 0x4000
	s_addc_u32 s57, s21, 0
	s_add_i32 s58, s41, s27
	global_load_lds_dwordx4 v6, s[20:21] sc1
	s_mov_b32 m0, s58
	s_nop 0
	global_load_lds_dwordx4 v2, s[56:57] sc1
	s_add_i32 m0, s58, 0x2000
	s_nop 0
	global_load_lds_dwordx4 v6, s[56:57] sc1
	s_mov_b32 m0, s29
	s_nop 0
	global_load_lds_dwordx4 v0, s[22:23] sc1
	s_mov_b32 m0, s30
	s_nop 0
	global_load_lds_dwordx4 v4, s[22:23] sc1
	s_waitcnt vmcnt(8)
	s_waitcnt lgkmcnt(0)
	s_setprio 1
	s_barrier
	v_mfma_f32_16x16x32_bf16 v[64:67], v[152:155], v[198:201], 0
	v_mfma_f32_16x16x32_bf16 v[68:71], v[164:167], v[198:201], 0
	v_mfma_f32_16x16x32_bf16 v[48:51], v[152:155], v[206:209], 0
	v_mfma_f32_16x16x32_bf16 v[52:55], v[164:167], v[206:209], 0
	v_mfma_f32_16x16x32_bf16 v[32:35], v[152:155], v[214:217], 0
	v_mfma_f32_16x16x32_bf16 v[36:39], v[164:167], v[214:217], 0
	v_mfma_f32_16x16x32_bf16 v[16:19], v[152:155], v[222:225], 0
	v_mfma_f32_16x16x32_bf16 v[20:23], v[164:167], v[222:225], 0
	v_mfma_f32_16x16x32_bf16 v[64:67], v[156:159], v[202:205], v[64:67]
	v_mfma_f32_16x16x32_bf16 v[68:71], v[168:171], v[202:205], v[68:71]
	v_mfma_f32_16x16x32_bf16 v[48:51], v[156:159], v[210:213], v[48:51]
	v_mfma_f32_16x16x32_bf16 v[52:55], v[168:171], v[210:213], v[52:55]
	v_mfma_f32_16x16x32_bf16 v[32:35], v[156:159], v[218:221], v[32:35]
	v_mfma_f32_16x16x32_bf16 v[36:39], v[168:171], v[218:221], v[36:39]
	v_mfma_f32_16x16x32_bf16 v[16:19], v[156:159], v[226:229], v[16:19]
	v_mfma_f32_16x16x32_bf16 v[20:23], v[168:171], v[226:229], v[20:23]
	v_mfma_f32_16x16x32_bf16 v[80:83], v[172:175], v[198:201], 0
	v_mfma_f32_16x16x32_bf16 v[84:87], v[190:193], v[198:201], 0
	v_mfma_f32_16x16x32_bf16 v[56:59], v[172:175], v[206:209], 0
	v_mfma_f32_16x16x32_bf16 v[60:63], v[190:193], v[206:209], 0
	v_mfma_f32_16x16x32_bf16 v[40:43], v[172:175], v[214:217], 0
	v_mfma_f32_16x16x32_bf16 v[44:47], v[190:193], v[214:217], 0
	v_mfma_f32_16x16x32_bf16 v[24:27], v[172:175], v[222:225], 0
	v_mfma_f32_16x16x32_bf16 v[28:31], v[190:193], v[222:225], 0
	v_mfma_f32_16x16x32_bf16 v[80:83], v[182:185], v[202:205], v[80:83]
	v_mfma_f32_16x16x32_bf16 v[84:87], v[194:197], v[202:205], v[84:87]
	v_mfma_f32_16x16x32_bf16 v[56:59], v[182:185], v[210:213], v[56:59]
	v_mfma_f32_16x16x32_bf16 v[60:63], v[194:197], v[210:213], v[60:63]
	v_mfma_f32_16x16x32_bf16 v[40:43], v[182:185], v[218:221], v[40:43]
	v_mfma_f32_16x16x32_bf16 v[44:47], v[194:197], v[218:221], v[44:47]
	s_setprio 2
	s_barrier
	v_mfma_f32_16x16x32_bf16 v[24:27], v[182:185], v[226:229], v[24:27]
	v_mfma_f32_16x16x32_bf16 v[28:31], v[194:197], v[226:229], v[28:31]
	s_setprio 0
	ds_read_b128 v[152:155], v255 offset:33024
	ds_read_b128 v[156:159], v255 offset:34048
	ds_read_b128 v[164:167], v255 offset:35072
	ds_read_b128 v[168:171], v255 offset:36096
	ds_read_b128 v[172:175], v255 offset:49408
	ds_read_b128 v[182:185], v255 offset:50432
	ds_read_b128 v[190:193], v255 offset:51456
	ds_read_b128 v[194:197], v255 offset:52480
	s_add_u32 s22, s22, 0x4000
	s_addc_u32 s23, s23, 0
	s_mov_b32 m0, s31
	ds_read_b128 v[198:201], v151 offset:32768
	ds_read_b128 v[202:205], v151 offset:33792
	ds_read_b128 v[206:209], v151 offset:34816
	ds_read_b128 v[210:213], v151 offset:35840
	ds_read_b128 v[214:217], v151 offset:36864
	ds_read_b128 v[218:221], v151 offset:37888
	ds_read_b128 v[222:225], v151 offset:38912
	ds_read_b128 v[226:229], v151 offset:39936
	global_load_lds_dwordx4 v0, s[22:23] sc1
	s_mov_b32 m0, s35
	s_nop 0
	global_load_lds_dwordx4 v4, s[22:23] sc1
	s_waitcnt vmcnt(8)
	s_waitcnt lgkmcnt(0)
	s_setprio 1
	s_barrier
	v_mfma_f32_16x16x32_bf16 v[128:131], v[152:155], v[198:201], v[128:131]
	v_mfma_f32_16x16x32_bf16 v[132:135], v[164:167], v[198:201], v[132:135]
	v_mfma_f32_16x16x32_bf16 v[112:115], v[152:155], v[206:209], v[112:115]
	v_mfma_f32_16x16x32_bf16 v[116:119], v[164:167], v[206:209], v[116:119]
	v_mfma_f32_16x16x32_bf16 v[96:99], v[152:155], v[214:217], v[96:99]
	v_mfma_f32_16x16x32_bf16 v[100:103], v[164:167], v[214:217], v[100:103]
	v_mfma_f32_16x16x32_bf16 v[72:75], v[152:155], v[222:225], v[72:75]
	v_mfma_f32_16x16x32_bf16 v[76:79], v[164:167], v[222:225], v[76:79]
	v_mfma_f32_16x16x32_bf16 v[128:131], v[156:159], v[202:205], v[128:131]
	v_mfma_f32_16x16x32_bf16 v[132:135], v[168:171], v[202:205], v[132:135]
	v_mfma_f32_16x16x32_bf16 v[112:115], v[156:159], v[210:213], v[112:115]
	v_mfma_f32_16x16x32_bf16 v[116:119], v[168:171], v[210:213], v[116:119]
	v_mfma_f32_16x16x32_bf16 v[96:99], v[156:159], v[218:221], v[96:99]
	v_mfma_f32_16x16x32_bf16 v[100:103], v[168:171], v[218:221], v[100:103]
	v_mfma_f32_16x16x32_bf16 v[72:75], v[156:159], v[226:229], v[72:75]
	v_mfma_f32_16x16x32_bf16 v[76:79], v[168:171], v[226:229], v[76:79]
	v_mfma_f32_16x16x32_bf16 v[136:139], v[172:175], v[198:201], v[136:139]
	v_mfma_f32_16x16x32_bf16 v[140:143], v[190:193], v[198:201], v[140:143]
	v_mfma_f32_16x16x32_bf16 v[120:123], v[172:175], v[206:209], v[120:123]
	v_mfma_f32_16x16x32_bf16 v[124:127], v[190:193], v[206:209], v[124:127]
	v_mfma_f32_16x16x32_bf16 v[104:107], v[172:175], v[214:217], v[104:107]
	v_mfma_f32_16x16x32_bf16 v[108:111], v[190:193], v[214:217], v[108:111]
	v_mfma_f32_16x16x32_bf16 v[88:91], v[172:175], v[222:225], v[88:91]
	v_mfma_f32_16x16x32_bf16 v[92:95], v[190:193], v[222:225], v[92:95]
	v_mfma_f32_16x16x32_bf16 v[136:139], v[182:185], v[202:205], v[136:139]
	v_mfma_f32_16x16x32_bf16 v[140:143], v[194:197], v[202:205], v[140:143]
	v_mfma_f32_16x16x32_bf16 v[120:123], v[182:185], v[210:213], v[120:123]
	v_mfma_f32_16x16x32_bf16 v[124:127], v[194:197], v[210:213], v[124:127]
	v_mfma_f32_16x16x32_bf16 v[104:107], v[182:185], v[218:221], v[104:107]
	v_mfma_f32_16x16x32_bf16 v[108:111], v[194:197], v[218:221], v[108:111]
	s_setprio 2
	s_barrier
	v_mfma_f32_16x16x32_bf16 v[88:91], v[182:185], v[226:229], v[88:91]
	v_mfma_f32_16x16x32_bf16 v[92:95], v[194:197], v[226:229], v[92:95]
	s_setprio 0
	s_add_u32 s22, s20, 0x8000
	s_addc_u32 s23, s21, 0
	s_add_i32 s56, s43, s27
	s_mov_b32 m0, s56
	ds_read_b128 v[198:201], v151 offset:49152
	ds_read_b128 v[202:205], v151 offset:50176
	ds_read_b128 v[206:209], v151 offset:51200
	ds_read_b128 v[210:213], v151 offset:52224
	ds_read_b128 v[214:217], v151 offset:53248
	ds_read_b128 v[218:221], v151 offset:54272
	ds_read_b128 v[222:225], v151 offset:55296
	ds_read_b128 v[226:229], v151 offset:56320
	global_load_lds_dwordx4 v2, s[22:23] sc1
	s_add_i32 m0, s56, 0x2000
	s_add_u32 s20, s20, 0xc000
	global_load_lds_dwordx4 v6, s[22:23] sc1
	s_addc_u32 s21, s21, 0
	s_add_i32 s22, s44, s27
	s_mov_b32 m0, s22
	s_nop 0
	global_load_lds_dwordx4 v2, s[20:21] sc1
	s_add_i32 m0, s22, 0x2000
	s_nop 0
	global_load_lds_dwordx4 v6, s[20:21] sc1
	s_mov_b32 m0, s38
	s_nop 0
	global_load_lds_dwordx4 v0, s[18:19] sc1
	s_mov_b32 m0, s39
	s_nop 0
	global_load_lds_dwordx4 v4, s[18:19] sc1
	s_waitcnt vmcnt(8)
	s_waitcnt lgkmcnt(0)
	s_setprio 1
	s_barrier
	v_mfma_f32_16x16x32_bf16 v[64:67], v[152:155], v[198:201], v[64:67]
	v_mfma_f32_16x16x32_bf16 v[68:71], v[164:167], v[198:201], v[68:71]
	v_mfma_f32_16x16x32_bf16 v[48:51], v[152:155], v[206:209], v[48:51]
	v_mfma_f32_16x16x32_bf16 v[52:55], v[164:167], v[206:209], v[52:55]
	v_mfma_f32_16x16x32_bf16 v[32:35], v[152:155], v[214:217], v[32:35]
	v_mfma_f32_16x16x32_bf16 v[36:39], v[164:167], v[214:217], v[36:39]
	v_mfma_f32_16x16x32_bf16 v[16:19], v[152:155], v[222:225], v[16:19]
	v_mfma_f32_16x16x32_bf16 v[20:23], v[164:167], v[222:225], v[20:23]
	v_mfma_f32_16x16x32_bf16 v[64:67], v[156:159], v[202:205], v[64:67]
	v_mfma_f32_16x16x32_bf16 v[68:71], v[168:171], v[202:205], v[68:71]
	v_mfma_f32_16x16x32_bf16 v[48:51], v[156:159], v[210:213], v[48:51]
	v_mfma_f32_16x16x32_bf16 v[52:55], v[168:171], v[210:213], v[52:55]
	v_mfma_f32_16x16x32_bf16 v[32:35], v[156:159], v[218:221], v[32:35]
	v_mfma_f32_16x16x32_bf16 v[36:39], v[168:171], v[218:221], v[36:39]
	v_mfma_f32_16x16x32_bf16 v[16:19], v[156:159], v[226:229], v[16:19]
	v_mfma_f32_16x16x32_bf16 v[20:23], v[168:171], v[226:229], v[20:23]
	v_mfma_f32_16x16x32_bf16 v[80:83], v[172:175], v[198:201], v[80:83]
	v_mfma_f32_16x16x32_bf16 v[84:87], v[190:193], v[198:201], v[84:87]
	v_mfma_f32_16x16x32_bf16 v[56:59], v[172:175], v[206:209], v[56:59]
	v_mfma_f32_16x16x32_bf16 v[60:63], v[190:193], v[206:209], v[60:63]
	v_mfma_f32_16x16x32_bf16 v[40:43], v[172:175], v[214:217], v[40:43]
	v_mfma_f32_16x16x32_bf16 v[44:47], v[190:193], v[214:217], v[44:47]
	v_mfma_f32_16x16x32_bf16 v[24:27], v[172:175], v[222:225], v[24:27]
	v_mfma_f32_16x16x32_bf16 v[28:31], v[190:193], v[222:225], v[28:31]
	v_mfma_f32_16x16x32_bf16 v[80:83], v[182:185], v[202:205], v[80:83]
	v_mfma_f32_16x16x32_bf16 v[84:87], v[194:197], v[202:205], v[84:87]
	v_mfma_f32_16x16x32_bf16 v[56:59], v[182:185], v[210:213], v[56:59]
	v_mfma_f32_16x16x32_bf16 v[60:63], v[194:197], v[210:213], v[60:63]
	v_mfma_f32_16x16x32_bf16 v[40:43], v[182:185], v[218:221], v[40:43]
	v_mfma_f32_16x16x32_bf16 v[44:47], v[194:197], v[218:221], v[44:47]
	s_setprio 2
	s_barrier
	v_mfma_f32_16x16x32_bf16 v[24:27], v[182:185], v[226:229], v[24:27]
	v_mfma_f32_16x16x32_bf16 v[28:31], v[194:197], v[226:229], v[28:31]
	s_setprio 0
	s_add_i32 s55, s55, 2
	s_add_u32 s6, s6, 0x10000
	s_addc_u32 s7, s7, 0
	s_cmp_gt_u32 s55, 41
.LBB0_1249:
	s_add_u32 s11, s12, s6
	s_addc_u32 s18, s13, s7
	ds_read_b128 v[152:155], v255 offset:256
	ds_read_b128 v[156:159], v255 offset:1280
	ds_read_b128 v[164:167], v255 offset:2304
	ds_read_b128 v[168:171], v255 offset:3328
	s_add_u32 s11, s11, 0x10000
	ds_read_b128 v[172:175], v255 offset:16640
	ds_read_b128 v[182:185], v255 offset:17664
	ds_read_b128 v[190:193], v255 offset:18688
	ds_read_b128 v[194:197], v255 offset:19712
	s_addc_u32 s18, s18, 0
	s_add_u32 s19, s49, s6
	s_addc_u32 s21, s50, s7
	s_cmp_eq_u32 s6, 0x150000
	s_cselect_b32 s22, s52, s11
	s_cselect_b32 s23, s51, s18
	s_cselect_b32 s20, s54, s19
	s_cselect_b32 s21, s53, s21
	s_add_u32 s18, s22, 0x8000
	s_addc_u32 s19, s23, 0
	s_add_i32 s11, s29, 0xc000
	s_add_u32 s98, s12, s6
	s_addc_u32 s99, s13, s7
	s_mov_b32 m0, s11
	s_add_i32 s48, s29, 0xe000
	ds_read_b128 v[198:201], v151
	ds_read_b128 v[202:205], v151 offset:1024
	ds_read_b128 v[206:209], v151 offset:2048
	ds_read_b128 v[210:213], v151 offset:3072
	ds_read_b128 v[214:217], v151 offset:4096
	ds_read_b128 v[218:221], v151 offset:5120
	ds_read_b128 v[222:225], v151 offset:6144
	ds_read_b128 v[226:229], v151 offset:7168
	global_load_lds_dwordx4 v8, s[98:99] sc1
	s_mov_b32 m0, s48
	s_nop 0
	global_load_lds_dwordx4 v10, s[98:99] sc1
	s_waitcnt vmcnt(8)
	s_waitcnt lgkmcnt(0)
	s_setprio 1
	s_barrier
	v_mfma_f32_16x16x32_bf16 v[128:131], v[152:155], v[198:201], v[128:131]
	v_mfma_f32_16x16x32_bf16 v[132:135], v[164:167], v[198:201], v[132:135]
	v_mfma_f32_16x16x32_bf16 v[112:115], v[152:155], v[206:209], v[112:115]
	v_mfma_f32_16x16x32_bf16 v[116:119], v[164:167], v[206:209], v[116:119]
	v_mfma_f32_16x16x32_bf16 v[96:99], v[152:155], v[214:217], v[96:99]
	v_mfma_f32_16x16x32_bf16 v[100:103], v[164:167], v[214:217], v[100:103]
	v_mfma_f32_16x16x32_bf16 v[72:75], v[152:155], v[222:225], v[72:75]
	v_mfma_f32_16x16x32_bf16 v[76:79], v[164:167], v[222:225], v[76:79]
	v_mfma_f32_16x16x32_bf16 v[128:131], v[156:159], v[202:205], v[128:131]
	v_mfma_f32_16x16x32_bf16 v[132:135], v[168:171], v[202:205], v[132:135]
	v_mfma_f32_16x16x32_bf16 v[112:115], v[156:159], v[210:213], v[112:115]
	v_mfma_f32_16x16x32_bf16 v[116:119], v[168:171], v[210:213], v[116:119]
	v_mfma_f32_16x16x32_bf16 v[96:99], v[156:159], v[218:221], v[96:99]
	v_mfma_f32_16x16x32_bf16 v[100:103], v[168:171], v[218:221], v[100:103]
	v_mfma_f32_16x16x32_bf16 v[72:75], v[156:159], v[226:229], v[72:75]
	v_mfma_f32_16x16x32_bf16 v[76:79], v[168:171], v[226:229], v[76:79]
	v_mfma_f32_16x16x32_bf16 v[136:139], v[172:175], v[198:201], v[136:139]
	v_mfma_f32_16x16x32_bf16 v[140:143], v[190:193], v[198:201], v[140:143]
	v_mfma_f32_16x16x32_bf16 v[120:123], v[172:175], v[206:209], v[120:123]
	v_mfma_f32_16x16x32_bf16 v[124:127], v[190:193], v[206:209], v[124:127]
	v_mfma_f32_16x16x32_bf16 v[104:107], v[172:175], v[214:217], v[104:107]
	v_mfma_f32_16x16x32_bf16 v[108:111], v[190:193], v[214:217], v[108:111]
	v_mfma_f32_16x16x32_bf16 v[88:91], v[172:175], v[222:225], v[88:91]
	v_mfma_f32_16x16x32_bf16 v[92:95], v[190:193], v[222:225], v[92:95]
	v_mfma_f32_16x16x32_bf16 v[136:139], v[182:185], v[202:205], v[136:139]
	v_mfma_f32_16x16x32_bf16 v[140:143], v[194:197], v[202:205], v[140:143]
	v_mfma_f32_16x16x32_bf16 v[120:123], v[182:185], v[210:213], v[120:123]
	v_mfma_f32_16x16x32_bf16 v[124:127], v[194:197], v[210:213], v[124:127]
	v_mfma_f32_16x16x32_bf16 v[104:107], v[182:185], v[218:221], v[104:107]
	v_mfma_f32_16x16x32_bf16 v[108:111], v[194:197], v[218:221], v[108:111]
	s_setprio 2
	s_barrier
	v_mfma_f32_16x16x32_bf16 v[88:91], v[182:185], v[226:229], v[88:91]
	v_mfma_f32_16x16x32_bf16 v[92:95], v[194:197], v[226:229], v[92:95]
	s_setprio 0
	s_add_i32 s56, s40, s27
	s_mov_b32 m0, s56
	ds_read_b128 v[198:201], v151 offset:16384
	ds_read_b128 v[202:205], v151 offset:17408
	ds_read_b128 v[206:209], v151 offset:18432
	ds_read_b128 v[210:213], v151 offset:19456
	ds_read_b128 v[214:217], v151 offset:20480
	ds_read_b128 v[218:221], v151 offset:21504
	ds_read_b128 v[222:225], v151 offset:22528
	ds_read_b128 v[226:229], v151 offset:23552
	global_load_lds_dwordx4 v2, s[20:21] sc1
	s_add_i32 m0, s56, 0x2000
	s_add_u32 s56, s20, 0x4000
	s_addc_u32 s57, s21, 0
	s_add_i32 s58, s41, s27
	global_load_lds_dwordx4 v6, s[20:21] sc1
	s_mov_b32 m0, s58
	s_nop 0
	global_load_lds_dwordx4 v2, s[56:57] sc1
	s_add_i32 m0, s58, 0x2000
	s_nop 0
	global_load_lds_dwordx4 v6, s[56:57] sc1
	s_mov_b32 m0, s29
	s_nop 0
	global_load_lds_dwordx4 v0, s[22:23] sc1
	s_mov_b32 m0, s30
	s_nop 0
	global_load_lds_dwordx4 v4, s[22:23] sc1
	s_waitcnt vmcnt(8)
	s_waitcnt lgkmcnt(0)
	s_setprio 1
	s_barrier
	v_mfma_f32_16x16x32_bf16 v[64:67], v[152:155], v[198:201], v[64:67]
	v_mfma_f32_16x16x32_bf16 v[68:71], v[164:167], v[198:201], v[68:71]
	v_mfma_f32_16x16x32_bf16 v[48:51], v[152:155], v[206:209], v[48:51]
	v_mfma_f32_16x16x32_bf16 v[52:55], v[164:167], v[206:209], v[52:55]
	v_mfma_f32_16x16x32_bf16 v[32:35], v[152:155], v[214:217], v[32:35]
	v_mfma_f32_16x16x32_bf16 v[36:39], v[164:167], v[214:217], v[36:39]
	v_mfma_f32_16x16x32_bf16 v[16:19], v[152:155], v[222:225], v[16:19]
	v_mfma_f32_16x16x32_bf16 v[20:23], v[164:167], v[222:225], v[20:23]
	v_mfma_f32_16x16x32_bf16 v[64:67], v[156:159], v[202:205], v[64:67]
	v_mfma_f32_16x16x32_bf16 v[68:71], v[168:171], v[202:205], v[68:71]
	v_mfma_f32_16x16x32_bf16 v[48:51], v[156:159], v[210:213], v[48:51]
	v_mfma_f32_16x16x32_bf16 v[52:55], v[168:171], v[210:213], v[52:55]
	v_mfma_f32_16x16x32_bf16 v[32:35], v[156:159], v[218:221], v[32:35]
	v_mfma_f32_16x16x32_bf16 v[36:39], v[168:171], v[218:221], v[36:39]
	v_mfma_f32_16x16x32_bf16 v[16:19], v[156:159], v[226:229], v[16:19]
	v_mfma_f32_16x16x32_bf16 v[20:23], v[168:171], v[226:229], v[20:23]
	v_mfma_f32_16x16x32_bf16 v[80:83], v[172:175], v[198:201], v[80:83]
	v_mfma_f32_16x16x32_bf16 v[84:87], v[190:193], v[198:201], v[84:87]
	v_mfma_f32_16x16x32_bf16 v[56:59], v[172:175], v[206:209], v[56:59]
	v_mfma_f32_16x16x32_bf16 v[60:63], v[190:193], v[206:209], v[60:63]
	v_mfma_f32_16x16x32_bf16 v[40:43], v[172:175], v[214:217], v[40:43]
	v_mfma_f32_16x16x32_bf16 v[44:47], v[190:193], v[214:217], v[44:47]
	v_mfma_f32_16x16x32_bf16 v[24:27], v[172:175], v[222:225], v[24:27]
	v_mfma_f32_16x16x32_bf16 v[28:31], v[190:193], v[222:225], v[28:31]
	v_mfma_f32_16x16x32_bf16 v[80:83], v[182:185], v[202:205], v[80:83]
	v_mfma_f32_16x16x32_bf16 v[84:87], v[194:197], v[202:205], v[84:87]
	v_mfma_f32_16x16x32_bf16 v[56:59], v[182:185], v[210:213], v[56:59]
	v_mfma_f32_16x16x32_bf16 v[60:63], v[194:197], v[210:213], v[60:63]
	v_mfma_f32_16x16x32_bf16 v[40:43], v[182:185], v[218:221], v[40:43]
	v_mfma_f32_16x16x32_bf16 v[44:47], v[194:197], v[218:221], v[44:47]
	s_setprio 2
	s_barrier
	v_mfma_f32_16x16x32_bf16 v[24:27], v[182:185], v[226:229], v[24:27]
	v_mfma_f32_16x16x32_bf16 v[28:31], v[194:197], v[226:229], v[28:31]
	s_setprio 0
	ds_read_b128 v[152:155], v255 offset:33024
	ds_read_b128 v[156:159], v255 offset:34048
	ds_read_b128 v[164:167], v255 offset:35072
	ds_read_b128 v[168:171], v255 offset:36096
	ds_read_b128 v[172:175], v255 offset:49408
	ds_read_b128 v[182:185], v255 offset:50432
	ds_read_b128 v[190:193], v255 offset:51456
	ds_read_b128 v[194:197], v255 offset:52480
	s_add_u32 s22, s22, 0x4000
	s_addc_u32 s23, s23, 0
	s_mov_b32 m0, s31
	ds_read_b128 v[198:201], v151 offset:32768
	ds_read_b128 v[202:205], v151 offset:33792
	ds_read_b128 v[206:209], v151 offset:34816
	ds_read_b128 v[210:213], v151 offset:35840
	ds_read_b128 v[214:217], v151 offset:36864
	ds_read_b128 v[218:221], v151 offset:37888
	ds_read_b128 v[222:225], v151 offset:38912
	ds_read_b128 v[226:229], v151 offset:39936
	global_load_lds_dwordx4 v0, s[22:23] sc1
	s_mov_b32 m0, s35
	s_nop 0
	global_load_lds_dwordx4 v4, s[22:23] sc1
	s_waitcnt vmcnt(8)
	s_waitcnt lgkmcnt(0)
	s_setprio 1
	s_barrier
	v_mfma_f32_16x16x32_bf16 v[128:131], v[152:155], v[198:201], v[128:131]
	v_mfma_f32_16x16x32_bf16 v[132:135], v[164:167], v[198:201], v[132:135]
	v_mfma_f32_16x16x32_bf16 v[112:115], v[152:155], v[206:209], v[112:115]
	v_mfma_f32_16x16x32_bf16 v[116:119], v[164:167], v[206:209], v[116:119]
	v_mfma_f32_16x16x32_bf16 v[96:99], v[152:155], v[214:217], v[96:99]
	v_mfma_f32_16x16x32_bf16 v[100:103], v[164:167], v[214:217], v[100:103]
	v_mfma_f32_16x16x32_bf16 v[72:75], v[152:155], v[222:225], v[72:75]
	v_mfma_f32_16x16x32_bf16 v[76:79], v[164:167], v[222:225], v[76:79]
	v_mfma_f32_16x16x32_bf16 v[128:131], v[156:159], v[202:205], v[128:131]
	v_mfma_f32_16x16x32_bf16 v[132:135], v[168:171], v[202:205], v[132:135]
	v_mfma_f32_16x16x32_bf16 v[112:115], v[156:159], v[210:213], v[112:115]
	v_mfma_f32_16x16x32_bf16 v[116:119], v[168:171], v[210:213], v[116:119]
	v_mfma_f32_16x16x32_bf16 v[96:99], v[156:159], v[218:221], v[96:99]
	v_mfma_f32_16x16x32_bf16 v[100:103], v[168:171], v[218:221], v[100:103]
	v_mfma_f32_16x16x32_bf16 v[72:75], v[156:159], v[226:229], v[72:75]
	v_mfma_f32_16x16x32_bf16 v[76:79], v[168:171], v[226:229], v[76:79]
	v_mfma_f32_16x16x32_bf16 v[136:139], v[172:175], v[198:201], v[136:139]
	v_mfma_f32_16x16x32_bf16 v[140:143], v[190:193], v[198:201], v[140:143]
	v_mfma_f32_16x16x32_bf16 v[120:123], v[172:175], v[206:209], v[120:123]
	v_mfma_f32_16x16x32_bf16 v[124:127], v[190:193], v[206:209], v[124:127]
	v_mfma_f32_16x16x32_bf16 v[104:107], v[172:175], v[214:217], v[104:107]
	v_mfma_f32_16x16x32_bf16 v[108:111], v[190:193], v[214:217], v[108:111]
	v_mfma_f32_16x16x32_bf16 v[88:91], v[172:175], v[222:225], v[88:91]
	v_mfma_f32_16x16x32_bf16 v[92:95], v[190:193], v[222:225], v[92:95]
	v_mfma_f32_16x16x32_bf16 v[136:139], v[182:185], v[202:205], v[136:139]
	v_mfma_f32_16x16x32_bf16 v[140:143], v[194:197], v[202:205], v[140:143]
	v_mfma_f32_16x16x32_bf16 v[120:123], v[182:185], v[210:213], v[120:123]
	v_mfma_f32_16x16x32_bf16 v[124:127], v[194:197], v[210:213], v[124:127]
	v_mfma_f32_16x16x32_bf16 v[104:107], v[182:185], v[218:221], v[104:107]
	v_mfma_f32_16x16x32_bf16 v[108:111], v[194:197], v[218:221], v[108:111]
	s_setprio 2
	s_barrier
	v_mfma_f32_16x16x32_bf16 v[88:91], v[182:185], v[226:229], v[88:91]
	v_mfma_f32_16x16x32_bf16 v[92:95], v[194:197], v[226:229], v[92:95]
	s_setprio 0
	s_add_u32 s22, s20, 0x8000
	s_addc_u32 s23, s21, 0
	s_add_i32 s56, s43, s27
	s_mov_b32 m0, s56
	ds_read_b128 v[198:201], v151 offset:49152
	ds_read_b128 v[202:205], v151 offset:50176
	ds_read_b128 v[206:209], v151 offset:51200
	ds_read_b128 v[210:213], v151 offset:52224
	ds_read_b128 v[214:217], v151 offset:53248
	ds_read_b128 v[218:221], v151 offset:54272
	ds_read_b128 v[222:225], v151 offset:55296
	ds_read_b128 v[226:229], v151 offset:56320
	global_load_lds_dwordx4 v2, s[22:23] sc1
	s_add_i32 m0, s56, 0x2000
	s_add_u32 s20, s20, 0xc000
	global_load_lds_dwordx4 v6, s[22:23] sc1
	s_addc_u32 s21, s21, 0
	s_add_i32 s22, s44, s27
	s_mov_b32 m0, s22
	s_nop 0
	global_load_lds_dwordx4 v2, s[20:21] sc1
	s_add_i32 m0, s22, 0x2000
	s_nop 0
	global_load_lds_dwordx4 v6, s[20:21] sc1
	s_mov_b32 m0, s38
	s_nop 0
	global_load_lds_dwordx4 v0, s[18:19] sc1
	s_mov_b32 m0, s39
	s_nop 0
	global_load_lds_dwordx4 v4, s[18:19] sc1
	s_waitcnt vmcnt(8)
	s_waitcnt lgkmcnt(0)
	s_setprio 1
	s_barrier
	v_mfma_f32_16x16x32_bf16 v[64:67], v[152:155], v[198:201], v[64:67]
	v_mfma_f32_16x16x32_bf16 v[68:71], v[164:167], v[198:201], v[68:71]
	v_mfma_f32_16x16x32_bf16 v[48:51], v[152:155], v[206:209], v[48:51]
	v_mfma_f32_16x16x32_bf16 v[52:55], v[164:167], v[206:209], v[52:55]
	v_mfma_f32_16x16x32_bf16 v[32:35], v[152:155], v[214:217], v[32:35]
	v_mfma_f32_16x16x32_bf16 v[36:39], v[164:167], v[214:217], v[36:39]
	v_mfma_f32_16x16x32_bf16 v[16:19], v[152:155], v[222:225], v[16:19]
	v_mfma_f32_16x16x32_bf16 v[20:23], v[164:167], v[222:225], v[20:23]
	v_mfma_f32_16x16x32_bf16 v[64:67], v[156:159], v[202:205], v[64:67]
	v_mfma_f32_16x16x32_bf16 v[68:71], v[168:171], v[202:205], v[68:71]
	v_mfma_f32_16x16x32_bf16 v[48:51], v[156:159], v[210:213], v[48:51]
	v_mfma_f32_16x16x32_bf16 v[52:55], v[168:171], v[210:213], v[52:55]
	v_mfma_f32_16x16x32_bf16 v[32:35], v[156:159], v[218:221], v[32:35]
	v_mfma_f32_16x16x32_bf16 v[36:39], v[168:171], v[218:221], v[36:39]
	v_mfma_f32_16x16x32_bf16 v[16:19], v[156:159], v[226:229], v[16:19]
	v_mfma_f32_16x16x32_bf16 v[20:23], v[168:171], v[226:229], v[20:23]
	v_mfma_f32_16x16x32_bf16 v[80:83], v[172:175], v[198:201], v[80:83]
	v_mfma_f32_16x16x32_bf16 v[84:87], v[190:193], v[198:201], v[84:87]
	v_mfma_f32_16x16x32_bf16 v[56:59], v[172:175], v[206:209], v[56:59]
	v_mfma_f32_16x16x32_bf16 v[60:63], v[190:193], v[206:209], v[60:63]
	v_mfma_f32_16x16x32_bf16 v[40:43], v[172:175], v[214:217], v[40:43]
	v_mfma_f32_16x16x32_bf16 v[44:47], v[190:193], v[214:217], v[44:47]
	v_mfma_f32_16x16x32_bf16 v[24:27], v[172:175], v[222:225], v[24:27]
	v_mfma_f32_16x16x32_bf16 v[28:31], v[190:193], v[222:225], v[28:31]
	v_mfma_f32_16x16x32_bf16 v[80:83], v[182:185], v[202:205], v[80:83]
	v_mfma_f32_16x16x32_bf16 v[84:87], v[194:197], v[202:205], v[84:87]
	v_mfma_f32_16x16x32_bf16 v[56:59], v[182:185], v[210:213], v[56:59]
	v_mfma_f32_16x16x32_bf16 v[60:63], v[194:197], v[210:213], v[60:63]
	v_mfma_f32_16x16x32_bf16 v[40:43], v[182:185], v[218:221], v[40:43]
	v_mfma_f32_16x16x32_bf16 v[44:47], v[194:197], v[218:221], v[44:47]
	s_setprio 2
	s_barrier
	v_mfma_f32_16x16x32_bf16 v[24:27], v[182:185], v[226:229], v[24:27]
	v_mfma_f32_16x16x32_bf16 v[28:31], v[194:197], v[226:229], v[28:31]
	s_setprio 0
	s_add_i32 s55, s55, 2
	s_add_u32 s6, s6, 0x10000
	s_addc_u32 s7, s7, 0
	s_cmp_gt_u32 s55, 41
	s_cbranch_scc0 .LBB0_1249
	s_add_u32 s6, s49, 0xffff0000
	s_addc_u32 s7, s50, -1
	s_and_b64 vcc, exec, s[4:5]
	s_cbranch_vccnz .LBB0_1236
	s_mov_b32 s8, s45
	s_mov_b32 s10, s46
	s_mov_b64 s[12:13], s[16:17]
	s_mov_b32 s42, s47
	s_andn2_b64 vcc, exec, s[0:1]
	s_cbranch_vccnz .LBB0_1237

	.amdhsa_kernel _Z14fwd_megakernel6Params
		.amdhsa_group_segment_fixed_size 256
		.amdhsa_private_segment_fixed_size 0
		.amdhsa_kernarg_size 440
		.amdhsa_user_sgpr_count 2
		.amdhsa_user_sgpr_dispatch_ptr 0
		.amdhsa_user_sgpr_queue_ptr 0
		.amdhsa_user_sgpr_kernarg_segment_ptr 1
		.amdhsa_user_sgpr_dispatch_id 0
		.amdhsa_user_sgpr_kernarg_preload_length 0
		.amdhsa_user_sgpr_kernarg_preload_offset 0
		.amdhsa_user_sgpr_private_segment_size 0
		.amdhsa_uses_dynamic_stack 0
		.amdhsa_enable_private_segment 0
		.amdhsa_system_sgpr_workgroup_id_x 1
		.amdhsa_system_sgpr_workgroup_id_y 0
		.amdhsa_system_sgpr_workgroup_id_z 0
		.amdhsa_system_sgpr_workgroup_info 0
		.amdhsa_system_vgpr_workitem_id 2
		.amdhsa_next_free_vgpr 256
		.amdhsa_next_free_sgpr 102
		.amdhsa_accum_offset 256
		.amdhsa_reserve_vcc 1
		.amdhsa_float_round_mode_32 0
		.amdhsa_float_round_mode_16_64 0
		.amdhsa_float_denorm_mode_32 3
		.amdhsa_float_denorm_mode_16_64 3
		.amdhsa_dx10_clamp 1
		.amdhsa_ieee_mode 1
		.amdhsa_fp16_overflow 0
		.amdhsa_tg_split 0
		.amdhsa_exception_fp_ieee_invalid_op 0
		.amdhsa_exception_fp_denorm_src 0
		.amdhsa_exception_fp_ieee_div_zero 0
		.amdhsa_exception_fp_ieee_overflow 0
		.amdhsa_exception_fp_ieee_underflow 0
		.amdhsa_exception_fp_ieee_inexact 0
		.amdhsa_exception_int_div_zero 0
	.end_amdhsa_kernel

amdhsa.kernels:
  - .agpr_count:     0
    .args:
      - .offset:         0
        .size:           184
        .value_kind:     by_value
      - .offset:         184
        .size:           4
        .value_kind:     hidden_block_count_x
      - .offset:         188
        .size:           4
        .value_kind:     hidden_block_count_y
      - .offset:         192
        .size:           4
        .value_kind:     hidden_block_count_z
      - .offset:         196
        .size:           2
        .value_kind:     hidden_group_size_x
      - .offset:         198
        .size:           2
        .value_kind:     hidden_group_size_y
      - .offset:         200
        .size:           2
        .value_kind:     hidden_group_size_z
      - .offset:         202
        .size:           2
        .value_kind:     hidden_remainder_x
      - .offset:         204
        .size:           2
        .value_kind:     hidden_remainder_y
      - .offset:         206
        .size:           2
        .value_kind:     hidden_remainder_z
      - .offset:         224
        .size:           8
        .value_kind:     hidden_global_offset_x
      - .offset:         232
        .size:           8
        .value_kind:     hidden_global_offset_y
      - .offset:         240
        .size:           8
        .value_kind:     hidden_global_offset_z
      - .offset:         248
        .size:           2
        .value_kind:     hidden_grid_dims
      - .offset:         304
        .size:           4
        .value_kind:     hidden_dynamic_lds_size
    .group_segment_fixed_size: 256
    .kernarg_segment_align: 8
    .kernarg_segment_size: 440
    .language:       OpenCL C
    .language_version:
      - 2
      - 0
    .max_flat_workgroup_size: 512
    .name:           _Z14fwd_megakernel6Params
    .private_segment_fixed_size: 0
    .sgpr_count:     108
    .sgpr_spill_count: 143
    .symbol:         _Z14fwd_megakernel6Params.kd
    .uniform_work_group_size: 1
    .uses_dynamic_stack: false
    .vgpr_count:     256
    .vgpr_spill_count: 0
    .wavefront_size: 64
